# combined: full-line stores + single zeroing + saddr gate loads + pipelined second gate batch + G1 state address behind branch + loop-edge SALU in MFMA shadow + peeled first K iteration with srcC=0
# speedup vs baseline: 1.0036x; 1.0036x over previous
.Lkz_0:
	s_and_b64 s[0:1], s[38:39], exec
	s_cselect_b32 s0, s29, s41
	s_cselect_b32 s1, s28, s40
	s_cselect_b32 s5, s31, s3
	s_cselect_b32 s7, s30, s2
	s_add_u32 s14, s40, 0x100
	s_addc_u32 s15, s41, 0
	s_add_u32 s25, s2, 0x100
	s_addc_u32 s27, s3, 0
	s_mov_b32 s2, 0
	v_add_u32_e32 v168, 0x10000, v162
	v_add_u32_e32 v184, 0x14000, v162
	ds_read_b128 v[150:153], v168
	ds_read_b128 v[154:157], v168 offset:1024
	ds_read_b128 v[164:167], v168 offset:2048
	ds_read_b128 v[168:171], v168 offset:3072
	ds_read_b128 v[172:175], v184
	ds_read_b128 v[176:179], v184 offset:1024
	ds_read_b128 v[180:183], v184 offset:2048
	ds_read_b128 v[184:187], v184 offset:3072
	s_add_i32 s33, s2, 2
	s_cmp_eq_u32 s72, s2
	s_cselect_b32 s42, s1, s14
	s_cselect_b32 s43, s0, s15
	s_cselect_b32 s40, s7, s25
	s_cselect_b32 s41, s5, s27
	s_add_u32 s2, s42, 0x80
	s_addc_u32 s3, s43, 0
	ds_read_b128 v[188:191], v163
	ds_read_b128 v[192:195], v163 offset:1024
	ds_read_b128 v[206:209], v163 offset:2048
	ds_read_b128 v[210:213], v163 offset:3072
	ds_read_b128 v[214:217], v163 offset:4096
	ds_read_b128 v[226:229], v163 offset:5120
	ds_read_b128 v[230:233], v163 offset:6144
	ds_read_b128 v[234:237], v163 offset:7168
	s_add_u32 s34, s14, 0x7ff80
	s_addc_u32 s35, s15, 0
	s_mov_b32 m0, s73
	s_nop 0
	global_load_lds_dwordx4 v149, s[34:35]
	s_mov_b32 m0, s75
	s_nop 0
	global_load_lds_dwordx4 v159, s[34:35]
	s_waitcnt vmcnt(8)
	s_waitcnt lgkmcnt(0)
	s_barrier
	s_setprio 1
	s_waitcnt lgkmcnt(7)
	v_mfma_f32_16x16x32_bf16 v[128:131], v[150:153], v[188:191], 0
	v_mfma_f32_16x16x32_bf16 v[124:127], v[164:167], v[188:191], 0
	s_waitcnt lgkmcnt(5)
	v_mfma_f32_16x16x32_bf16 v[112:115], v[150:153], v[206:209], 0
	v_mfma_f32_16x16x32_bf16 v[108:111], v[164:167], v[206:209], 0
	s_waitcnt lgkmcnt(3)
	v_mfma_f32_16x16x32_bf16 v[96:99], v[150:153], v[214:217], 0
	v_mfma_f32_16x16x32_bf16 v[92:95], v[164:167], v[214:217], 0
	s_waitcnt lgkmcnt(1)
	v_mfma_f32_16x16x32_bf16 v[80:83], v[150:153], v[230:233], 0
	v_mfma_f32_16x16x32_bf16 v[76:79], v[164:167], v[230:233], 0
	v_mfma_f32_16x16x32_bf16 v[128:131], v[154:157], v[192:195], v[128:131]
	v_mfma_f32_16x16x32_bf16 v[124:127], v[168:171], v[192:195], v[124:127]
	v_mfma_f32_16x16x32_bf16 v[112:115], v[154:157], v[210:213], v[112:115]
	v_mfma_f32_16x16x32_bf16 v[108:111], v[168:171], v[210:213], v[108:111]
	v_mfma_f32_16x16x32_bf16 v[96:99], v[154:157], v[226:229], v[96:99]
	v_mfma_f32_16x16x32_bf16 v[92:95], v[168:171], v[226:229], v[92:95]
	s_waitcnt lgkmcnt(0)
	v_mfma_f32_16x16x32_bf16 v[80:83], v[154:157], v[234:237], v[80:83]
	v_mfma_f32_16x16x32_bf16 v[76:79], v[168:171], v[234:237], v[76:79]
	s_setprio 0
	s_setprio 1
	v_mfma_f32_16x16x32_bf16 v[120:123], v[172:175], v[188:191], 0
	v_mfma_f32_16x16x32_bf16 v[116:119], v[180:183], v[188:191], 0
	v_mfma_f32_16x16x32_bf16 v[104:107], v[172:175], v[206:209], 0
	v_mfma_f32_16x16x32_bf16 v[100:103], v[180:183], v[206:209], 0
	v_mfma_f32_16x16x32_bf16 v[88:91], v[172:175], v[214:217], 0
	v_mfma_f32_16x16x32_bf16 v[84:87], v[180:183], v[214:217], 0
	v_mfma_f32_16x16x32_bf16 v[72:75], v[172:175], v[230:233], 0
	v_mfma_f32_16x16x32_bf16 v[68:71], v[180:183], v[230:233], 0
	v_mfma_f32_16x16x32_bf16 v[120:123], v[176:179], v[192:195], v[120:123]
	v_mfma_f32_16x16x32_bf16 v[116:119], v[184:187], v[192:195], v[116:119]
	v_mfma_f32_16x16x32_bf16 v[104:107], v[176:179], v[210:213], v[104:107]
	v_mfma_f32_16x16x32_bf16 v[100:103], v[184:187], v[210:213], v[100:103]
	v_mfma_f32_16x16x32_bf16 v[88:91], v[176:179], v[226:229], v[88:91]
	v_mfma_f32_16x16x32_bf16 v[84:87], v[184:187], v[226:229], v[84:87]
	v_mfma_f32_16x16x32_bf16 v[72:75], v[176:179], v[234:237], v[72:75]
	v_mfma_f32_16x16x32_bf16 v[68:71], v[184:187], v[234:237], v[68:71]
	s_setprio 0
	s_barrier
	ds_read_b128 v[188:191], v163 offset:16384
	ds_read_b128 v[192:195], v163 offset:17408
	ds_read_b128 v[206:209], v163 offset:18432
	ds_read_b128 v[210:213], v163 offset:19456
	ds_read_b128 v[214:217], v163 offset:20480
	ds_read_b128 v[226:229], v163 offset:21504
	ds_read_b128 v[230:233], v163 offset:22528
	ds_read_b128 v[234:237], v163 offset:23552
	s_mov_b32 m0, s55
	s_nop 0
	global_load_lds_dwordx4 v158, s[40:41]
	s_mov_b32 m0, s56
	s_nop 0
	global_load_lds_dwordx4 v160, s[40:41]
	s_add_u32 s34, s40, 0x80000
	s_addc_u32 s35, s41, 0
	s_mov_b32 m0, s57
	s_nop 0
	global_load_lds_dwordx4 v158, s[34:35]
	s_mov_b32 m0, s58
	s_nop 0
	global_load_lds_dwordx4 v160, s[34:35]
	s_mov_b32 m0, s54
	s_nop 0
	global_load_lds_dwordx4 v149, s[42:43]
	s_mov_b32 m0, s59
	s_nop 0
	global_load_lds_dwordx4 v159, s[42:43]
	s_waitcnt vmcnt(8)
	s_waitcnt lgkmcnt(0)
	s_barrier
	s_setprio 1
	s_waitcnt lgkmcnt(7)
	v_mfma_f32_16x16x32_bf16 v[64:67], v[150:153], v[188:191], 0
	v_mfma_f32_16x16x32_bf16 v[60:63], v[164:167], v[188:191], 0
	s_waitcnt lgkmcnt(5)
	v_mfma_f32_16x16x32_bf16 v[48:51], v[150:153], v[206:209], 0
	v_mfma_f32_16x16x32_bf16 v[44:47], v[164:167], v[206:209], 0
	s_waitcnt lgkmcnt(3)
	v_mfma_f32_16x16x32_bf16 v[32:35], v[150:153], v[214:217], 0
	v_mfma_f32_16x16x32_bf16 v[28:31], v[164:167], v[214:217], 0
	s_waitcnt lgkmcnt(1)
	v_mfma_f32_16x16x32_bf16 v[16:19], v[150:153], v[230:233], 0
	v_mfma_f32_16x16x32_bf16 v[12:15], v[164:167], v[230:233], 0
	v_mfma_f32_16x16x32_bf16 v[64:67], v[154:157], v[192:195], v[64:67]
	v_mfma_f32_16x16x32_bf16 v[60:63], v[168:171], v[192:195], v[60:63]
	v_mfma_f32_16x16x32_bf16 v[48:51], v[154:157], v[210:213], v[48:51]
	v_mfma_f32_16x16x32_bf16 v[44:47], v[168:171], v[210:213], v[44:47]
	v_mfma_f32_16x16x32_bf16 v[32:35], v[154:157], v[226:229], v[32:35]
	v_mfma_f32_16x16x32_bf16 v[28:31], v[168:171], v[226:229], v[28:31]
	s_waitcnt lgkmcnt(0)
	v_mfma_f32_16x16x32_bf16 v[16:19], v[154:157], v[234:237], v[16:19]
	v_mfma_f32_16x16x32_bf16 v[12:15], v[168:171], v[234:237], v[12:15]
	s_setprio 0
	s_setprio 1
	v_mfma_f32_16x16x32_bf16 v[56:59], v[172:175], v[188:191], 0
	v_mfma_f32_16x16x32_bf16 v[52:55], v[180:183], v[188:191], 0
	v_mfma_f32_16x16x32_bf16 v[40:43], v[172:175], v[206:209], 0
	v_mfma_f32_16x16x32_bf16 v[36:39], v[180:183], v[206:209], 0
	v_mfma_f32_16x16x32_bf16 v[24:27], v[172:175], v[214:217], 0
	v_mfma_f32_16x16x32_bf16 v[20:23], v[180:183], v[214:217], 0
	v_mfma_f32_16x16x32_bf16 v[8:11], v[172:175], v[230:233], 0
	v_mfma_f32_16x16x32_bf16 v[4:7], v[180:183], v[230:233], 0
	v_mfma_f32_16x16x32_bf16 v[56:59], v[176:179], v[192:195], v[56:59]
	v_mfma_f32_16x16x32_bf16 v[52:55], v[184:187], v[192:195], v[52:55]
	v_mfma_f32_16x16x32_bf16 v[40:43], v[176:179], v[210:213], v[40:43]
	v_mfma_f32_16x16x32_bf16 v[36:39], v[184:187], v[210:213], v[36:39]
	v_mfma_f32_16x16x32_bf16 v[24:27], v[176:179], v[226:229], v[24:27]
	v_mfma_f32_16x16x32_bf16 v[20:23], v[184:187], v[226:229], v[20:23]
	v_mfma_f32_16x16x32_bf16 v[8:11], v[176:179], v[234:237], v[8:11]
	v_mfma_f32_16x16x32_bf16 v[4:7], v[184:187], v[234:237], v[4:7]
	s_setprio 0
	s_barrier
	v_add_u32_e32 v168, 0x18000, v162
	v_add_u32_e32 v184, 0x1c000, v162
	ds_read_b128 v[150:153], v168
	ds_read_b128 v[154:157], v168 offset:1024
	ds_read_b128 v[164:167], v168 offset:2048
	ds_read_b128 v[168:171], v168 offset:3072
	ds_read_b128 v[172:175], v184
	ds_read_b128 v[176:179], v184 offset:1024
	ds_read_b128 v[180:183], v184 offset:2048
	ds_read_b128 v[184:187], v184 offset:3072
	ds_read_b128 v[188:191], v163 offset:32768
	ds_read_b128 v[192:195], v163 offset:33792
	ds_read_b128 v[206:209], v163 offset:34816
	ds_read_b128 v[210:213], v163 offset:35840
	ds_read_b128 v[214:217], v163 offset:36864
	ds_read_b128 v[226:229], v163 offset:37888
	ds_read_b128 v[230:233], v163 offset:38912
	ds_read_b128 v[234:237], v163 offset:39936
	s_add_u32 s34, s42, 0x80000
	s_addc_u32 s35, s43, 0
	s_mov_b32 m0, s60
	s_nop 0
	global_load_lds_dwordx4 v149, s[34:35]
	s_mov_b32 m0, s61
	s_nop 0
	global_load_lds_dwordx4 v159, s[34:35]
	s_waitcnt vmcnt(8)
	s_waitcnt lgkmcnt(0)
	s_barrier
	s_setprio 1
	s_waitcnt lgkmcnt(7)
	v_mfma_f32_16x16x32_bf16 v[128:131], v[150:153], v[188:191], v[128:131]
	v_mfma_f32_16x16x32_bf16 v[124:127], v[164:167], v[188:191], v[124:127]
	s_waitcnt lgkmcnt(5)
	v_mfma_f32_16x16x32_bf16 v[112:115], v[150:153], v[206:209], v[112:115]
	v_mfma_f32_16x16x32_bf16 v[108:111], v[164:167], v[206:209], v[108:111]
	s_waitcnt lgkmcnt(3)
	v_mfma_f32_16x16x32_bf16 v[96:99], v[150:153], v[214:217], v[96:99]
	v_mfma_f32_16x16x32_bf16 v[92:95], v[164:167], v[214:217], v[92:95]
	s_waitcnt lgkmcnt(1)
	v_mfma_f32_16x16x32_bf16 v[80:83], v[150:153], v[230:233], v[80:83]
	v_mfma_f32_16x16x32_bf16 v[76:79], v[164:167], v[230:233], v[76:79]
	v_mfma_f32_16x16x32_bf16 v[128:131], v[154:157], v[192:195], v[128:131]
	v_mfma_f32_16x16x32_bf16 v[124:127], v[168:171], v[192:195], v[124:127]
	v_mfma_f32_16x16x32_bf16 v[112:115], v[154:157], v[210:213], v[112:115]
	v_mfma_f32_16x16x32_bf16 v[108:111], v[168:171], v[210:213], v[108:111]
	v_mfma_f32_16x16x32_bf16 v[96:99], v[154:157], v[226:229], v[96:99]
	v_mfma_f32_16x16x32_bf16 v[92:95], v[168:171], v[226:229], v[92:95]
	s_waitcnt lgkmcnt(0)
	v_mfma_f32_16x16x32_bf16 v[80:83], v[154:157], v[234:237], v[80:83]
	v_mfma_f32_16x16x32_bf16 v[76:79], v[168:171], v[234:237], v[76:79]
	s_setprio 0
	s_setprio 1
	v_mfma_f32_16x16x32_bf16 v[120:123], v[172:175], v[188:191], v[120:123]
	v_mfma_f32_16x16x32_bf16 v[116:119], v[180:183], v[188:191], v[116:119]
	v_mfma_f32_16x16x32_bf16 v[104:107], v[172:175], v[206:209], v[104:107]
	v_mfma_f32_16x16x32_bf16 v[100:103], v[180:183], v[206:209], v[100:103]
	v_mfma_f32_16x16x32_bf16 v[88:91], v[172:175], v[214:217], v[88:91]
	v_mfma_f32_16x16x32_bf16 v[84:87], v[180:183], v[214:217], v[84:87]
	v_mfma_f32_16x16x32_bf16 v[72:75], v[172:175], v[230:233], v[72:75]
	v_mfma_f32_16x16x32_bf16 v[68:71], v[180:183], v[230:233], v[68:71]
	v_mfma_f32_16x16x32_bf16 v[120:123], v[176:179], v[192:195], v[120:123]
	v_mfma_f32_16x16x32_bf16 v[116:119], v[184:187], v[192:195], v[116:119]
	v_mfma_f32_16x16x32_bf16 v[104:107], v[176:179], v[210:213], v[104:107]
	v_mfma_f32_16x16x32_bf16 v[100:103], v[184:187], v[210:213], v[100:103]
	v_mfma_f32_16x16x32_bf16 v[88:91], v[176:179], v[226:229], v[88:91]
	v_mfma_f32_16x16x32_bf16 v[84:87], v[184:187], v[226:229], v[84:87]
	v_mfma_f32_16x16x32_bf16 v[72:75], v[176:179], v[234:237], v[72:75]
	v_mfma_f32_16x16x32_bf16 v[68:71], v[184:187], v[234:237], v[68:71]
	s_setprio 0
	s_barrier
	ds_read_b128 v[188:191], v163 offset:49152
	ds_read_b128 v[192:195], v163 offset:50176
	ds_read_b128 v[206:209], v163 offset:51200
	ds_read_b128 v[210:213], v163 offset:52224
	ds_read_b128 v[214:217], v163 offset:53248
	ds_read_b128 v[226:229], v163 offset:54272
	ds_read_b128 v[230:233], v163 offset:55296
	ds_read_b128 v[234:237], v163 offset:56320
	s_add_u32 s34, s40, 0x80
	s_addc_u32 s35, s41, 0
	s_mov_b32 m0, s66
	s_nop 0
	global_load_lds_dwordx4 v158, s[34:35]
	s_mov_b32 m0, s67
	s_nop 0
	global_load_lds_dwordx4 v160, s[34:35]
	s_add_u32 s34, s40, 0x80080
	s_addc_u32 s35, s41, 0
	s_mov_b32 m0, s70
	s_nop 0
	global_load_lds_dwordx4 v158, s[34:35]
	s_mov_b32 m0, s71
	s_nop 0
	global_load_lds_dwordx4 v160, s[34:35]
	s_mov_b32 m0, s68
	s_nop 0
	global_load_lds_dwordx4 v149, s[2:3]
	s_mov_b32 m0, s69
	s_nop 0
	global_load_lds_dwordx4 v159, s[2:3]
	s_waitcnt vmcnt(8)
	s_waitcnt lgkmcnt(0)
	s_barrier
	s_setprio 1
	s_waitcnt lgkmcnt(7)
	v_mfma_f32_16x16x32_bf16 v[64:67], v[150:153], v[188:191], v[64:67]
	v_mfma_f32_16x16x32_bf16 v[60:63], v[164:167], v[188:191], v[60:63]
	s_add_u32 s14, s14, 0x100
	s_waitcnt lgkmcnt(5)
	v_mfma_f32_16x16x32_bf16 v[48:51], v[150:153], v[206:209], v[48:51]
	s_addc_u32 s15, s15, 0
	v_mfma_f32_16x16x32_bf16 v[44:47], v[164:167], v[206:209], v[44:47]
	s_add_u32 s25, s25, 0x100
	s_waitcnt lgkmcnt(3)
	v_mfma_f32_16x16x32_bf16 v[32:35], v[150:153], v[214:217], v[32:35]
	s_addc_u32 s27, s27, 0
	v_mfma_f32_16x16x32_bf16 v[28:31], v[164:167], v[214:217], v[28:31]
	s_mov_b32 s2, s33
	s_waitcnt lgkmcnt(1)
	v_mfma_f32_16x16x32_bf16 v[16:19], v[150:153], v[230:233], v[16:19]
	s_cmp_ge_i32 s33, s65
	v_mfma_f32_16x16x32_bf16 v[12:15], v[164:167], v[230:233], v[12:15]
	v_mfma_f32_16x16x32_bf16 v[64:67], v[154:157], v[192:195], v[64:67]
	v_mfma_f32_16x16x32_bf16 v[60:63], v[168:171], v[192:195], v[60:63]
	v_mfma_f32_16x16x32_bf16 v[48:51], v[154:157], v[210:213], v[48:51]
	v_mfma_f32_16x16x32_bf16 v[44:47], v[168:171], v[210:213], v[44:47]
	v_mfma_f32_16x16x32_bf16 v[32:35], v[154:157], v[226:229], v[32:35]
	v_mfma_f32_16x16x32_bf16 v[28:31], v[168:171], v[226:229], v[28:31]
	s_waitcnt lgkmcnt(0)
	v_mfma_f32_16x16x32_bf16 v[16:19], v[154:157], v[234:237], v[16:19]
	v_mfma_f32_16x16x32_bf16 v[12:15], v[168:171], v[234:237], v[12:15]
	s_setprio 0
	s_setprio 1
	v_mfma_f32_16x16x32_bf16 v[56:59], v[172:175], v[188:191], v[56:59]
	v_mfma_f32_16x16x32_bf16 v[52:55], v[180:183], v[188:191], v[52:55]
	v_mfma_f32_16x16x32_bf16 v[40:43], v[172:175], v[206:209], v[40:43]
	v_mfma_f32_16x16x32_bf16 v[36:39], v[180:183], v[206:209], v[36:39]
	v_mfma_f32_16x16x32_bf16 v[24:27], v[172:175], v[214:217], v[24:27]
	v_mfma_f32_16x16x32_bf16 v[20:23], v[180:183], v[214:217], v[20:23]
	v_mfma_f32_16x16x32_bf16 v[8:11], v[172:175], v[230:233], v[8:11]
	v_mfma_f32_16x16x32_bf16 v[4:7], v[180:183], v[230:233], v[4:7]
	v_mfma_f32_16x16x32_bf16 v[56:59], v[176:179], v[192:195], v[56:59]
	v_mfma_f32_16x16x32_bf16 v[52:55], v[184:187], v[192:195], v[52:55]
	v_mfma_f32_16x16x32_bf16 v[40:43], v[176:179], v[210:213], v[40:43]
	v_mfma_f32_16x16x32_bf16 v[36:39], v[184:187], v[210:213], v[36:39]
	v_mfma_f32_16x16x32_bf16 v[24:27], v[176:179], v[226:229], v[24:27]
	v_mfma_f32_16x16x32_bf16 v[20:23], v[184:187], v[226:229], v[20:23]
	v_mfma_f32_16x16x32_bf16 v[8:11], v[176:179], v[234:237], v[8:11]
	v_mfma_f32_16x16x32_bf16 v[4:7], v[184:187], v[234:237], v[4:7]
	s_setprio 0
	s_barrier
	s_cbranch_scc0 .LBB0_317
	s_branch .LBB0_318

.Lkz_1:
	s_and_b64 s[48:49], s[4:5], exec
	s_cselect_b32 s27, s31, s43
	s_cselect_b32 s29, s30, s42
	s_cselect_b32 s73, s39, s41
	s_cselect_b32 s74, s38, s40
	s_add_u32 s75, s42, 0x100
	s_addc_u32 s76, s43, 0
	s_add_u32 s77, s40, 0x100
	s_addc_u32 s78, s41, 0
	s_add_u32 s40, s42, 0x20080
	s_addc_u32 s41, s43, 0
	s_mov_b32 s42, 0
	v_add_u32_e32 v150, 0x10000, v136
	v_add_u32_e32 v166, 0x14000, v136
	ds_read_b128 v[138:141], v150
	ds_read_b128 v[142:145], v150 offset:1024
	ds_read_b128 v[146:149], v150 offset:2048
	ds_read_b128 v[150:153], v150 offset:3072
	ds_read_b128 v[154:157], v166
	ds_read_b128 v[158:161], v166 offset:1024
	ds_read_b128 v[162:165], v166 offset:2048
	ds_read_b128 v[166:169], v166 offset:3072
	s_add_i32 s79, s42, 2
	s_cmp_eq_u32 s69, s42
	s_cselect_b32 s50, s29, s75
	s_cselect_b32 s51, s27, s76
	s_cselect_b32 s48, s74, s77
	s_cselect_b32 s49, s73, s78
	s_add_u32 s42, s50, 0x80
	s_addc_u32 s43, s51, 0
	ds_read_b128 v[170:173], v137
	ds_read_b128 v[174:177], v137 offset:1024
	ds_read_b128 v[178:181], v137 offset:2048
	ds_read_b128 v[182:185], v137 offset:3072
	ds_read_b128 v[186:189], v137 offset:4096
	ds_read_b128 v[190:193], v137 offset:5120
	ds_read_b128 v[194:197], v137 offset:6144
	ds_read_b128 v[206:209], v137 offset:7168
	s_mov_b32 m0, s70
	s_nop 0
	global_load_lds_dwordx4 v1, s[40:41]
	s_mov_b32 m0, s71
	s_nop 0
	global_load_lds_dwordx4 v132, s[40:41]
	s_waitcnt vmcnt(8)
	s_waitcnt lgkmcnt(0)
	s_barrier
	s_setprio 1
	s_waitcnt lgkmcnt(7)
	v_mfma_f32_16x16x32_bf16 v[124:127], v[138:141], v[170:173], 0
	v_mfma_f32_16x16x32_bf16 v[128:131], v[146:149], v[170:173], 0
	s_waitcnt lgkmcnt(5)
	v_mfma_f32_16x16x32_bf16 v[112:115], v[138:141], v[178:181], 0
	v_mfma_f32_16x16x32_bf16 v[108:111], v[146:149], v[178:181], 0
	s_waitcnt lgkmcnt(3)
	v_mfma_f32_16x16x32_bf16 v[96:99], v[138:141], v[186:189], 0
	v_mfma_f32_16x16x32_bf16 v[92:95], v[146:149], v[186:189], 0
	s_waitcnt lgkmcnt(1)
	v_mfma_f32_16x16x32_bf16 v[80:83], v[138:141], v[194:197], 0
	v_mfma_f32_16x16x32_bf16 v[76:79], v[146:149], v[194:197], 0
	v_mfma_f32_16x16x32_bf16 v[124:127], v[142:145], v[174:177], v[124:127]
	v_mfma_f32_16x16x32_bf16 v[128:131], v[150:153], v[174:177], v[128:131]
	v_mfma_f32_16x16x32_bf16 v[112:115], v[142:145], v[182:185], v[112:115]
	v_mfma_f32_16x16x32_bf16 v[108:111], v[150:153], v[182:185], v[108:111]
	v_mfma_f32_16x16x32_bf16 v[96:99], v[142:145], v[190:193], v[96:99]
	v_mfma_f32_16x16x32_bf16 v[92:95], v[150:153], v[190:193], v[92:95]
	s_waitcnt lgkmcnt(0)
	v_mfma_f32_16x16x32_bf16 v[80:83], v[142:145], v[206:209], v[80:83]
	v_mfma_f32_16x16x32_bf16 v[76:79], v[150:153], v[206:209], v[76:79]
	s_setprio 0
	s_setprio 1
	v_mfma_f32_16x16x32_bf16 v[120:123], v[154:157], v[170:173], 0
	v_mfma_f32_16x16x32_bf16 v[116:119], v[162:165], v[170:173], 0
	v_mfma_f32_16x16x32_bf16 v[104:107], v[154:157], v[178:181], 0
	v_mfma_f32_16x16x32_bf16 v[100:103], v[162:165], v[178:181], 0
	v_mfma_f32_16x16x32_bf16 v[88:91], v[154:157], v[186:189], 0
	v_mfma_f32_16x16x32_bf16 v[84:87], v[162:165], v[186:189], 0
	v_mfma_f32_16x16x32_bf16 v[72:75], v[154:157], v[194:197], 0
	v_mfma_f32_16x16x32_bf16 v[68:71], v[162:165], v[194:197], 0
	v_mfma_f32_16x16x32_bf16 v[120:123], v[158:161], v[174:177], v[120:123]
	v_mfma_f32_16x16x32_bf16 v[116:119], v[166:169], v[174:177], v[116:119]
	v_mfma_f32_16x16x32_bf16 v[104:107], v[158:161], v[182:185], v[104:107]
	v_mfma_f32_16x16x32_bf16 v[100:103], v[166:169], v[182:185], v[100:103]
	v_mfma_f32_16x16x32_bf16 v[88:91], v[158:161], v[190:193], v[88:91]
	v_mfma_f32_16x16x32_bf16 v[84:87], v[166:169], v[190:193], v[84:87]
	v_mfma_f32_16x16x32_bf16 v[72:75], v[158:161], v[206:209], v[72:75]
	v_mfma_f32_16x16x32_bf16 v[68:71], v[166:169], v[206:209], v[68:71]
	s_setprio 0
	s_barrier
	ds_read_b128 v[170:173], v137 offset:16384
	ds_read_b128 v[174:177], v137 offset:17408
	ds_read_b128 v[178:181], v137 offset:18432
	ds_read_b128 v[182:185], v137 offset:19456
	ds_read_b128 v[186:189], v137 offset:20480
	ds_read_b128 v[190:193], v137 offset:21504
	ds_read_b128 v[194:197], v137 offset:22528
	ds_read_b128 v[206:209], v137 offset:23552
	s_mov_b32 m0, s34
	s_nop 0
	global_load_lds_dwordx4 v2, s[48:49]
	s_mov_b32 m0, s35
	s_nop 0
	global_load_lds_dwordx4 v133, s[48:49]
	s_add_u32 s80, s48, 0x20000
	s_addc_u32 s81, s49, 0
	s_mov_b32 m0, s57
	s_nop 0
	global_load_lds_dwordx4 v2, s[80:81]
	s_mov_b32 m0, s58
	s_nop 0
	global_load_lds_dwordx4 v133, s[80:81]
	s_mov_b32 m0, s33
	s_nop 0
	global_load_lds_dwordx4 v1, s[50:51]
	s_mov_b32 m0, s59
	s_nop 0
	global_load_lds_dwordx4 v132, s[50:51]
	s_waitcnt vmcnt(8)
	s_waitcnt lgkmcnt(0)
	s_barrier
	s_setprio 1
	s_waitcnt lgkmcnt(7)
	v_mfma_f32_16x16x32_bf16 v[64:67], v[138:141], v[170:173], 0
	v_mfma_f32_16x16x32_bf16 v[60:63], v[146:149], v[170:173], 0
	s_waitcnt lgkmcnt(5)
	v_mfma_f32_16x16x32_bf16 v[48:51], v[138:141], v[178:181], 0
	v_mfma_f32_16x16x32_bf16 v[44:47], v[146:149], v[178:181], 0
	s_waitcnt lgkmcnt(3)
	v_mfma_f32_16x16x32_bf16 v[32:35], v[138:141], v[186:189], 0
	v_mfma_f32_16x16x32_bf16 v[28:31], v[146:149], v[186:189], 0
	s_waitcnt lgkmcnt(1)
	v_mfma_f32_16x16x32_bf16 v[16:19], v[138:141], v[194:197], 0
	v_mfma_f32_16x16x32_bf16 v[12:15], v[146:149], v[194:197], 0
	v_mfma_f32_16x16x32_bf16 v[64:67], v[142:145], v[174:177], v[64:67]
	v_mfma_f32_16x16x32_bf16 v[60:63], v[150:153], v[174:177], v[60:63]
	v_mfma_f32_16x16x32_bf16 v[48:51], v[142:145], v[182:185], v[48:51]
	v_mfma_f32_16x16x32_bf16 v[44:47], v[150:153], v[182:185], v[44:47]
	v_mfma_f32_16x16x32_bf16 v[32:35], v[142:145], v[190:193], v[32:35]
	v_mfma_f32_16x16x32_bf16 v[28:31], v[150:153], v[190:193], v[28:31]
	s_waitcnt lgkmcnt(0)
	v_mfma_f32_16x16x32_bf16 v[16:19], v[142:145], v[206:209], v[16:19]
	v_mfma_f32_16x16x32_bf16 v[12:15], v[150:153], v[206:209], v[12:15]
	s_setprio 0
	s_setprio 1
	v_mfma_f32_16x16x32_bf16 v[56:59], v[154:157], v[170:173], 0
	v_mfma_f32_16x16x32_bf16 v[52:55], v[162:165], v[170:173], 0
	v_mfma_f32_16x16x32_bf16 v[40:43], v[154:157], v[178:181], 0
	v_mfma_f32_16x16x32_bf16 v[36:39], v[162:165], v[178:181], 0
	v_mfma_f32_16x16x32_bf16 v[24:27], v[154:157], v[186:189], 0
	v_mfma_f32_16x16x32_bf16 v[20:23], v[162:165], v[186:189], 0
	v_mfma_f32_16x16x32_bf16 v[8:11], v[154:157], v[194:197], 0
	v_mfma_f32_16x16x32_bf16 v[4:7], v[162:165], v[194:197], 0
	v_mfma_f32_16x16x32_bf16 v[56:59], v[158:161], v[174:177], v[56:59]
	v_mfma_f32_16x16x32_bf16 v[52:55], v[166:169], v[174:177], v[52:55]
	v_mfma_f32_16x16x32_bf16 v[40:43], v[158:161], v[182:185], v[40:43]
	v_mfma_f32_16x16x32_bf16 v[36:39], v[166:169], v[182:185], v[36:39]
	v_mfma_f32_16x16x32_bf16 v[24:27], v[158:161], v[190:193], v[24:27]
	v_mfma_f32_16x16x32_bf16 v[20:23], v[166:169], v[190:193], v[20:23]
	v_mfma_f32_16x16x32_bf16 v[8:11], v[158:161], v[206:209], v[8:11]
	v_mfma_f32_16x16x32_bf16 v[4:7], v[166:169], v[206:209], v[4:7]
	s_setprio 0
	s_barrier
	v_add_u32_e32 v150, 0x18000, v136
	v_add_u32_e32 v166, 0x1c000, v136
	ds_read_b128 v[138:141], v150
	ds_read_b128 v[142:145], v150 offset:1024
	ds_read_b128 v[146:149], v150 offset:2048
	ds_read_b128 v[150:153], v150 offset:3072
	ds_read_b128 v[154:157], v166
	ds_read_b128 v[158:161], v166 offset:1024
	ds_read_b128 v[162:165], v166 offset:2048
	ds_read_b128 v[166:169], v166 offset:3072
	ds_read_b128 v[170:173], v137 offset:32768
	ds_read_b128 v[174:177], v137 offset:33792
	ds_read_b128 v[178:181], v137 offset:34816
	ds_read_b128 v[182:185], v137 offset:35840
	ds_read_b128 v[186:189], v137 offset:36864
	ds_read_b128 v[190:193], v137 offset:37888
	ds_read_b128 v[194:197], v137 offset:38912
	ds_read_b128 v[206:209], v137 offset:39936
	s_add_u32 s50, s50, 0x20000
	s_addc_u32 s51, s51, 0
	s_mov_b32 m0, s60
	s_nop 0
	global_load_lds_dwordx4 v1, s[50:51]
	s_mov_b32 m0, s61
	s_nop 0
	global_load_lds_dwordx4 v132, s[50:51]
	s_waitcnt vmcnt(8)
	s_waitcnt lgkmcnt(0)
	s_barrier
	s_setprio 1
	s_waitcnt lgkmcnt(7)
	v_mfma_f32_16x16x32_bf16 v[124:127], v[138:141], v[170:173], v[124:127]
	v_mfma_f32_16x16x32_bf16 v[128:131], v[146:149], v[170:173], v[128:131]
	s_waitcnt lgkmcnt(5)
	v_mfma_f32_16x16x32_bf16 v[112:115], v[138:141], v[178:181], v[112:115]
	v_mfma_f32_16x16x32_bf16 v[108:111], v[146:149], v[178:181], v[108:111]
	s_waitcnt lgkmcnt(3)
	v_mfma_f32_16x16x32_bf16 v[96:99], v[138:141], v[186:189], v[96:99]
	v_mfma_f32_16x16x32_bf16 v[92:95], v[146:149], v[186:189], v[92:95]
	s_waitcnt lgkmcnt(1)
	v_mfma_f32_16x16x32_bf16 v[80:83], v[138:141], v[194:197], v[80:83]
	v_mfma_f32_16x16x32_bf16 v[76:79], v[146:149], v[194:197], v[76:79]
	v_mfma_f32_16x16x32_bf16 v[124:127], v[142:145], v[174:177], v[124:127]
	v_mfma_f32_16x16x32_bf16 v[128:131], v[150:153], v[174:177], v[128:131]
	v_mfma_f32_16x16x32_bf16 v[112:115], v[142:145], v[182:185], v[112:115]
	v_mfma_f32_16x16x32_bf16 v[108:111], v[150:153], v[182:185], v[108:111]
	v_mfma_f32_16x16x32_bf16 v[96:99], v[142:145], v[190:193], v[96:99]
	v_mfma_f32_16x16x32_bf16 v[92:95], v[150:153], v[190:193], v[92:95]
	s_waitcnt lgkmcnt(0)
	v_mfma_f32_16x16x32_bf16 v[80:83], v[142:145], v[206:209], v[80:83]
	v_mfma_f32_16x16x32_bf16 v[76:79], v[150:153], v[206:209], v[76:79]
	s_setprio 0
	s_setprio 1
	v_mfma_f32_16x16x32_bf16 v[120:123], v[154:157], v[170:173], v[120:123]
	v_mfma_f32_16x16x32_bf16 v[116:119], v[162:165], v[170:173], v[116:119]
	v_mfma_f32_16x16x32_bf16 v[104:107], v[154:157], v[178:181], v[104:107]
	v_mfma_f32_16x16x32_bf16 v[100:103], v[162:165], v[178:181], v[100:103]
	v_mfma_f32_16x16x32_bf16 v[88:91], v[154:157], v[186:189], v[88:91]
	v_mfma_f32_16x16x32_bf16 v[84:87], v[162:165], v[186:189], v[84:87]
	v_mfma_f32_16x16x32_bf16 v[72:75], v[154:157], v[194:197], v[72:75]
	v_mfma_f32_16x16x32_bf16 v[68:71], v[162:165], v[194:197], v[68:71]
	v_mfma_f32_16x16x32_bf16 v[120:123], v[158:161], v[174:177], v[120:123]
	v_mfma_f32_16x16x32_bf16 v[116:119], v[166:169], v[174:177], v[116:119]
	v_mfma_f32_16x16x32_bf16 v[104:107], v[158:161], v[182:185], v[104:107]
	v_mfma_f32_16x16x32_bf16 v[100:103], v[166:169], v[182:185], v[100:103]
	v_mfma_f32_16x16x32_bf16 v[88:91], v[158:161], v[190:193], v[88:91]
	v_mfma_f32_16x16x32_bf16 v[84:87], v[166:169], v[190:193], v[84:87]
	v_mfma_f32_16x16x32_bf16 v[72:75], v[158:161], v[206:209], v[72:75]
	v_mfma_f32_16x16x32_bf16 v[68:71], v[166:169], v[206:209], v[68:71]
	s_setprio 0
	s_barrier
	ds_read_b128 v[170:173], v137 offset:49152
	ds_read_b128 v[174:177], v137 offset:50176
	ds_read_b128 v[178:181], v137 offset:51200
	ds_read_b128 v[182:185], v137 offset:52224
	ds_read_b128 v[186:189], v137 offset:53248
	ds_read_b128 v[190:193], v137 offset:54272
	ds_read_b128 v[194:197], v137 offset:55296
	ds_read_b128 v[206:209], v137 offset:56320
	s_add_u32 s50, s48, 0x80
	s_addc_u32 s51, s49, 0
	s_mov_b32 m0, s63
	s_nop 0
	global_load_lds_dwordx4 v2, s[50:51]
	s_add_u32 s48, s48, 0x20080
	s_mov_b32 m0, s64
	s_nop 0
	global_load_lds_dwordx4 v133, s[50:51]
	s_addc_u32 s49, s49, 0
	s_mov_b32 m0, s67
	s_nop 0
	global_load_lds_dwordx4 v2, s[48:49]
	s_mov_b32 m0, s68
	s_nop 0
	global_load_lds_dwordx4 v133, s[48:49]
	s_mov_b32 m0, s65
	s_nop 0
	global_load_lds_dwordx4 v1, s[42:43]
	s_mov_b32 m0, s66
	s_nop 0
	global_load_lds_dwordx4 v132, s[42:43]
	s_waitcnt vmcnt(8)
	s_waitcnt lgkmcnt(0)
	s_barrier
	s_setprio 1
	s_waitcnt lgkmcnt(7)
	v_mfma_f32_16x16x32_bf16 v[64:67], v[138:141], v[170:173], v[64:67]
	v_mfma_f32_16x16x32_bf16 v[60:63], v[146:149], v[170:173], v[60:63]
	s_add_u32 s75, s75, 0x100
	s_waitcnt lgkmcnt(5)
	v_mfma_f32_16x16x32_bf16 v[48:51], v[138:141], v[178:181], v[48:51]
	s_addc_u32 s76, s76, 0
	v_mfma_f32_16x16x32_bf16 v[44:47], v[146:149], v[178:181], v[44:47]
	s_add_u32 s77, s77, 0x100
	s_waitcnt lgkmcnt(3)
	v_mfma_f32_16x16x32_bf16 v[32:35], v[138:141], v[186:189], v[32:35]
	s_addc_u32 s78, s78, 0
	v_mfma_f32_16x16x32_bf16 v[28:31], v[146:149], v[186:189], v[28:31]
	s_add_u32 s40, s40, 0x100
	s_waitcnt lgkmcnt(1)
	v_mfma_f32_16x16x32_bf16 v[16:19], v[138:141], v[194:197], v[16:19]
	s_addc_u32 s41, s41, 0
	v_mfma_f32_16x16x32_bf16 v[12:15], v[146:149], v[194:197], v[12:15]
	s_mov_b32 s42, s79
	v_mfma_f32_16x16x32_bf16 v[64:67], v[142:145], v[174:177], v[64:67]
	s_cmp_ge_i32 s79, s62
	v_mfma_f32_16x16x32_bf16 v[60:63], v[150:153], v[174:177], v[60:63]
	v_mfma_f32_16x16x32_bf16 v[48:51], v[142:145], v[182:185], v[48:51]
	v_mfma_f32_16x16x32_bf16 v[44:47], v[150:153], v[182:185], v[44:47]
	v_mfma_f32_16x16x32_bf16 v[32:35], v[142:145], v[190:193], v[32:35]
	v_mfma_f32_16x16x32_bf16 v[28:31], v[150:153], v[190:193], v[28:31]
	s_waitcnt lgkmcnt(0)
	v_mfma_f32_16x16x32_bf16 v[16:19], v[142:145], v[206:209], v[16:19]
	v_mfma_f32_16x16x32_bf16 v[12:15], v[150:153], v[206:209], v[12:15]
	s_setprio 0
	s_setprio 1
	v_mfma_f32_16x16x32_bf16 v[56:59], v[154:157], v[170:173], v[56:59]
	v_mfma_f32_16x16x32_bf16 v[52:55], v[162:165], v[170:173], v[52:55]
	v_mfma_f32_16x16x32_bf16 v[40:43], v[154:157], v[178:181], v[40:43]
	v_mfma_f32_16x16x32_bf16 v[36:39], v[162:165], v[178:181], v[36:39]
	v_mfma_f32_16x16x32_bf16 v[24:27], v[154:157], v[186:189], v[24:27]
	v_mfma_f32_16x16x32_bf16 v[20:23], v[162:165], v[186:189], v[20:23]
	v_mfma_f32_16x16x32_bf16 v[8:11], v[154:157], v[194:197], v[8:11]
	v_mfma_f32_16x16x32_bf16 v[4:7], v[162:165], v[194:197], v[4:7]
	v_mfma_f32_16x16x32_bf16 v[56:59], v[158:161], v[174:177], v[56:59]
	v_mfma_f32_16x16x32_bf16 v[52:55], v[166:169], v[174:177], v[52:55]
	v_mfma_f32_16x16x32_bf16 v[40:43], v[158:161], v[182:185], v[40:43]
	v_mfma_f32_16x16x32_bf16 v[36:39], v[166:169], v[182:185], v[36:39]
	v_mfma_f32_16x16x32_bf16 v[24:27], v[158:161], v[190:193], v[24:27]
	v_mfma_f32_16x16x32_bf16 v[20:23], v[166:169], v[190:193], v[20:23]
	v_mfma_f32_16x16x32_bf16 v[8:11], v[158:161], v[206:209], v[8:11]
	v_mfma_f32_16x16x32_bf16 v[4:7], v[166:169], v[206:209], v[4:7]
	s_setprio 0
	s_barrier
	s_cbranch_scc0 .LBB0_588
	s_branch .LBB0_589

.Lkz_2:
	s_and_b64 s[48:49], s[4:5], exec
	s_cselect_b32 s3, s31, s43
	s_cselect_b32 s27, s30, s42
	s_cselect_b32 s73, s39, s41
	s_cselect_b32 s74, s38, s40
	s_add_u32 s75, s42, 0x100
	s_addc_u32 s76, s43, 0
	s_add_u32 s77, s40, 0x100
	s_addc_u32 s78, s41, 0
	s_add_u32 s40, s42, 0x10080
	s_addc_u32 s41, s43, 0
	s_mov_b32 s42, 0
	v_add_u32_e32 v150, 0x10000, v136
	v_add_u32_e32 v166, 0x14000, v136
	ds_read_b128 v[138:141], v150
	ds_read_b128 v[142:145], v150 offset:1024
	ds_read_b128 v[146:149], v150 offset:2048
	ds_read_b128 v[150:153], v150 offset:3072
	ds_read_b128 v[154:157], v166
	ds_read_b128 v[158:161], v166 offset:1024
	ds_read_b128 v[162:165], v166 offset:2048
	ds_read_b128 v[166:169], v166 offset:3072
	s_add_i32 s79, s42, 2
	s_cmp_eq_u32 s68, s42
	s_cselect_b32 s50, s27, s75
	s_cselect_b32 s51, s3, s76
	s_cselect_b32 s48, s74, s77
	s_cselect_b32 s49, s73, s78
	s_add_u32 s42, s50, 0x80
	s_addc_u32 s43, s51, 0
	ds_read_b128 v[170:173], v137
	ds_read_b128 v[174:177], v137 offset:1024
	ds_read_b128 v[178:181], v137 offset:2048
	ds_read_b128 v[182:185], v137 offset:3072
	ds_read_b128 v[186:189], v137 offset:4096
	ds_read_b128 v[190:193], v137 offset:5120
	ds_read_b128 v[194:197], v137 offset:6144
	ds_read_b128 v[206:209], v137 offset:7168
	s_mov_b32 m0, s69
	s_nop 0
	global_load_lds_dwordx4 v1, s[40:41]
	s_mov_b32 m0, s70
	s_nop 0
	global_load_lds_dwordx4 v132, s[40:41]
	s_waitcnt vmcnt(8)
	s_waitcnt lgkmcnt(0)
	s_barrier
	s_setprio 1
	s_waitcnt lgkmcnt(7)
	v_mfma_f32_16x16x32_bf16 v[124:127], v[138:141], v[170:173], 0
	v_mfma_f32_16x16x32_bf16 v[128:131], v[146:149], v[170:173], 0
	s_waitcnt lgkmcnt(5)
	v_mfma_f32_16x16x32_bf16 v[112:115], v[138:141], v[178:181], 0
	v_mfma_f32_16x16x32_bf16 v[108:111], v[146:149], v[178:181], 0
	s_waitcnt lgkmcnt(3)
	v_mfma_f32_16x16x32_bf16 v[96:99], v[138:141], v[186:189], 0
	v_mfma_f32_16x16x32_bf16 v[92:95], v[146:149], v[186:189], 0
	s_waitcnt lgkmcnt(1)
	v_mfma_f32_16x16x32_bf16 v[80:83], v[138:141], v[194:197], 0
	v_mfma_f32_16x16x32_bf16 v[76:79], v[146:149], v[194:197], 0
	v_mfma_f32_16x16x32_bf16 v[124:127], v[142:145], v[174:177], v[124:127]
	v_mfma_f32_16x16x32_bf16 v[128:131], v[150:153], v[174:177], v[128:131]
	v_mfma_f32_16x16x32_bf16 v[112:115], v[142:145], v[182:185], v[112:115]
	v_mfma_f32_16x16x32_bf16 v[108:111], v[150:153], v[182:185], v[108:111]
	v_mfma_f32_16x16x32_bf16 v[96:99], v[142:145], v[190:193], v[96:99]
	v_mfma_f32_16x16x32_bf16 v[92:95], v[150:153], v[190:193], v[92:95]
	s_waitcnt lgkmcnt(0)
	v_mfma_f32_16x16x32_bf16 v[80:83], v[142:145], v[206:209], v[80:83]
	v_mfma_f32_16x16x32_bf16 v[76:79], v[150:153], v[206:209], v[76:79]
	s_setprio 0
	s_setprio 1
	v_mfma_f32_16x16x32_bf16 v[120:123], v[154:157], v[170:173], 0
	v_mfma_f32_16x16x32_bf16 v[116:119], v[162:165], v[170:173], 0
	v_mfma_f32_16x16x32_bf16 v[104:107], v[154:157], v[178:181], 0
	v_mfma_f32_16x16x32_bf16 v[100:103], v[162:165], v[178:181], 0
	v_mfma_f32_16x16x32_bf16 v[88:91], v[154:157], v[186:189], 0
	v_mfma_f32_16x16x32_bf16 v[84:87], v[162:165], v[186:189], 0
	v_mfma_f32_16x16x32_bf16 v[72:75], v[154:157], v[194:197], 0
	v_mfma_f32_16x16x32_bf16 v[68:71], v[162:165], v[194:197], 0
	v_mfma_f32_16x16x32_bf16 v[120:123], v[158:161], v[174:177], v[120:123]
	v_mfma_f32_16x16x32_bf16 v[116:119], v[166:169], v[174:177], v[116:119]
	v_mfma_f32_16x16x32_bf16 v[104:107], v[158:161], v[182:185], v[104:107]
	v_mfma_f32_16x16x32_bf16 v[100:103], v[166:169], v[182:185], v[100:103]
	v_mfma_f32_16x16x32_bf16 v[88:91], v[158:161], v[190:193], v[88:91]
	v_mfma_f32_16x16x32_bf16 v[84:87], v[166:169], v[190:193], v[84:87]
	v_mfma_f32_16x16x32_bf16 v[72:75], v[158:161], v[206:209], v[72:75]
	v_mfma_f32_16x16x32_bf16 v[68:71], v[166:169], v[206:209], v[68:71]
	s_setprio 0
	s_barrier
	ds_read_b128 v[170:173], v137 offset:16384
	ds_read_b128 v[174:177], v137 offset:17408
	ds_read_b128 v[178:181], v137 offset:18432
	ds_read_b128 v[182:185], v137 offset:19456
	ds_read_b128 v[186:189], v137 offset:20480
	ds_read_b128 v[190:193], v137 offset:21504
	ds_read_b128 v[194:197], v137 offset:22528
	ds_read_b128 v[206:209], v137 offset:23552
	s_mov_b32 m0, s29
	s_nop 0
	global_load_lds_dwordx4 v2, s[48:49]
	s_mov_b32 m0, s34
	s_nop 0
	global_load_lds_dwordx4 v133, s[48:49]
	s_add_u32 s80, s48, 0x10000
	s_addc_u32 s81, s49, 0
	s_mov_b32 m0, s35
	s_nop 0
	global_load_lds_dwordx4 v2, s[80:81]
	s_mov_b32 m0, s57
	s_nop 0
	global_load_lds_dwordx4 v133, s[80:81]
	s_mov_b32 m0, s0
	s_nop 0
	global_load_lds_dwordx4 v1, s[50:51]
	s_mov_b32 m0, s58
	s_nop 0
	global_load_lds_dwordx4 v132, s[50:51]
	s_waitcnt vmcnt(8)
	s_waitcnt lgkmcnt(0)
	s_barrier
	s_setprio 1
	s_waitcnt lgkmcnt(7)
	v_mfma_f32_16x16x32_bf16 v[64:67], v[138:141], v[170:173], 0
	v_mfma_f32_16x16x32_bf16 v[60:63], v[146:149], v[170:173], 0
	s_waitcnt lgkmcnt(5)
	v_mfma_f32_16x16x32_bf16 v[48:51], v[138:141], v[178:181], 0
	v_mfma_f32_16x16x32_bf16 v[44:47], v[146:149], v[178:181], 0
	s_waitcnt lgkmcnt(3)
	v_mfma_f32_16x16x32_bf16 v[32:35], v[138:141], v[186:189], 0
	v_mfma_f32_16x16x32_bf16 v[28:31], v[146:149], v[186:189], 0
	s_waitcnt lgkmcnt(1)
	v_mfma_f32_16x16x32_bf16 v[16:19], v[138:141], v[194:197], 0
	v_mfma_f32_16x16x32_bf16 v[12:15], v[146:149], v[194:197], 0
	v_mfma_f32_16x16x32_bf16 v[64:67], v[142:145], v[174:177], v[64:67]
	v_mfma_f32_16x16x32_bf16 v[60:63], v[150:153], v[174:177], v[60:63]
	v_mfma_f32_16x16x32_bf16 v[48:51], v[142:145], v[182:185], v[48:51]
	v_mfma_f32_16x16x32_bf16 v[44:47], v[150:153], v[182:185], v[44:47]
	v_mfma_f32_16x16x32_bf16 v[32:35], v[142:145], v[190:193], v[32:35]
	v_mfma_f32_16x16x32_bf16 v[28:31], v[150:153], v[190:193], v[28:31]
	s_waitcnt lgkmcnt(0)
	v_mfma_f32_16x16x32_bf16 v[16:19], v[142:145], v[206:209], v[16:19]
	v_mfma_f32_16x16x32_bf16 v[12:15], v[150:153], v[206:209], v[12:15]
	s_setprio 0
	s_setprio 1
	v_mfma_f32_16x16x32_bf16 v[56:59], v[154:157], v[170:173], 0
	v_mfma_f32_16x16x32_bf16 v[52:55], v[162:165], v[170:173], 0
	v_mfma_f32_16x16x32_bf16 v[40:43], v[154:157], v[178:181], 0
	v_mfma_f32_16x16x32_bf16 v[36:39], v[162:165], v[178:181], 0
	v_mfma_f32_16x16x32_bf16 v[24:27], v[154:157], v[186:189], 0
	v_mfma_f32_16x16x32_bf16 v[20:23], v[162:165], v[186:189], 0
	v_mfma_f32_16x16x32_bf16 v[8:11], v[154:157], v[194:197], 0
	v_mfma_f32_16x16x32_bf16 v[4:7], v[162:165], v[194:197], 0
	v_mfma_f32_16x16x32_bf16 v[56:59], v[158:161], v[174:177], v[56:59]
	v_mfma_f32_16x16x32_bf16 v[52:55], v[166:169], v[174:177], v[52:55]
	v_mfma_f32_16x16x32_bf16 v[40:43], v[158:161], v[182:185], v[40:43]
	v_mfma_f32_16x16x32_bf16 v[36:39], v[166:169], v[182:185], v[36:39]
	v_mfma_f32_16x16x32_bf16 v[24:27], v[158:161], v[190:193], v[24:27]
	v_mfma_f32_16x16x32_bf16 v[20:23], v[166:169], v[190:193], v[20:23]
	v_mfma_f32_16x16x32_bf16 v[8:11], v[158:161], v[206:209], v[8:11]
	v_mfma_f32_16x16x32_bf16 v[4:7], v[166:169], v[206:209], v[4:7]
	s_setprio 0
	s_barrier
	v_add_u32_e32 v150, 0x18000, v136
	v_add_u32_e32 v166, 0x1c000, v136
	ds_read_b128 v[138:141], v150
	ds_read_b128 v[142:145], v150 offset:1024
	ds_read_b128 v[146:149], v150 offset:2048
	ds_read_b128 v[150:153], v150 offset:3072
	ds_read_b128 v[154:157], v166
	ds_read_b128 v[158:161], v166 offset:1024
	ds_read_b128 v[162:165], v166 offset:2048
	ds_read_b128 v[166:169], v166 offset:3072
	ds_read_b128 v[170:173], v137 offset:32768
	ds_read_b128 v[174:177], v137 offset:33792
	ds_read_b128 v[178:181], v137 offset:34816
	ds_read_b128 v[182:185], v137 offset:35840
	ds_read_b128 v[186:189], v137 offset:36864
	ds_read_b128 v[190:193], v137 offset:37888
	ds_read_b128 v[194:197], v137 offset:38912
	ds_read_b128 v[206:209], v137 offset:39936
	s_add_u32 s50, s50, 0x10000
	s_addc_u32 s51, s51, 0
	s_mov_b32 m0, s59
	s_nop 0
	global_load_lds_dwordx4 v1, s[50:51]
	s_mov_b32 m0, s60
	s_nop 0
	global_load_lds_dwordx4 v132, s[50:51]
	s_waitcnt vmcnt(8)
	s_waitcnt lgkmcnt(0)
	s_barrier
	s_setprio 1
	s_waitcnt lgkmcnt(7)
	v_mfma_f32_16x16x32_bf16 v[124:127], v[138:141], v[170:173], v[124:127]
	v_mfma_f32_16x16x32_bf16 v[128:131], v[146:149], v[170:173], v[128:131]
	s_waitcnt lgkmcnt(5)
	v_mfma_f32_16x16x32_bf16 v[112:115], v[138:141], v[178:181], v[112:115]
	v_mfma_f32_16x16x32_bf16 v[108:111], v[146:149], v[178:181], v[108:111]
	s_waitcnt lgkmcnt(3)
	v_mfma_f32_16x16x32_bf16 v[96:99], v[138:141], v[186:189], v[96:99]
	v_mfma_f32_16x16x32_bf16 v[92:95], v[146:149], v[186:189], v[92:95]
	s_waitcnt lgkmcnt(1)
	v_mfma_f32_16x16x32_bf16 v[80:83], v[138:141], v[194:197], v[80:83]
	v_mfma_f32_16x16x32_bf16 v[76:79], v[146:149], v[194:197], v[76:79]
	v_mfma_f32_16x16x32_bf16 v[124:127], v[142:145], v[174:177], v[124:127]
	v_mfma_f32_16x16x32_bf16 v[128:131], v[150:153], v[174:177], v[128:131]
	v_mfma_f32_16x16x32_bf16 v[112:115], v[142:145], v[182:185], v[112:115]
	v_mfma_f32_16x16x32_bf16 v[108:111], v[150:153], v[182:185], v[108:111]
	v_mfma_f32_16x16x32_bf16 v[96:99], v[142:145], v[190:193], v[96:99]
	v_mfma_f32_16x16x32_bf16 v[92:95], v[150:153], v[190:193], v[92:95]
	s_waitcnt lgkmcnt(0)
	v_mfma_f32_16x16x32_bf16 v[80:83], v[142:145], v[206:209], v[80:83]
	v_mfma_f32_16x16x32_bf16 v[76:79], v[150:153], v[206:209], v[76:79]
	s_setprio 0
	s_setprio 1
	v_mfma_f32_16x16x32_bf16 v[120:123], v[154:157], v[170:173], v[120:123]
	v_mfma_f32_16x16x32_bf16 v[116:119], v[162:165], v[170:173], v[116:119]
	v_mfma_f32_16x16x32_bf16 v[104:107], v[154:157], v[178:181], v[104:107]
	v_mfma_f32_16x16x32_bf16 v[100:103], v[162:165], v[178:181], v[100:103]
	v_mfma_f32_16x16x32_bf16 v[88:91], v[154:157], v[186:189], v[88:91]
	v_mfma_f32_16x16x32_bf16 v[84:87], v[162:165], v[186:189], v[84:87]
	v_mfma_f32_16x16x32_bf16 v[72:75], v[154:157], v[194:197], v[72:75]
	v_mfma_f32_16x16x32_bf16 v[68:71], v[162:165], v[194:197], v[68:71]
	v_mfma_f32_16x16x32_bf16 v[120:123], v[158:161], v[174:177], v[120:123]
	v_mfma_f32_16x16x32_bf16 v[116:119], v[166:169], v[174:177], v[116:119]
	v_mfma_f32_16x16x32_bf16 v[104:107], v[158:161], v[182:185], v[104:107]
	v_mfma_f32_16x16x32_bf16 v[100:103], v[166:169], v[182:185], v[100:103]
	v_mfma_f32_16x16x32_bf16 v[88:91], v[158:161], v[190:193], v[88:91]
	v_mfma_f32_16x16x32_bf16 v[84:87], v[166:169], v[190:193], v[84:87]
	v_mfma_f32_16x16x32_bf16 v[72:75], v[158:161], v[206:209], v[72:75]
	v_mfma_f32_16x16x32_bf16 v[68:71], v[166:169], v[206:209], v[68:71]
	s_setprio 0
	s_barrier
	ds_read_b128 v[170:173], v137 offset:49152
	ds_read_b128 v[174:177], v137 offset:50176
	ds_read_b128 v[178:181], v137 offset:51200
	ds_read_b128 v[182:185], v137 offset:52224
	ds_read_b128 v[186:189], v137 offset:53248
	ds_read_b128 v[190:193], v137 offset:54272
	ds_read_b128 v[194:197], v137 offset:55296
	ds_read_b128 v[206:209], v137 offset:56320
	s_add_u32 s50, s48, 0x80
	s_addc_u32 s51, s49, 0
	s_mov_b32 m0, s62
	s_nop 0
	global_load_lds_dwordx4 v2, s[50:51]
	s_add_u32 s48, s48, 0x10080
	s_mov_b32 m0, s63
	s_nop 0
	global_load_lds_dwordx4 v133, s[50:51]
	s_addc_u32 s49, s49, 0
	s_mov_b32 m0, s66
	s_nop 0
	global_load_lds_dwordx4 v2, s[48:49]
	s_mov_b32 m0, s67
	s_nop 0
	global_load_lds_dwordx4 v133, s[48:49]
	s_mov_b32 m0, s64
	s_nop 0
	global_load_lds_dwordx4 v1, s[42:43]
	s_mov_b32 m0, s65
	s_nop 0
	global_load_lds_dwordx4 v132, s[42:43]
	s_waitcnt vmcnt(8)
	s_waitcnt lgkmcnt(0)
	s_barrier
	s_setprio 1
	s_waitcnt lgkmcnt(7)
	v_mfma_f32_16x16x32_bf16 v[64:67], v[138:141], v[170:173], v[64:67]
	v_mfma_f32_16x16x32_bf16 v[60:63], v[146:149], v[170:173], v[60:63]
	s_add_u32 s75, s75, 0x100
	s_waitcnt lgkmcnt(5)
	v_mfma_f32_16x16x32_bf16 v[48:51], v[138:141], v[178:181], v[48:51]
	s_addc_u32 s76, s76, 0
	v_mfma_f32_16x16x32_bf16 v[44:47], v[146:149], v[178:181], v[44:47]
	s_add_u32 s77, s77, 0x100
	s_waitcnt lgkmcnt(3)
	v_mfma_f32_16x16x32_bf16 v[32:35], v[138:141], v[186:189], v[32:35]
	s_addc_u32 s78, s78, 0
	v_mfma_f32_16x16x32_bf16 v[28:31], v[146:149], v[186:189], v[28:31]
	s_add_u32 s40, s40, 0x100
	s_waitcnt lgkmcnt(1)
	v_mfma_f32_16x16x32_bf16 v[16:19], v[138:141], v[194:197], v[16:19]
	s_addc_u32 s41, s41, 0
	v_mfma_f32_16x16x32_bf16 v[12:15], v[146:149], v[194:197], v[12:15]
	s_mov_b32 s42, s79
	v_mfma_f32_16x16x32_bf16 v[64:67], v[142:145], v[174:177], v[64:67]
	s_cmp_ge_i32 s79, s61
	v_mfma_f32_16x16x32_bf16 v[60:63], v[150:153], v[174:177], v[60:63]
	v_mfma_f32_16x16x32_bf16 v[48:51], v[142:145], v[182:185], v[48:51]
	v_mfma_f32_16x16x32_bf16 v[44:47], v[150:153], v[182:185], v[44:47]
	v_mfma_f32_16x16x32_bf16 v[32:35], v[142:145], v[190:193], v[32:35]
	v_mfma_f32_16x16x32_bf16 v[28:31], v[150:153], v[190:193], v[28:31]
	s_waitcnt lgkmcnt(0)
	v_mfma_f32_16x16x32_bf16 v[16:19], v[142:145], v[206:209], v[16:19]
	v_mfma_f32_16x16x32_bf16 v[12:15], v[150:153], v[206:209], v[12:15]
	s_setprio 0
	s_setprio 1
	v_mfma_f32_16x16x32_bf16 v[56:59], v[154:157], v[170:173], v[56:59]
	v_mfma_f32_16x16x32_bf16 v[52:55], v[162:165], v[170:173], v[52:55]
	v_mfma_f32_16x16x32_bf16 v[40:43], v[154:157], v[178:181], v[40:43]
	v_mfma_f32_16x16x32_bf16 v[36:39], v[162:165], v[178:181], v[36:39]
	v_mfma_f32_16x16x32_bf16 v[24:27], v[154:157], v[186:189], v[24:27]
	v_mfma_f32_16x16x32_bf16 v[20:23], v[162:165], v[186:189], v[20:23]
	v_mfma_f32_16x16x32_bf16 v[8:11], v[154:157], v[194:197], v[8:11]
	v_mfma_f32_16x16x32_bf16 v[4:7], v[162:165], v[194:197], v[4:7]
	v_mfma_f32_16x16x32_bf16 v[56:59], v[158:161], v[174:177], v[56:59]
	v_mfma_f32_16x16x32_bf16 v[52:55], v[166:169], v[174:177], v[52:55]
	v_mfma_f32_16x16x32_bf16 v[40:43], v[158:161], v[182:185], v[40:43]
	v_mfma_f32_16x16x32_bf16 v[36:39], v[166:169], v[182:185], v[36:39]
	v_mfma_f32_16x16x32_bf16 v[24:27], v[158:161], v[190:193], v[24:27]
	v_mfma_f32_16x16x32_bf16 v[20:23], v[166:169], v[190:193], v[20:23]
	v_mfma_f32_16x16x32_bf16 v[8:11], v[158:161], v[206:209], v[8:11]
	v_mfma_f32_16x16x32_bf16 v[4:7], v[166:169], v[206:209], v[4:7]
	s_setprio 0
	s_barrier
	s_cbranch_scc0 .LBB0_605
	s_branch .LBB0_606

.Lkz_3:
	s_and_b64 s[40:41], s[38:39], exec
	s_cselect_b32 s3, s25, s31
	s_cselect_b32 s21, s24, s30
	s_cselect_b32 s23, s27, s29
	s_cselect_b32 s66, s26, s28
	s_add_u32 s67, s30, 0x100
	s_addc_u32 s68, s31, 0
	s_add_u32 s69, s28, 0x100
	s_addc_u32 s70, s29, 0
	s_mov_b32 s28, 0
	v_add_u32_e32 v144, 0x10000, v154
	v_add_u32_e32 v148, 0x14000, v154
	ds_read_b128 v[132:135], v144
	ds_read_b128 v[136:139], v144 offset:1024
	ds_read_b128 v[140:143], v144 offset:2048
	ds_read_b128 v[144:147], v144 offset:3072
	ds_read_b128 v[156:159], v148
	ds_read_b128 v[160:163], v148 offset:1024
	ds_read_b128 v[164:167], v148 offset:2048
	ds_read_b128 v[168:171], v148 offset:3072
	s_add_i32 s71, s28, 2
	s_cmp_eq_u32 s14, s28
	s_cselect_b32 s40, s21, s67
	s_cselect_b32 s41, s3, s68
	s_cselect_b32 s30, s66, s69
	s_cselect_b32 s31, s23, s70
	s_add_u32 s28, s40, 0x80
	s_addc_u32 s29, s41, 0
	ds_read_b128 v[172:175], v155
	ds_read_b128 v[176:179], v155 offset:1024
	ds_read_b128 v[180:183], v155 offset:2048
	ds_read_b128 v[184:187], v155 offset:3072
	ds_read_b128 v[188:191], v155 offset:4096
	ds_read_b128 v[192:195], v155 offset:5120
	ds_read_b128 v[206:209], v155 offset:6144
	ds_read_b128 v[210:213], v155 offset:7168
	s_add_u32 s72, s67, 0x1ff80
	s_addc_u32 s73, s68, 0
	s_mov_b32 m0, s15
	s_nop 0
	global_load_lds_dwordx4 v1, s[72:73]
	s_mov_b32 m0, s34
	s_nop 0
	global_load_lds_dwordx4 v150, s[72:73]
	s_waitcnt vmcnt(8)
	s_waitcnt lgkmcnt(0)
	s_barrier
	s_setprio 1
	s_waitcnt lgkmcnt(7)
	v_mfma_f32_16x16x32_bf16 v[124:127], v[132:135], v[172:175], 0
	v_mfma_f32_16x16x32_bf16 v[128:131], v[140:143], v[172:175], 0
	s_waitcnt lgkmcnt(5)
	v_mfma_f32_16x16x32_bf16 v[112:115], v[132:135], v[180:183], 0
	v_mfma_f32_16x16x32_bf16 v[108:111], v[140:143], v[180:183], 0
	s_waitcnt lgkmcnt(3)
	v_mfma_f32_16x16x32_bf16 v[96:99], v[132:135], v[188:191], 0
	v_mfma_f32_16x16x32_bf16 v[92:95], v[140:143], v[188:191], 0
	s_waitcnt lgkmcnt(1)
	v_mfma_f32_16x16x32_bf16 v[80:83], v[132:135], v[206:209], 0
	v_mfma_f32_16x16x32_bf16 v[76:79], v[140:143], v[206:209], 0
	v_mfma_f32_16x16x32_bf16 v[124:127], v[136:139], v[176:179], v[124:127]
	v_mfma_f32_16x16x32_bf16 v[128:131], v[144:147], v[176:179], v[128:131]
	v_mfma_f32_16x16x32_bf16 v[112:115], v[136:139], v[184:187], v[112:115]
	v_mfma_f32_16x16x32_bf16 v[108:111], v[144:147], v[184:187], v[108:111]
	v_mfma_f32_16x16x32_bf16 v[96:99], v[136:139], v[192:195], v[96:99]
	v_mfma_f32_16x16x32_bf16 v[92:95], v[144:147], v[192:195], v[92:95]
	s_waitcnt lgkmcnt(0)
	v_mfma_f32_16x16x32_bf16 v[80:83], v[136:139], v[210:213], v[80:83]
	v_mfma_f32_16x16x32_bf16 v[76:79], v[144:147], v[210:213], v[76:79]
	s_setprio 0
	s_setprio 1
	v_mfma_f32_16x16x32_bf16 v[120:123], v[156:159], v[172:175], 0
	v_mfma_f32_16x16x32_bf16 v[116:119], v[164:167], v[172:175], 0
	v_mfma_f32_16x16x32_bf16 v[104:107], v[156:159], v[180:183], 0
	v_mfma_f32_16x16x32_bf16 v[100:103], v[164:167], v[180:183], 0
	v_mfma_f32_16x16x32_bf16 v[88:91], v[156:159], v[188:191], 0
	v_mfma_f32_16x16x32_bf16 v[84:87], v[164:167], v[188:191], 0
	v_mfma_f32_16x16x32_bf16 v[72:75], v[156:159], v[206:209], 0
	v_mfma_f32_16x16x32_bf16 v[68:71], v[164:167], v[206:209], 0
	v_mfma_f32_16x16x32_bf16 v[120:123], v[160:163], v[176:179], v[120:123]
	v_mfma_f32_16x16x32_bf16 v[116:119], v[168:171], v[176:179], v[116:119]
	v_mfma_f32_16x16x32_bf16 v[104:107], v[160:163], v[184:187], v[104:107]
	v_mfma_f32_16x16x32_bf16 v[100:103], v[168:171], v[184:187], v[100:103]
	v_mfma_f32_16x16x32_bf16 v[88:91], v[160:163], v[192:195], v[88:91]
	v_mfma_f32_16x16x32_bf16 v[84:87], v[168:171], v[192:195], v[84:87]
	v_mfma_f32_16x16x32_bf16 v[72:75], v[160:163], v[210:213], v[72:75]
	v_mfma_f32_16x16x32_bf16 v[68:71], v[168:171], v[210:213], v[68:71]
	s_setprio 0
	s_barrier
	ds_read_b128 v[172:175], v155 offset:16384
	ds_read_b128 v[176:179], v155 offset:17408
	ds_read_b128 v[180:183], v155 offset:18432
	ds_read_b128 v[184:187], v155 offset:19456
	ds_read_b128 v[188:191], v155 offset:20480
	ds_read_b128 v[192:195], v155 offset:21504
	ds_read_b128 v[206:209], v155 offset:22528
	ds_read_b128 v[210:213], v155 offset:23552
	s_mov_b32 m0, s50
	s_nop 0
	global_load_lds_dwordx4 v2, s[30:31]
	s_mov_b32 m0, s51
	s_nop 0
	global_load_lds_dwordx4 v151, s[30:31]
	s_add_u32 s72, s30, 0x20000
	s_addc_u32 s73, s31, 0
	s_mov_b32 m0, s55
	s_nop 0
	global_load_lds_dwordx4 v2, s[72:73]
	s_mov_b32 m0, s56
	s_nop 0
	global_load_lds_dwordx4 v151, s[72:73]
	s_mov_b32 m0, s1
	s_nop 0
	global_load_lds_dwordx4 v1, s[40:41]
	s_mov_b32 m0, s57
	s_nop 0
	global_load_lds_dwordx4 v150, s[40:41]
	s_waitcnt vmcnt(8)
	s_waitcnt lgkmcnt(0)
	s_barrier
	s_setprio 1
	s_waitcnt lgkmcnt(7)
	v_mfma_f32_16x16x32_bf16 v[64:67], v[132:135], v[172:175], 0
	v_mfma_f32_16x16x32_bf16 v[60:63], v[140:143], v[172:175], 0
	s_waitcnt lgkmcnt(5)
	v_mfma_f32_16x16x32_bf16 v[48:51], v[132:135], v[180:183], 0
	v_mfma_f32_16x16x32_bf16 v[44:47], v[140:143], v[180:183], 0
	s_waitcnt lgkmcnt(3)
	v_mfma_f32_16x16x32_bf16 v[32:35], v[132:135], v[188:191], 0
	v_mfma_f32_16x16x32_bf16 v[28:31], v[140:143], v[188:191], 0
	s_waitcnt lgkmcnt(1)
	v_mfma_f32_16x16x32_bf16 v[16:19], v[132:135], v[206:209], 0
	v_mfma_f32_16x16x32_bf16 v[12:15], v[140:143], v[206:209], 0
	v_mfma_f32_16x16x32_bf16 v[64:67], v[136:139], v[176:179], v[64:67]
	v_mfma_f32_16x16x32_bf16 v[60:63], v[144:147], v[176:179], v[60:63]
	v_mfma_f32_16x16x32_bf16 v[48:51], v[136:139], v[184:187], v[48:51]
	v_mfma_f32_16x16x32_bf16 v[44:47], v[144:147], v[184:187], v[44:47]
	v_mfma_f32_16x16x32_bf16 v[32:35], v[136:139], v[192:195], v[32:35]
	v_mfma_f32_16x16x32_bf16 v[28:31], v[144:147], v[192:195], v[28:31]
	s_waitcnt lgkmcnt(0)
	v_mfma_f32_16x16x32_bf16 v[16:19], v[136:139], v[210:213], v[16:19]
	v_mfma_f32_16x16x32_bf16 v[12:15], v[144:147], v[210:213], v[12:15]
	s_setprio 0
	s_setprio 1
	v_mfma_f32_16x16x32_bf16 v[56:59], v[156:159], v[172:175], 0
	v_mfma_f32_16x16x32_bf16 v[52:55], v[164:167], v[172:175], 0
	v_mfma_f32_16x16x32_bf16 v[40:43], v[156:159], v[180:183], 0
	v_mfma_f32_16x16x32_bf16 v[36:39], v[164:167], v[180:183], 0
	v_mfma_f32_16x16x32_bf16 v[24:27], v[156:159], v[188:191], 0
	v_mfma_f32_16x16x32_bf16 v[20:23], v[164:167], v[188:191], 0
	v_mfma_f32_16x16x32_bf16 v[8:11], v[156:159], v[206:209], 0
	v_mfma_f32_16x16x32_bf16 v[4:7], v[164:167], v[206:209], 0
	v_mfma_f32_16x16x32_bf16 v[56:59], v[160:163], v[176:179], v[56:59]
	v_mfma_f32_16x16x32_bf16 v[52:55], v[168:171], v[176:179], v[52:55]
	v_mfma_f32_16x16x32_bf16 v[40:43], v[160:163], v[184:187], v[40:43]
	v_mfma_f32_16x16x32_bf16 v[36:39], v[168:171], v[184:187], v[36:39]
	v_mfma_f32_16x16x32_bf16 v[24:27], v[160:163], v[192:195], v[24:27]
	v_mfma_f32_16x16x32_bf16 v[20:23], v[168:171], v[192:195], v[20:23]
	v_mfma_f32_16x16x32_bf16 v[8:11], v[160:163], v[210:213], v[8:11]
	v_mfma_f32_16x16x32_bf16 v[4:7], v[168:171], v[210:213], v[4:7]
	s_setprio 0
	s_barrier
	v_add_u32_e32 v144, 0x18000, v154
	v_add_u32_e32 v148, 0x1c000, v154
	ds_read_b128 v[132:135], v144
	ds_read_b128 v[136:139], v144 offset:1024
	ds_read_b128 v[140:143], v144 offset:2048
	ds_read_b128 v[144:147], v144 offset:3072
	ds_read_b128 v[156:159], v148
	ds_read_b128 v[160:163], v148 offset:1024
	ds_read_b128 v[164:167], v148 offset:2048
	ds_read_b128 v[168:171], v148 offset:3072
	ds_read_b128 v[172:175], v155 offset:32768
	ds_read_b128 v[176:179], v155 offset:33792
	ds_read_b128 v[180:183], v155 offset:34816
	ds_read_b128 v[184:187], v155 offset:35840
	ds_read_b128 v[188:191], v155 offset:36864
	ds_read_b128 v[192:195], v155 offset:37888
	ds_read_b128 v[206:209], v155 offset:38912
	ds_read_b128 v[210:213], v155 offset:39936
	s_add_u32 s40, s40, 0x20000
	s_addc_u32 s41, s41, 0
	s_mov_b32 m0, s58
	s_nop 0
	global_load_lds_dwordx4 v1, s[40:41]
	s_mov_b32 m0, s59
	s_nop 0
	global_load_lds_dwordx4 v150, s[40:41]
	s_waitcnt vmcnt(8)
	s_waitcnt lgkmcnt(0)
	s_barrier
	s_setprio 1
	s_waitcnt lgkmcnt(7)
	v_mfma_f32_16x16x32_bf16 v[124:127], v[132:135], v[172:175], v[124:127]
	v_mfma_f32_16x16x32_bf16 v[128:131], v[140:143], v[172:175], v[128:131]
	s_waitcnt lgkmcnt(5)
	v_mfma_f32_16x16x32_bf16 v[112:115], v[132:135], v[180:183], v[112:115]
	v_mfma_f32_16x16x32_bf16 v[108:111], v[140:143], v[180:183], v[108:111]
	s_waitcnt lgkmcnt(3)
	v_mfma_f32_16x16x32_bf16 v[96:99], v[132:135], v[188:191], v[96:99]
	v_mfma_f32_16x16x32_bf16 v[92:95], v[140:143], v[188:191], v[92:95]
	s_waitcnt lgkmcnt(1)
	v_mfma_f32_16x16x32_bf16 v[80:83], v[132:135], v[206:209], v[80:83]
	v_mfma_f32_16x16x32_bf16 v[76:79], v[140:143], v[206:209], v[76:79]
	v_mfma_f32_16x16x32_bf16 v[124:127], v[136:139], v[176:179], v[124:127]
	v_mfma_f32_16x16x32_bf16 v[128:131], v[144:147], v[176:179], v[128:131]
	v_mfma_f32_16x16x32_bf16 v[112:115], v[136:139], v[184:187], v[112:115]
	v_mfma_f32_16x16x32_bf16 v[108:111], v[144:147], v[184:187], v[108:111]
	v_mfma_f32_16x16x32_bf16 v[96:99], v[136:139], v[192:195], v[96:99]
	v_mfma_f32_16x16x32_bf16 v[92:95], v[144:147], v[192:195], v[92:95]
	s_waitcnt lgkmcnt(0)
	v_mfma_f32_16x16x32_bf16 v[80:83], v[136:139], v[210:213], v[80:83]
	v_mfma_f32_16x16x32_bf16 v[76:79], v[144:147], v[210:213], v[76:79]
	s_setprio 0
	s_setprio 1
	v_mfma_f32_16x16x32_bf16 v[120:123], v[156:159], v[172:175], v[120:123]
	v_mfma_f32_16x16x32_bf16 v[116:119], v[164:167], v[172:175], v[116:119]
	v_mfma_f32_16x16x32_bf16 v[104:107], v[156:159], v[180:183], v[104:107]
	v_mfma_f32_16x16x32_bf16 v[100:103], v[164:167], v[180:183], v[100:103]
	v_mfma_f32_16x16x32_bf16 v[88:91], v[156:159], v[188:191], v[88:91]
	v_mfma_f32_16x16x32_bf16 v[84:87], v[164:167], v[188:191], v[84:87]
	v_mfma_f32_16x16x32_bf16 v[72:75], v[156:159], v[206:209], v[72:75]
	v_mfma_f32_16x16x32_bf16 v[68:71], v[164:167], v[206:209], v[68:71]
	v_mfma_f32_16x16x32_bf16 v[120:123], v[160:163], v[176:179], v[120:123]
	v_mfma_f32_16x16x32_bf16 v[116:119], v[168:171], v[176:179], v[116:119]
	v_mfma_f32_16x16x32_bf16 v[104:107], v[160:163], v[184:187], v[104:107]
	v_mfma_f32_16x16x32_bf16 v[100:103], v[168:171], v[184:187], v[100:103]
	v_mfma_f32_16x16x32_bf16 v[88:91], v[160:163], v[192:195], v[88:91]
	v_mfma_f32_16x16x32_bf16 v[84:87], v[168:171], v[192:195], v[84:87]
	v_mfma_f32_16x16x32_bf16 v[72:75], v[160:163], v[210:213], v[72:75]
	v_mfma_f32_16x16x32_bf16 v[68:71], v[168:171], v[210:213], v[68:71]
	s_setprio 0
	s_barrier
	ds_read_b128 v[172:175], v155 offset:49152
	ds_read_b128 v[176:179], v155 offset:50176
	ds_read_b128 v[180:183], v155 offset:51200
	ds_read_b128 v[184:187], v155 offset:52224
	ds_read_b128 v[188:191], v155 offset:53248
	ds_read_b128 v[192:195], v155 offset:54272
	ds_read_b128 v[206:209], v155 offset:55296
	ds_read_b128 v[210:213], v155 offset:56320
	s_add_u32 s40, s30, 0x80
	s_addc_u32 s41, s31, 0
	s_mov_b32 m0, s61
	s_nop 0
	global_load_lds_dwordx4 v2, s[40:41]
	s_add_u32 s30, s30, 0x20080
	s_mov_b32 m0, s62
	s_nop 0
	global_load_lds_dwordx4 v151, s[40:41]
	s_addc_u32 s31, s31, 0
	s_mov_b32 m0, s65
	s_nop 0
	global_load_lds_dwordx4 v2, s[30:31]
	s_mov_b32 m0, s33
	s_nop 0
	global_load_lds_dwordx4 v151, s[30:31]
	s_mov_b32 m0, s63
	s_nop 0
	global_load_lds_dwordx4 v1, s[28:29]
	s_mov_b32 m0, s64
	s_nop 0
	global_load_lds_dwordx4 v150, s[28:29]
	s_waitcnt vmcnt(8)
	s_waitcnt lgkmcnt(0)
	s_barrier
	s_setprio 1
	s_waitcnt lgkmcnt(7)
	v_mfma_f32_16x16x32_bf16 v[64:67], v[132:135], v[172:175], v[64:67]
	v_mfma_f32_16x16x32_bf16 v[60:63], v[140:143], v[172:175], v[60:63]
	s_add_u32 s67, s67, 0x100
	s_waitcnt lgkmcnt(5)
	v_mfma_f32_16x16x32_bf16 v[48:51], v[132:135], v[180:183], v[48:51]
	s_addc_u32 s68, s68, 0
	v_mfma_f32_16x16x32_bf16 v[44:47], v[140:143], v[180:183], v[44:47]
	s_add_u32 s69, s69, 0x100
	s_waitcnt lgkmcnt(3)
	v_mfma_f32_16x16x32_bf16 v[32:35], v[132:135], v[188:191], v[32:35]
	s_addc_u32 s70, s70, 0
	v_mfma_f32_16x16x32_bf16 v[28:31], v[140:143], v[188:191], v[28:31]
	s_mov_b32 s28, s71
	s_waitcnt lgkmcnt(1)
	v_mfma_f32_16x16x32_bf16 v[16:19], v[132:135], v[206:209], v[16:19]
	s_cmp_ge_i32 s71, s60
	v_mfma_f32_16x16x32_bf16 v[12:15], v[140:143], v[206:209], v[12:15]
	v_mfma_f32_16x16x32_bf16 v[64:67], v[136:139], v[176:179], v[64:67]
	v_mfma_f32_16x16x32_bf16 v[60:63], v[144:147], v[176:179], v[60:63]
	v_mfma_f32_16x16x32_bf16 v[48:51], v[136:139], v[184:187], v[48:51]
	v_mfma_f32_16x16x32_bf16 v[44:47], v[144:147], v[184:187], v[44:47]
	v_mfma_f32_16x16x32_bf16 v[32:35], v[136:139], v[192:195], v[32:35]
	v_mfma_f32_16x16x32_bf16 v[28:31], v[144:147], v[192:195], v[28:31]
	s_waitcnt lgkmcnt(0)
	v_mfma_f32_16x16x32_bf16 v[16:19], v[136:139], v[210:213], v[16:19]
	v_mfma_f32_16x16x32_bf16 v[12:15], v[144:147], v[210:213], v[12:15]
	s_setprio 0
	s_setprio 1
	v_mfma_f32_16x16x32_bf16 v[56:59], v[156:159], v[172:175], v[56:59]
	v_mfma_f32_16x16x32_bf16 v[52:55], v[164:167], v[172:175], v[52:55]
	v_mfma_f32_16x16x32_bf16 v[40:43], v[156:159], v[180:183], v[40:43]
	v_mfma_f32_16x16x32_bf16 v[36:39], v[164:167], v[180:183], v[36:39]
	v_mfma_f32_16x16x32_bf16 v[24:27], v[156:159], v[188:191], v[24:27]
	v_mfma_f32_16x16x32_bf16 v[20:23], v[164:167], v[188:191], v[20:23]
	v_mfma_f32_16x16x32_bf16 v[8:11], v[156:159], v[206:209], v[8:11]
	v_mfma_f32_16x16x32_bf16 v[4:7], v[164:167], v[206:209], v[4:7]
	v_mfma_f32_16x16x32_bf16 v[56:59], v[160:163], v[176:179], v[56:59]
	v_mfma_f32_16x16x32_bf16 v[52:55], v[168:171], v[176:179], v[52:55]
	v_mfma_f32_16x16x32_bf16 v[40:43], v[160:163], v[184:187], v[40:43]
	v_mfma_f32_16x16x32_bf16 v[36:39], v[168:171], v[184:187], v[36:39]
	v_mfma_f32_16x16x32_bf16 v[24:27], v[160:163], v[192:195], v[24:27]
	v_mfma_f32_16x16x32_bf16 v[20:23], v[168:171], v[192:195], v[20:23]
	v_mfma_f32_16x16x32_bf16 v[8:11], v[160:163], v[210:213], v[8:11]
	v_mfma_f32_16x16x32_bf16 v[4:7], v[168:171], v[210:213], v[4:7]
	s_setprio 0
	s_barrier
	s_cbranch_scc0 .LBB0_622
	s_branch .LBB0_623

.Lkz_5:
	s_and_b64 s[38:39], s[4:5], exec
	s_cselect_b32 s3, s25, s31
	s_cselect_b32 s21, s24, s30
	s_cselect_b32 s65, s27, s29
	s_cselect_b32 s66, s26, s28
	s_add_u32 s67, s30, 0x100
	s_addc_u32 s68, s31, 0
	s_add_u32 s69, s28, 0x100
	s_addc_u32 s70, s29, 0
	s_add_u32 s28, s30, 0x80080
	s_addc_u32 s29, s31, 0
	s_mov_b32 s30, 0
	v_add_u32_e32 v150, 0x10000, v136
	v_add_u32_e32 v166, 0x14000, v136
	ds_read_b128 v[138:141], v150
	ds_read_b128 v[142:145], v150 offset:1024
	ds_read_b128 v[146:149], v150 offset:2048
	ds_read_b128 v[150:153], v150 offset:3072
	ds_read_b128 v[154:157], v166
	ds_read_b128 v[158:161], v166 offset:1024
	ds_read_b128 v[162:165], v166 offset:2048
	ds_read_b128 v[166:169], v166 offset:3072
	s_add_i32 s71, s30, 2
	s_cmp_eq_u32 s60, s30
	s_cselect_b32 s40, s21, s67
	s_cselect_b32 s41, s3, s68
	s_cselect_b32 s38, s66, s69
	s_cselect_b32 s39, s65, s70
	s_add_u32 s30, s40, 0x80
	s_addc_u32 s31, s41, 0
	ds_read_b128 v[170:173], v137
	ds_read_b128 v[174:177], v137 offset:1024
	ds_read_b128 v[178:181], v137 offset:2048
	ds_read_b128 v[182:185], v137 offset:3072
	ds_read_b128 v[186:189], v137 offset:4096
	ds_read_b128 v[190:193], v137 offset:5120
	ds_read_b128 v[194:197], v137 offset:6144
	ds_read_b128 v[202:205], v137 offset:7168
	s_mov_b32 m0, s61
	s_nop 0
	global_load_lds_dwordx4 v1, s[28:29]
	s_mov_b32 m0, s62
	s_nop 0
	global_load_lds_dwordx4 v132, s[28:29]
	s_waitcnt vmcnt(8)
	s_waitcnt lgkmcnt(0)
	s_barrier
	s_setprio 1
	s_waitcnt lgkmcnt(7)
	v_mfma_f32_16x16x32_bf16 v[124:127], v[138:141], v[170:173], 0
	v_mfma_f32_16x16x32_bf16 v[128:131], v[146:149], v[170:173], 0
	s_waitcnt lgkmcnt(5)
	v_mfma_f32_16x16x32_bf16 v[112:115], v[138:141], v[178:181], 0
	v_mfma_f32_16x16x32_bf16 v[108:111], v[146:149], v[178:181], 0
	s_waitcnt lgkmcnt(3)
	v_mfma_f32_16x16x32_bf16 v[96:99], v[138:141], v[186:189], 0
	v_mfma_f32_16x16x32_bf16 v[92:95], v[146:149], v[186:189], 0
	s_waitcnt lgkmcnt(1)
	v_mfma_f32_16x16x32_bf16 v[80:83], v[138:141], v[194:197], 0
	v_mfma_f32_16x16x32_bf16 v[76:79], v[146:149], v[194:197], 0
	v_mfma_f32_16x16x32_bf16 v[124:127], v[142:145], v[174:177], v[124:127]
	v_mfma_f32_16x16x32_bf16 v[128:131], v[150:153], v[174:177], v[128:131]
	v_mfma_f32_16x16x32_bf16 v[112:115], v[142:145], v[182:185], v[112:115]
	v_mfma_f32_16x16x32_bf16 v[108:111], v[150:153], v[182:185], v[108:111]
	v_mfma_f32_16x16x32_bf16 v[96:99], v[142:145], v[190:193], v[96:99]
	v_mfma_f32_16x16x32_bf16 v[92:95], v[150:153], v[190:193], v[92:95]
	s_waitcnt lgkmcnt(0)
	v_mfma_f32_16x16x32_bf16 v[80:83], v[142:145], v[202:205], v[80:83]
	v_mfma_f32_16x16x32_bf16 v[76:79], v[150:153], v[202:205], v[76:79]
	s_setprio 0
	s_setprio 1
	v_mfma_f32_16x16x32_bf16 v[120:123], v[154:157], v[170:173], 0
	v_mfma_f32_16x16x32_bf16 v[116:119], v[162:165], v[170:173], 0
	v_mfma_f32_16x16x32_bf16 v[104:107], v[154:157], v[178:181], 0
	v_mfma_f32_16x16x32_bf16 v[100:103], v[162:165], v[178:181], 0
	v_mfma_f32_16x16x32_bf16 v[88:91], v[154:157], v[186:189], 0
	v_mfma_f32_16x16x32_bf16 v[84:87], v[162:165], v[186:189], 0
	v_mfma_f32_16x16x32_bf16 v[72:75], v[154:157], v[194:197], 0
	v_mfma_f32_16x16x32_bf16 v[68:71], v[162:165], v[194:197], 0
	v_mfma_f32_16x16x32_bf16 v[120:123], v[158:161], v[174:177], v[120:123]
	v_mfma_f32_16x16x32_bf16 v[116:119], v[166:169], v[174:177], v[116:119]
	v_mfma_f32_16x16x32_bf16 v[104:107], v[158:161], v[182:185], v[104:107]
	v_mfma_f32_16x16x32_bf16 v[100:103], v[166:169], v[182:185], v[100:103]
	v_mfma_f32_16x16x32_bf16 v[88:91], v[158:161], v[190:193], v[88:91]
	v_mfma_f32_16x16x32_bf16 v[84:87], v[166:169], v[190:193], v[84:87]
	v_mfma_f32_16x16x32_bf16 v[72:75], v[158:161], v[202:205], v[72:75]
	v_mfma_f32_16x16x32_bf16 v[68:71], v[166:169], v[202:205], v[68:71]
	s_setprio 0
	s_barrier
	ds_read_b128 v[170:173], v137 offset:16384
	ds_read_b128 v[174:177], v137 offset:17408
	ds_read_b128 v[178:181], v137 offset:18432
	ds_read_b128 v[182:185], v137 offset:19456
	ds_read_b128 v[186:189], v137 offset:20480
	ds_read_b128 v[190:193], v137 offset:21504
	ds_read_b128 v[194:197], v137 offset:22528
	ds_read_b128 v[202:205], v137 offset:23552
	s_mov_b32 m0, s23
	s_nop 0
	global_load_lds_dwordx4 v2, s[38:39]
	s_mov_b32 m0, s42
	s_nop 0
	global_load_lds_dwordx4 v133, s[38:39]
	s_add_u32 s72, s38, 0x20000
	s_addc_u32 s73, s39, 0
	s_mov_b32 m0, s43
	s_nop 0
	global_load_lds_dwordx4 v2, s[72:73]
	s_mov_b32 m0, s48
	s_nop 0
	global_load_lds_dwordx4 v133, s[72:73]
	s_mov_b32 m0, s35
	s_nop 0
	global_load_lds_dwordx4 v1, s[40:41]
	s_mov_b32 m0, s49
	s_nop 0
	global_load_lds_dwordx4 v132, s[40:41]
	s_waitcnt vmcnt(8)
	s_waitcnt lgkmcnt(0)
	s_barrier
	s_setprio 1
	s_waitcnt lgkmcnt(7)
	v_mfma_f32_16x16x32_bf16 v[64:67], v[138:141], v[170:173], 0
	v_mfma_f32_16x16x32_bf16 v[60:63], v[146:149], v[170:173], 0
	s_waitcnt lgkmcnt(5)
	v_mfma_f32_16x16x32_bf16 v[48:51], v[138:141], v[178:181], 0
	v_mfma_f32_16x16x32_bf16 v[44:47], v[146:149], v[178:181], 0
	s_waitcnt lgkmcnt(3)
	v_mfma_f32_16x16x32_bf16 v[32:35], v[138:141], v[186:189], 0
	v_mfma_f32_16x16x32_bf16 v[28:31], v[146:149], v[186:189], 0
	s_waitcnt lgkmcnt(1)
	v_mfma_f32_16x16x32_bf16 v[16:19], v[138:141], v[194:197], 0
	v_mfma_f32_16x16x32_bf16 v[12:15], v[146:149], v[194:197], 0
	v_mfma_f32_16x16x32_bf16 v[64:67], v[142:145], v[174:177], v[64:67]
	v_mfma_f32_16x16x32_bf16 v[60:63], v[150:153], v[174:177], v[60:63]
	v_mfma_f32_16x16x32_bf16 v[48:51], v[142:145], v[182:185], v[48:51]
	v_mfma_f32_16x16x32_bf16 v[44:47], v[150:153], v[182:185], v[44:47]
	v_mfma_f32_16x16x32_bf16 v[32:35], v[142:145], v[190:193], v[32:35]
	v_mfma_f32_16x16x32_bf16 v[28:31], v[150:153], v[190:193], v[28:31]
	s_waitcnt lgkmcnt(0)
	v_mfma_f32_16x16x32_bf16 v[16:19], v[142:145], v[202:205], v[16:19]
	v_mfma_f32_16x16x32_bf16 v[12:15], v[150:153], v[202:205], v[12:15]
	s_setprio 0
	s_setprio 1
	v_mfma_f32_16x16x32_bf16 v[56:59], v[154:157], v[170:173], 0
	v_mfma_f32_16x16x32_bf16 v[52:55], v[162:165], v[170:173], 0
	v_mfma_f32_16x16x32_bf16 v[40:43], v[154:157], v[178:181], 0
	v_mfma_f32_16x16x32_bf16 v[36:39], v[162:165], v[178:181], 0
	v_mfma_f32_16x16x32_bf16 v[24:27], v[154:157], v[186:189], 0
	v_mfma_f32_16x16x32_bf16 v[20:23], v[162:165], v[186:189], 0
	v_mfma_f32_16x16x32_bf16 v[8:11], v[154:157], v[194:197], 0
	v_mfma_f32_16x16x32_bf16 v[4:7], v[162:165], v[194:197], 0
	v_mfma_f32_16x16x32_bf16 v[56:59], v[158:161], v[174:177], v[56:59]
	v_mfma_f32_16x16x32_bf16 v[52:55], v[166:169], v[174:177], v[52:55]
	v_mfma_f32_16x16x32_bf16 v[40:43], v[158:161], v[182:185], v[40:43]
	v_mfma_f32_16x16x32_bf16 v[36:39], v[166:169], v[182:185], v[36:39]
	v_mfma_f32_16x16x32_bf16 v[24:27], v[158:161], v[190:193], v[24:27]
	v_mfma_f32_16x16x32_bf16 v[20:23], v[166:169], v[190:193], v[20:23]
	v_mfma_f32_16x16x32_bf16 v[8:11], v[158:161], v[202:205], v[8:11]
	v_mfma_f32_16x16x32_bf16 v[4:7], v[166:169], v[202:205], v[4:7]
	s_setprio 0
	s_barrier
	v_add_u32_e32 v150, 0x18000, v136
	v_add_u32_e32 v166, 0x1c000, v136
	ds_read_b128 v[138:141], v150
	ds_read_b128 v[142:145], v150 offset:1024
	ds_read_b128 v[146:149], v150 offset:2048
	ds_read_b128 v[150:153], v150 offset:3072
	ds_read_b128 v[154:157], v166
	ds_read_b128 v[158:161], v166 offset:1024
	ds_read_b128 v[162:165], v166 offset:2048
	ds_read_b128 v[166:169], v166 offset:3072
	ds_read_b128 v[170:173], v137 offset:32768
	ds_read_b128 v[174:177], v137 offset:33792
	ds_read_b128 v[178:181], v137 offset:34816
	ds_read_b128 v[182:185], v137 offset:35840
	ds_read_b128 v[186:189], v137 offset:36864
	ds_read_b128 v[190:193], v137 offset:37888
	ds_read_b128 v[194:197], v137 offset:38912
	ds_read_b128 v[202:205], v137 offset:39936
	s_add_u32 s40, s40, 0x80000
	s_addc_u32 s41, s41, 0
	s_mov_b32 m0, s50
	s_nop 0
	global_load_lds_dwordx4 v1, s[40:41]
	s_mov_b32 m0, s51
	s_nop 0
	global_load_lds_dwordx4 v132, s[40:41]
	s_waitcnt vmcnt(8)
	s_waitcnt lgkmcnt(0)
	s_barrier
	s_setprio 1
	s_waitcnt lgkmcnt(7)
	v_mfma_f32_16x16x32_bf16 v[124:127], v[138:141], v[170:173], v[124:127]
	v_mfma_f32_16x16x32_bf16 v[128:131], v[146:149], v[170:173], v[128:131]
	s_waitcnt lgkmcnt(5)
	v_mfma_f32_16x16x32_bf16 v[112:115], v[138:141], v[178:181], v[112:115]
	v_mfma_f32_16x16x32_bf16 v[108:111], v[146:149], v[178:181], v[108:111]
	s_waitcnt lgkmcnt(3)
	v_mfma_f32_16x16x32_bf16 v[96:99], v[138:141], v[186:189], v[96:99]
	v_mfma_f32_16x16x32_bf16 v[92:95], v[146:149], v[186:189], v[92:95]
	s_waitcnt lgkmcnt(1)
	v_mfma_f32_16x16x32_bf16 v[80:83], v[138:141], v[194:197], v[80:83]
	v_mfma_f32_16x16x32_bf16 v[76:79], v[146:149], v[194:197], v[76:79]
	v_mfma_f32_16x16x32_bf16 v[124:127], v[142:145], v[174:177], v[124:127]
	v_mfma_f32_16x16x32_bf16 v[128:131], v[150:153], v[174:177], v[128:131]
	v_mfma_f32_16x16x32_bf16 v[112:115], v[142:145], v[182:185], v[112:115]
	v_mfma_f32_16x16x32_bf16 v[108:111], v[150:153], v[182:185], v[108:111]
	v_mfma_f32_16x16x32_bf16 v[96:99], v[142:145], v[190:193], v[96:99]
	v_mfma_f32_16x16x32_bf16 v[92:95], v[150:153], v[190:193], v[92:95]
	s_waitcnt lgkmcnt(0)
	v_mfma_f32_16x16x32_bf16 v[80:83], v[142:145], v[202:205], v[80:83]
	v_mfma_f32_16x16x32_bf16 v[76:79], v[150:153], v[202:205], v[76:79]
	s_setprio 0
	s_setprio 1
	v_mfma_f32_16x16x32_bf16 v[120:123], v[154:157], v[170:173], v[120:123]
	v_mfma_f32_16x16x32_bf16 v[116:119], v[162:165], v[170:173], v[116:119]
	v_mfma_f32_16x16x32_bf16 v[104:107], v[154:157], v[178:181], v[104:107]
	v_mfma_f32_16x16x32_bf16 v[100:103], v[162:165], v[178:181], v[100:103]
	v_mfma_f32_16x16x32_bf16 v[88:91], v[154:157], v[186:189], v[88:91]
	v_mfma_f32_16x16x32_bf16 v[84:87], v[162:165], v[186:189], v[84:87]
	v_mfma_f32_16x16x32_bf16 v[72:75], v[154:157], v[194:197], v[72:75]
	v_mfma_f32_16x16x32_bf16 v[68:71], v[162:165], v[194:197], v[68:71]
	v_mfma_f32_16x16x32_bf16 v[120:123], v[158:161], v[174:177], v[120:123]
	v_mfma_f32_16x16x32_bf16 v[116:119], v[166:169], v[174:177], v[116:119]
	v_mfma_f32_16x16x32_bf16 v[104:107], v[158:161], v[182:185], v[104:107]
	v_mfma_f32_16x16x32_bf16 v[100:103], v[166:169], v[182:185], v[100:103]
	v_mfma_f32_16x16x32_bf16 v[88:91], v[158:161], v[190:193], v[88:91]
	v_mfma_f32_16x16x32_bf16 v[84:87], v[166:169], v[190:193], v[84:87]
	v_mfma_f32_16x16x32_bf16 v[72:75], v[158:161], v[202:205], v[72:75]
	v_mfma_f32_16x16x32_bf16 v[68:71], v[166:169], v[202:205], v[68:71]
	s_setprio 0
	s_barrier
	ds_read_b128 v[170:173], v137 offset:49152
	ds_read_b128 v[174:177], v137 offset:50176
	ds_read_b128 v[178:181], v137 offset:51200
	ds_read_b128 v[182:185], v137 offset:52224
	ds_read_b128 v[186:189], v137 offset:53248
	ds_read_b128 v[190:193], v137 offset:54272
	ds_read_b128 v[194:197], v137 offset:55296
	ds_read_b128 v[202:205], v137 offset:56320
	s_add_u32 s40, s38, 0x80
	s_addc_u32 s41, s39, 0
	s_mov_b32 m0, s54
	s_nop 0
	global_load_lds_dwordx4 v2, s[40:41]
	s_add_u32 s38, s38, 0x20080
	s_mov_b32 m0, s55
	s_nop 0
	global_load_lds_dwordx4 v133, s[40:41]
	s_addc_u32 s39, s39, 0
	s_mov_b32 m0, s58
	s_nop 0
	global_load_lds_dwordx4 v2, s[38:39]
	s_mov_b32 m0, s59
	s_nop 0
	global_load_lds_dwordx4 v133, s[38:39]
	s_mov_b32 m0, s56
	s_nop 0
	global_load_lds_dwordx4 v1, s[30:31]
	s_mov_b32 m0, s57
	s_nop 0
	global_load_lds_dwordx4 v132, s[30:31]
	s_waitcnt vmcnt(8)
	s_waitcnt lgkmcnt(0)
	s_barrier
	s_setprio 1
	s_waitcnt lgkmcnt(7)
	v_mfma_f32_16x16x32_bf16 v[64:67], v[138:141], v[170:173], v[64:67]
	v_mfma_f32_16x16x32_bf16 v[60:63], v[146:149], v[170:173], v[60:63]
	s_add_u32 s67, s67, 0x100
	s_waitcnt lgkmcnt(5)
	v_mfma_f32_16x16x32_bf16 v[48:51], v[138:141], v[178:181], v[48:51]
	s_addc_u32 s68, s68, 0
	v_mfma_f32_16x16x32_bf16 v[44:47], v[146:149], v[178:181], v[44:47]
	s_add_u32 s69, s69, 0x100
	s_waitcnt lgkmcnt(3)
	v_mfma_f32_16x16x32_bf16 v[32:35], v[138:141], v[186:189], v[32:35]
	s_addc_u32 s70, s70, 0
	v_mfma_f32_16x16x32_bf16 v[28:31], v[146:149], v[186:189], v[28:31]
	s_add_u32 s28, s28, 0x100
	s_waitcnt lgkmcnt(1)
	v_mfma_f32_16x16x32_bf16 v[16:19], v[138:141], v[194:197], v[16:19]
	s_addc_u32 s29, s29, 0
	v_mfma_f32_16x16x32_bf16 v[12:15], v[146:149], v[194:197], v[12:15]
	s_mov_b32 s30, s71
	v_mfma_f32_16x16x32_bf16 v[64:67], v[142:145], v[174:177], v[64:67]
	s_cmp_ge_i32 s71, s53
	v_mfma_f32_16x16x32_bf16 v[60:63], v[150:153], v[174:177], v[60:63]
	v_mfma_f32_16x16x32_bf16 v[48:51], v[142:145], v[182:185], v[48:51]
	v_mfma_f32_16x16x32_bf16 v[44:47], v[150:153], v[182:185], v[44:47]
	v_mfma_f32_16x16x32_bf16 v[32:35], v[142:145], v[190:193], v[32:35]
	v_mfma_f32_16x16x32_bf16 v[28:31], v[150:153], v[190:193], v[28:31]
	s_waitcnt lgkmcnt(0)
	v_mfma_f32_16x16x32_bf16 v[16:19], v[142:145], v[202:205], v[16:19]
	v_mfma_f32_16x16x32_bf16 v[12:15], v[150:153], v[202:205], v[12:15]
	s_setprio 0
	s_setprio 1
	v_mfma_f32_16x16x32_bf16 v[56:59], v[154:157], v[170:173], v[56:59]
	v_mfma_f32_16x16x32_bf16 v[52:55], v[162:165], v[170:173], v[52:55]
	v_mfma_f32_16x16x32_bf16 v[40:43], v[154:157], v[178:181], v[40:43]
	v_mfma_f32_16x16x32_bf16 v[36:39], v[162:165], v[178:181], v[36:39]
	v_mfma_f32_16x16x32_bf16 v[24:27], v[154:157], v[186:189], v[24:27]
	v_mfma_f32_16x16x32_bf16 v[20:23], v[162:165], v[186:189], v[20:23]
	v_mfma_f32_16x16x32_bf16 v[8:11], v[154:157], v[194:197], v[8:11]
	v_mfma_f32_16x16x32_bf16 v[4:7], v[162:165], v[194:197], v[4:7]
	v_mfma_f32_16x16x32_bf16 v[56:59], v[158:161], v[174:177], v[56:59]
	v_mfma_f32_16x16x32_bf16 v[52:55], v[166:169], v[174:177], v[52:55]
	v_mfma_f32_16x16x32_bf16 v[40:43], v[158:161], v[182:185], v[40:43]
	v_mfma_f32_16x16x32_bf16 v[36:39], v[166:169], v[182:185], v[36:39]
	v_mfma_f32_16x16x32_bf16 v[24:27], v[158:161], v[190:193], v[24:27]
	v_mfma_f32_16x16x32_bf16 v[20:23], v[166:169], v[190:193], v[20:23]
	v_mfma_f32_16x16x32_bf16 v[8:11], v[158:161], v[202:205], v[8:11]
	v_mfma_f32_16x16x32_bf16 v[4:7], v[166:169], v[202:205], v[4:7]
	s_setprio 0
	s_barrier
	s_cbranch_scc0 .LBB0_1096
	s_branch .LBB0_1097
.LBB0_1096:
	v_add_u32_e32 v150, 0x10000, v136
	v_add_u32_e32 v166, 0x14000, v136
	ds_read_b128 v[138:141], v150
	ds_read_b128 v[142:145], v150 offset:1024
	ds_read_b128 v[146:149], v150 offset:2048
	ds_read_b128 v[150:153], v150 offset:3072
	ds_read_b128 v[154:157], v166
	ds_read_b128 v[158:161], v166 offset:1024
	ds_read_b128 v[162:165], v166 offset:2048
	ds_read_b128 v[166:169], v166 offset:3072
	s_add_i32 s71, s30, 2
	s_cmp_eq_u32 s60, s30
	s_cselect_b32 s40, s21, s67
	s_cselect_b32 s41, s3, s68
	s_cselect_b32 s38, s66, s69
	s_cselect_b32 s39, s65, s70
	s_add_u32 s30, s40, 0x80
	s_addc_u32 s31, s41, 0
	ds_read_b128 v[170:173], v137
	ds_read_b128 v[174:177], v137 offset:1024
	ds_read_b128 v[178:181], v137 offset:2048
	ds_read_b128 v[182:185], v137 offset:3072
	ds_read_b128 v[186:189], v137 offset:4096
	ds_read_b128 v[190:193], v137 offset:5120
	ds_read_b128 v[194:197], v137 offset:6144
	ds_read_b128 v[202:205], v137 offset:7168
	s_mov_b32 m0, s61
	s_nop 0
	global_load_lds_dwordx4 v1, s[28:29]
	s_mov_b32 m0, s62
	s_nop 0
	global_load_lds_dwordx4 v132, s[28:29]
	s_waitcnt vmcnt(8)
	s_waitcnt lgkmcnt(0)
	s_barrier
	s_setprio 1
	s_waitcnt lgkmcnt(7)
	v_mfma_f32_16x16x32_bf16 v[124:127], v[138:141], v[170:173], v[124:127]
	v_mfma_f32_16x16x32_bf16 v[128:131], v[146:149], v[170:173], v[128:131]
	s_waitcnt lgkmcnt(5)
	v_mfma_f32_16x16x32_bf16 v[112:115], v[138:141], v[178:181], v[112:115]
	v_mfma_f32_16x16x32_bf16 v[108:111], v[146:149], v[178:181], v[108:111]
	s_waitcnt lgkmcnt(3)
	v_mfma_f32_16x16x32_bf16 v[96:99], v[138:141], v[186:189], v[96:99]
	v_mfma_f32_16x16x32_bf16 v[92:95], v[146:149], v[186:189], v[92:95]
	s_waitcnt lgkmcnt(1)
	v_mfma_f32_16x16x32_bf16 v[80:83], v[138:141], v[194:197], v[80:83]
	v_mfma_f32_16x16x32_bf16 v[76:79], v[146:149], v[194:197], v[76:79]
	v_mfma_f32_16x16x32_bf16 v[124:127], v[142:145], v[174:177], v[124:127]
	v_mfma_f32_16x16x32_bf16 v[128:131], v[150:153], v[174:177], v[128:131]
	v_mfma_f32_16x16x32_bf16 v[112:115], v[142:145], v[182:185], v[112:115]
	v_mfma_f32_16x16x32_bf16 v[108:111], v[150:153], v[182:185], v[108:111]
	v_mfma_f32_16x16x32_bf16 v[96:99], v[142:145], v[190:193], v[96:99]
	v_mfma_f32_16x16x32_bf16 v[92:95], v[150:153], v[190:193], v[92:95]
	s_waitcnt lgkmcnt(0)
	v_mfma_f32_16x16x32_bf16 v[80:83], v[142:145], v[202:205], v[80:83]
	v_mfma_f32_16x16x32_bf16 v[76:79], v[150:153], v[202:205], v[76:79]
	s_setprio 0
	s_setprio 1
	v_mfma_f32_16x16x32_bf16 v[120:123], v[154:157], v[170:173], v[120:123]
	v_mfma_f32_16x16x32_bf16 v[116:119], v[162:165], v[170:173], v[116:119]
	v_mfma_f32_16x16x32_bf16 v[104:107], v[154:157], v[178:181], v[104:107]
	v_mfma_f32_16x16x32_bf16 v[100:103], v[162:165], v[178:181], v[100:103]
	v_mfma_f32_16x16x32_bf16 v[88:91], v[154:157], v[186:189], v[88:91]
	v_mfma_f32_16x16x32_bf16 v[84:87], v[162:165], v[186:189], v[84:87]
	v_mfma_f32_16x16x32_bf16 v[72:75], v[154:157], v[194:197], v[72:75]
	v_mfma_f32_16x16x32_bf16 v[68:71], v[162:165], v[194:197], v[68:71]
	v_mfma_f32_16x16x32_bf16 v[120:123], v[158:161], v[174:177], v[120:123]
	v_mfma_f32_16x16x32_bf16 v[116:119], v[166:169], v[174:177], v[116:119]
	v_mfma_f32_16x16x32_bf16 v[104:107], v[158:161], v[182:185], v[104:107]
	v_mfma_f32_16x16x32_bf16 v[100:103], v[166:169], v[182:185], v[100:103]
	v_mfma_f32_16x16x32_bf16 v[88:91], v[158:161], v[190:193], v[88:91]
	v_mfma_f32_16x16x32_bf16 v[84:87], v[166:169], v[190:193], v[84:87]
	v_mfma_f32_16x16x32_bf16 v[72:75], v[158:161], v[202:205], v[72:75]
	v_mfma_f32_16x16x32_bf16 v[68:71], v[166:169], v[202:205], v[68:71]
	s_setprio 0
	s_barrier
	ds_read_b128 v[170:173], v137 offset:16384
	ds_read_b128 v[174:177], v137 offset:17408
	ds_read_b128 v[178:181], v137 offset:18432
	ds_read_b128 v[182:185], v137 offset:19456
	ds_read_b128 v[186:189], v137 offset:20480
	ds_read_b128 v[190:193], v137 offset:21504
	ds_read_b128 v[194:197], v137 offset:22528
	ds_read_b128 v[202:205], v137 offset:23552
	s_mov_b32 m0, s23
	s_nop 0
	global_load_lds_dwordx4 v2, s[38:39]
	s_mov_b32 m0, s42
	s_nop 0
	global_load_lds_dwordx4 v133, s[38:39]
	s_add_u32 s72, s38, 0x20000
	s_addc_u32 s73, s39, 0
	s_mov_b32 m0, s43
	s_nop 0
	global_load_lds_dwordx4 v2, s[72:73]
	s_mov_b32 m0, s48
	s_nop 0
	global_load_lds_dwordx4 v133, s[72:73]
	s_mov_b32 m0, s35
	s_nop 0
	global_load_lds_dwordx4 v1, s[40:41]
	s_mov_b32 m0, s49
	s_nop 0
	global_load_lds_dwordx4 v132, s[40:41]
	s_waitcnt vmcnt(8)
	s_waitcnt lgkmcnt(0)
	s_barrier
	s_setprio 1
	s_waitcnt lgkmcnt(7)
	v_mfma_f32_16x16x32_bf16 v[64:67], v[138:141], v[170:173], v[64:67]
	v_mfma_f32_16x16x32_bf16 v[60:63], v[146:149], v[170:173], v[60:63]
	s_waitcnt lgkmcnt(5)
	v_mfma_f32_16x16x32_bf16 v[48:51], v[138:141], v[178:181], v[48:51]
	v_mfma_f32_16x16x32_bf16 v[44:47], v[146:149], v[178:181], v[44:47]
	s_waitcnt lgkmcnt(3)
	v_mfma_f32_16x16x32_bf16 v[32:35], v[138:141], v[186:189], v[32:35]
	v_mfma_f32_16x16x32_bf16 v[28:31], v[146:149], v[186:189], v[28:31]
	s_waitcnt lgkmcnt(1)
	v_mfma_f32_16x16x32_bf16 v[16:19], v[138:141], v[194:197], v[16:19]
	v_mfma_f32_16x16x32_bf16 v[12:15], v[146:149], v[194:197], v[12:15]
	v_mfma_f32_16x16x32_bf16 v[64:67], v[142:145], v[174:177], v[64:67]
	v_mfma_f32_16x16x32_bf16 v[60:63], v[150:153], v[174:177], v[60:63]
	v_mfma_f32_16x16x32_bf16 v[48:51], v[142:145], v[182:185], v[48:51]
	v_mfma_f32_16x16x32_bf16 v[44:47], v[150:153], v[182:185], v[44:47]
	v_mfma_f32_16x16x32_bf16 v[32:35], v[142:145], v[190:193], v[32:35]
	v_mfma_f32_16x16x32_bf16 v[28:31], v[150:153], v[190:193], v[28:31]
	s_waitcnt lgkmcnt(0)
	v_mfma_f32_16x16x32_bf16 v[16:19], v[142:145], v[202:205], v[16:19]
	v_mfma_f32_16x16x32_bf16 v[12:15], v[150:153], v[202:205], v[12:15]
	s_setprio 0
	s_setprio 1
	v_mfma_f32_16x16x32_bf16 v[56:59], v[154:157], v[170:173], v[56:59]
	v_mfma_f32_16x16x32_bf16 v[52:55], v[162:165], v[170:173], v[52:55]
	v_mfma_f32_16x16x32_bf16 v[40:43], v[154:157], v[178:181], v[40:43]
	v_mfma_f32_16x16x32_bf16 v[36:39], v[162:165], v[178:181], v[36:39]
	v_mfma_f32_16x16x32_bf16 v[24:27], v[154:157], v[186:189], v[24:27]
	v_mfma_f32_16x16x32_bf16 v[20:23], v[162:165], v[186:189], v[20:23]
	v_mfma_f32_16x16x32_bf16 v[8:11], v[154:157], v[194:197], v[8:11]
	v_mfma_f32_16x16x32_bf16 v[4:7], v[162:165], v[194:197], v[4:7]
	v_mfma_f32_16x16x32_bf16 v[56:59], v[158:161], v[174:177], v[56:59]
	v_mfma_f32_16x16x32_bf16 v[52:55], v[166:169], v[174:177], v[52:55]
	v_mfma_f32_16x16x32_bf16 v[40:43], v[158:161], v[182:185], v[40:43]
	v_mfma_f32_16x16x32_bf16 v[36:39], v[166:169], v[182:185], v[36:39]
	v_mfma_f32_16x16x32_bf16 v[24:27], v[158:161], v[190:193], v[24:27]
	v_mfma_f32_16x16x32_bf16 v[20:23], v[166:169], v[190:193], v[20:23]
	v_mfma_f32_16x16x32_bf16 v[8:11], v[158:161], v[202:205], v[8:11]
	v_mfma_f32_16x16x32_bf16 v[4:7], v[166:169], v[202:205], v[4:7]
	s_setprio 0
	s_barrier
	v_add_u32_e32 v150, 0x18000, v136
	v_add_u32_e32 v166, 0x1c000, v136
	ds_read_b128 v[138:141], v150
	ds_read_b128 v[142:145], v150 offset:1024
	ds_read_b128 v[146:149], v150 offset:2048
	ds_read_b128 v[150:153], v150 offset:3072
	ds_read_b128 v[154:157], v166
	ds_read_b128 v[158:161], v166 offset:1024
	ds_read_b128 v[162:165], v166 offset:2048
	ds_read_b128 v[166:169], v166 offset:3072
	ds_read_b128 v[170:173], v137 offset:32768
	ds_read_b128 v[174:177], v137 offset:33792
	ds_read_b128 v[178:181], v137 offset:34816
	ds_read_b128 v[182:185], v137 offset:35840
	ds_read_b128 v[186:189], v137 offset:36864
	ds_read_b128 v[190:193], v137 offset:37888
	ds_read_b128 v[194:197], v137 offset:38912
	ds_read_b128 v[202:205], v137 offset:39936
	s_add_u32 s40, s40, 0x80000
	s_addc_u32 s41, s41, 0
	s_mov_b32 m0, s50
	s_nop 0
	global_load_lds_dwordx4 v1, s[40:41]
	s_mov_b32 m0, s51
	s_nop 0
	global_load_lds_dwordx4 v132, s[40:41]
	s_waitcnt vmcnt(8)
	s_waitcnt lgkmcnt(0)
	s_barrier
	s_setprio 1
	s_waitcnt lgkmcnt(7)
	v_mfma_f32_16x16x32_bf16 v[124:127], v[138:141], v[170:173], v[124:127]
	v_mfma_f32_16x16x32_bf16 v[128:131], v[146:149], v[170:173], v[128:131]
	s_waitcnt lgkmcnt(5)
	v_mfma_f32_16x16x32_bf16 v[112:115], v[138:141], v[178:181], v[112:115]
	v_mfma_f32_16x16x32_bf16 v[108:111], v[146:149], v[178:181], v[108:111]
	s_waitcnt lgkmcnt(3)
	v_mfma_f32_16x16x32_bf16 v[96:99], v[138:141], v[186:189], v[96:99]
	v_mfma_f32_16x16x32_bf16 v[92:95], v[146:149], v[186:189], v[92:95]
	s_waitcnt lgkmcnt(1)
	v_mfma_f32_16x16x32_bf16 v[80:83], v[138:141], v[194:197], v[80:83]
	v_mfma_f32_16x16x32_bf16 v[76:79], v[146:149], v[194:197], v[76:79]
	v_mfma_f32_16x16x32_bf16 v[124:127], v[142:145], v[174:177], v[124:127]
	v_mfma_f32_16x16x32_bf16 v[128:131], v[150:153], v[174:177], v[128:131]
	v_mfma_f32_16x16x32_bf16 v[112:115], v[142:145], v[182:185], v[112:115]
	v_mfma_f32_16x16x32_bf16 v[108:111], v[150:153], v[182:185], v[108:111]
	v_mfma_f32_16x16x32_bf16 v[96:99], v[142:145], v[190:193], v[96:99]
	v_mfma_f32_16x16x32_bf16 v[92:95], v[150:153], v[190:193], v[92:95]
	s_waitcnt lgkmcnt(0)
	v_mfma_f32_16x16x32_bf16 v[80:83], v[142:145], v[202:205], v[80:83]
	v_mfma_f32_16x16x32_bf16 v[76:79], v[150:153], v[202:205], v[76:79]
	s_setprio 0
	s_setprio 1
	v_mfma_f32_16x16x32_bf16 v[120:123], v[154:157], v[170:173], v[120:123]
	v_mfma_f32_16x16x32_bf16 v[116:119], v[162:165], v[170:173], v[116:119]
	v_mfma_f32_16x16x32_bf16 v[104:107], v[154:157], v[178:181], v[104:107]
	v_mfma_f32_16x16x32_bf16 v[100:103], v[162:165], v[178:181], v[100:103]
	v_mfma_f32_16x16x32_bf16 v[88:91], v[154:157], v[186:189], v[88:91]
	v_mfma_f32_16x16x32_bf16 v[84:87], v[162:165], v[186:189], v[84:87]
	v_mfma_f32_16x16x32_bf16 v[72:75], v[154:157], v[194:197], v[72:75]
	v_mfma_f32_16x16x32_bf16 v[68:71], v[162:165], v[194:197], v[68:71]
	v_mfma_f32_16x16x32_bf16 v[120:123], v[158:161], v[174:177], v[120:123]
	v_mfma_f32_16x16x32_bf16 v[116:119], v[166:169], v[174:177], v[116:119]
	v_mfma_f32_16x16x32_bf16 v[104:107], v[158:161], v[182:185], v[104:107]
	v_mfma_f32_16x16x32_bf16 v[100:103], v[166:169], v[182:185], v[100:103]
	v_mfma_f32_16x16x32_bf16 v[88:91], v[158:161], v[190:193], v[88:91]
	v_mfma_f32_16x16x32_bf16 v[84:87], v[166:169], v[190:193], v[84:87]
	v_mfma_f32_16x16x32_bf16 v[72:75], v[158:161], v[202:205], v[72:75]
	v_mfma_f32_16x16x32_bf16 v[68:71], v[166:169], v[202:205], v[68:71]
	s_setprio 0
	s_barrier
	ds_read_b128 v[170:173], v137 offset:49152
	ds_read_b128 v[174:177], v137 offset:50176
	ds_read_b128 v[178:181], v137 offset:51200
	ds_read_b128 v[182:185], v137 offset:52224
	ds_read_b128 v[186:189], v137 offset:53248
	ds_read_b128 v[190:193], v137 offset:54272
	ds_read_b128 v[194:197], v137 offset:55296
	ds_read_b128 v[202:205], v137 offset:56320
	s_add_u32 s40, s38, 0x80
	s_addc_u32 s41, s39, 0
	s_mov_b32 m0, s54
	s_nop 0
	global_load_lds_dwordx4 v2, s[40:41]
	s_add_u32 s38, s38, 0x20080
	s_mov_b32 m0, s55
	s_nop 0
	global_load_lds_dwordx4 v133, s[40:41]
	s_addc_u32 s39, s39, 0
	s_mov_b32 m0, s58
	s_nop 0
	global_load_lds_dwordx4 v2, s[38:39]
	s_mov_b32 m0, s59
	s_nop 0
	global_load_lds_dwordx4 v133, s[38:39]
	s_mov_b32 m0, s56
	s_nop 0
	global_load_lds_dwordx4 v1, s[30:31]
	s_mov_b32 m0, s57
	s_nop 0
	global_load_lds_dwordx4 v132, s[30:31]
	s_waitcnt vmcnt(8)
	s_waitcnt lgkmcnt(0)
	s_barrier
	s_setprio 1
	s_waitcnt lgkmcnt(7)
	v_mfma_f32_16x16x32_bf16 v[64:67], v[138:141], v[170:173], v[64:67]
	v_mfma_f32_16x16x32_bf16 v[60:63], v[146:149], v[170:173], v[60:63]
	s_add_u32 s67, s67, 0x100
	s_waitcnt lgkmcnt(5)
	v_mfma_f32_16x16x32_bf16 v[48:51], v[138:141], v[178:181], v[48:51]
	s_addc_u32 s68, s68, 0
	v_mfma_f32_16x16x32_bf16 v[44:47], v[146:149], v[178:181], v[44:47]
	s_add_u32 s69, s69, 0x100
	s_waitcnt lgkmcnt(3)
	v_mfma_f32_16x16x32_bf16 v[32:35], v[138:141], v[186:189], v[32:35]
	s_addc_u32 s70, s70, 0
	v_mfma_f32_16x16x32_bf16 v[28:31], v[146:149], v[186:189], v[28:31]
	s_add_u32 s28, s28, 0x100
	s_waitcnt lgkmcnt(1)
	v_mfma_f32_16x16x32_bf16 v[16:19], v[138:141], v[194:197], v[16:19]
	s_addc_u32 s29, s29, 0
	v_mfma_f32_16x16x32_bf16 v[12:15], v[146:149], v[194:197], v[12:15]
	s_mov_b32 s30, s71
	v_mfma_f32_16x16x32_bf16 v[64:67], v[142:145], v[174:177], v[64:67]
	s_cmp_ge_i32 s71, s53
	v_mfma_f32_16x16x32_bf16 v[60:63], v[150:153], v[174:177], v[60:63]
	v_mfma_f32_16x16x32_bf16 v[48:51], v[142:145], v[182:185], v[48:51]
	v_mfma_f32_16x16x32_bf16 v[44:47], v[150:153], v[182:185], v[44:47]
	v_mfma_f32_16x16x32_bf16 v[32:35], v[142:145], v[190:193], v[32:35]
	v_mfma_f32_16x16x32_bf16 v[28:31], v[150:153], v[190:193], v[28:31]
	s_waitcnt lgkmcnt(0)
	v_mfma_f32_16x16x32_bf16 v[16:19], v[142:145], v[202:205], v[16:19]
	v_mfma_f32_16x16x32_bf16 v[12:15], v[150:153], v[202:205], v[12:15]
	s_setprio 0
	s_setprio 1
	v_mfma_f32_16x16x32_bf16 v[56:59], v[154:157], v[170:173], v[56:59]
	v_mfma_f32_16x16x32_bf16 v[52:55], v[162:165], v[170:173], v[52:55]
	v_mfma_f32_16x16x32_bf16 v[40:43], v[154:157], v[178:181], v[40:43]
	v_mfma_f32_16x16x32_bf16 v[36:39], v[162:165], v[178:181], v[36:39]
	v_mfma_f32_16x16x32_bf16 v[24:27], v[154:157], v[186:189], v[24:27]
	v_mfma_f32_16x16x32_bf16 v[20:23], v[162:165], v[186:189], v[20:23]
	v_mfma_f32_16x16x32_bf16 v[8:11], v[154:157], v[194:197], v[8:11]
	v_mfma_f32_16x16x32_bf16 v[4:7], v[162:165], v[194:197], v[4:7]
	v_mfma_f32_16x16x32_bf16 v[56:59], v[158:161], v[174:177], v[56:59]
	v_mfma_f32_16x16x32_bf16 v[52:55], v[166:169], v[174:177], v[52:55]
	v_mfma_f32_16x16x32_bf16 v[40:43], v[158:161], v[182:185], v[40:43]
	v_mfma_f32_16x16x32_bf16 v[36:39], v[166:169], v[182:185], v[36:39]
	v_mfma_f32_16x16x32_bf16 v[24:27], v[158:161], v[190:193], v[24:27]
	v_mfma_f32_16x16x32_bf16 v[20:23], v[166:169], v[190:193], v[20:23]
	v_mfma_f32_16x16x32_bf16 v[8:11], v[158:161], v[202:205], v[8:11]
	v_mfma_f32_16x16x32_bf16 v[4:7], v[166:169], v[202:205], v[4:7]
	s_setprio 0
	s_barrier
	s_cbranch_scc0 .LBB0_1096

.Lkz_6:
	s_and_b64 s[38:39], s[4:5], exec
	s_cselect_b32 s21, s25, s31
	s_cselect_b32 s23, s24, s30
	s_cselect_b32 s63, s27, s29
	s_cselect_b32 s64, s26, s28
	s_add_u32 s65, s30, 0x100
	s_addc_u32 s66, s31, 0
	s_add_u32 s67, s28, 0x100
	s_addc_u32 s68, s29, 0
	s_mov_b32 s28, 0
	v_add_u32_e32 v132, 0x10000, v138
	ds_read_b128 v[140:143], v132
	ds_read_b128 v[144:147], v132 offset:1024
	ds_read_b128 v[148:151], v132 offset:2048
	ds_read_b128 v[152:155], v132 offset:3072
	v_add_u32_e32 v132, 0x14000, v138
	ds_read_b128 v[156:159], v132
	ds_read_b128 v[160:163], v132 offset:1024
	ds_read_b128 v[164:167], v132 offset:2048
	ds_read_b128 v[168:171], v132 offset:3072
	s_add_i32 s69, s28, 2
	s_cmp_eq_u32 s59, s28
	s_cselect_b32 s38, s23, s65
	s_cselect_b32 s39, s21, s66
	s_cselect_b32 s30, s64, s67
	s_cselect_b32 s31, s63, s68
	s_add_u32 s28, s38, 0x80
	s_addc_u32 s29, s39, 0
	ds_read_b128 v[172:175], v139
	ds_read_b128 v[176:179], v139 offset:1024
	ds_read_b128 v[180:183], v139 offset:2048
	ds_read_b128 v[184:187], v139 offset:3072
	ds_read_b128 v[188:191], v139 offset:4096
	ds_read_b128 v[192:195], v139 offset:5120
	ds_read_b128 v[196:199], v139 offset:6144
	ds_read_b128 v[202:205], v139 offset:7168
	s_add_u32 s70, s65, 0x7ff80
	s_addc_u32 s71, s66, 0
	s_mov_b32 m0, s60
	s_nop 0
	global_load_lds_dwordx4 v1, s[70:71]
	s_mov_b32 m0, s61
	s_nop 0
	global_load_lds_dwordx4 v134, s[70:71]
	s_waitcnt vmcnt(8)
	s_waitcnt lgkmcnt(0)
	s_barrier
	s_setprio 1
	s_waitcnt lgkmcnt(7)
	v_mfma_f32_16x16x32_bf16 v[124:127], v[140:143], v[172:175], 0
	v_mfma_f32_16x16x32_bf16 v[128:131], v[148:151], v[172:175], 0
	s_waitcnt lgkmcnt(5)
	v_mfma_f32_16x16x32_bf16 v[112:115], v[140:143], v[180:183], 0
	v_mfma_f32_16x16x32_bf16 v[108:111], v[148:151], v[180:183], 0
	s_waitcnt lgkmcnt(3)
	v_mfma_f32_16x16x32_bf16 v[96:99], v[140:143], v[188:191], 0
	v_mfma_f32_16x16x32_bf16 v[92:95], v[148:151], v[188:191], 0
	s_waitcnt lgkmcnt(1)
	v_mfma_f32_16x16x32_bf16 v[80:83], v[140:143], v[196:199], 0
	v_mfma_f32_16x16x32_bf16 v[76:79], v[148:151], v[196:199], 0
	v_mfma_f32_16x16x32_bf16 v[124:127], v[144:147], v[176:179], v[124:127]
	v_mfma_f32_16x16x32_bf16 v[128:131], v[152:155], v[176:179], v[128:131]
	v_mfma_f32_16x16x32_bf16 v[112:115], v[144:147], v[184:187], v[112:115]
	v_mfma_f32_16x16x32_bf16 v[108:111], v[152:155], v[184:187], v[108:111]
	v_mfma_f32_16x16x32_bf16 v[96:99], v[144:147], v[192:195], v[96:99]
	v_mfma_f32_16x16x32_bf16 v[92:95], v[152:155], v[192:195], v[92:95]
	s_waitcnt lgkmcnt(0)
	v_mfma_f32_16x16x32_bf16 v[80:83], v[144:147], v[202:205], v[80:83]
	v_mfma_f32_16x16x32_bf16 v[76:79], v[152:155], v[202:205], v[76:79]
	s_setprio 0
	s_setprio 1
	v_mfma_f32_16x16x32_bf16 v[120:123], v[156:159], v[172:175], 0
	v_mfma_f32_16x16x32_bf16 v[116:119], v[164:167], v[172:175], 0
	v_mfma_f32_16x16x32_bf16 v[104:107], v[156:159], v[180:183], 0
	v_mfma_f32_16x16x32_bf16 v[100:103], v[164:167], v[180:183], 0
	v_mfma_f32_16x16x32_bf16 v[88:91], v[156:159], v[188:191], 0
	v_mfma_f32_16x16x32_bf16 v[84:87], v[164:167], v[188:191], 0
	v_mfma_f32_16x16x32_bf16 v[72:75], v[156:159], v[196:199], 0
	v_mfma_f32_16x16x32_bf16 v[68:71], v[164:167], v[196:199], 0
	v_mfma_f32_16x16x32_bf16 v[120:123], v[160:163], v[176:179], v[120:123]
	v_mfma_f32_16x16x32_bf16 v[116:119], v[168:171], v[176:179], v[116:119]
	v_mfma_f32_16x16x32_bf16 v[104:107], v[160:163], v[184:187], v[104:107]
	v_mfma_f32_16x16x32_bf16 v[100:103], v[168:171], v[184:187], v[100:103]
	v_mfma_f32_16x16x32_bf16 v[88:91], v[160:163], v[192:195], v[88:91]
	v_mfma_f32_16x16x32_bf16 v[84:87], v[168:171], v[192:195], v[84:87]
	v_mfma_f32_16x16x32_bf16 v[72:75], v[160:163], v[202:205], v[72:75]
	v_mfma_f32_16x16x32_bf16 v[68:71], v[168:171], v[202:205], v[68:71]
	s_setprio 0
	s_barrier
	ds_read_b128 v[172:175], v139 offset:16384
	ds_read_b128 v[176:179], v139 offset:17408
	ds_read_b128 v[180:183], v139 offset:18432
	ds_read_b128 v[184:187], v139 offset:19456
	ds_read_b128 v[188:191], v139 offset:20480
	ds_read_b128 v[192:195], v139 offset:21504
	ds_read_b128 v[196:199], v139 offset:22528
	ds_read_b128 v[202:205], v139 offset:23552
	s_mov_b32 m0, s40
	s_nop 0
	global_load_lds_dwordx4 v2, s[30:31]
	s_mov_b32 m0, s41
	s_nop 0
	global_load_lds_dwordx4 v135, s[30:31]
	s_add_u32 s70, s30, 0x20000
	s_addc_u32 s71, s31, 0
	s_mov_b32 m0, s42
	s_nop 0
	global_load_lds_dwordx4 v2, s[70:71]
	s_mov_b32 m0, s43
	s_nop 0
	global_load_lds_dwordx4 v135, s[70:71]
	s_mov_b32 m0, s0
	s_nop 0
	global_load_lds_dwordx4 v1, s[38:39]
	s_mov_b32 m0, s48
	s_nop 0
	global_load_lds_dwordx4 v134, s[38:39]
	s_waitcnt vmcnt(8)
	s_waitcnt lgkmcnt(0)
	s_barrier
	s_setprio 1
	s_waitcnt lgkmcnt(7)
	v_mfma_f32_16x16x32_bf16 v[64:67], v[140:143], v[172:175], 0
	v_mfma_f32_16x16x32_bf16 v[60:63], v[148:151], v[172:175], 0
	s_waitcnt lgkmcnt(5)
	v_mfma_f32_16x16x32_bf16 v[48:51], v[140:143], v[180:183], 0
	v_mfma_f32_16x16x32_bf16 v[44:47], v[148:151], v[180:183], 0
	s_waitcnt lgkmcnt(3)
	v_mfma_f32_16x16x32_bf16 v[32:35], v[140:143], v[188:191], 0
	v_mfma_f32_16x16x32_bf16 v[28:31], v[148:151], v[188:191], 0
	s_waitcnt lgkmcnt(1)
	v_mfma_f32_16x16x32_bf16 v[16:19], v[140:143], v[196:199], 0
	v_mfma_f32_16x16x32_bf16 v[12:15], v[148:151], v[196:199], 0
	v_mfma_f32_16x16x32_bf16 v[64:67], v[144:147], v[176:179], v[64:67]
	v_mfma_f32_16x16x32_bf16 v[60:63], v[152:155], v[176:179], v[60:63]
	v_mfma_f32_16x16x32_bf16 v[48:51], v[144:147], v[184:187], v[48:51]
	v_mfma_f32_16x16x32_bf16 v[44:47], v[152:155], v[184:187], v[44:47]
	v_mfma_f32_16x16x32_bf16 v[32:35], v[144:147], v[192:195], v[32:35]
	v_mfma_f32_16x16x32_bf16 v[28:31], v[152:155], v[192:195], v[28:31]
	s_waitcnt lgkmcnt(0)
	v_mfma_f32_16x16x32_bf16 v[16:19], v[144:147], v[202:205], v[16:19]
	v_mfma_f32_16x16x32_bf16 v[12:15], v[152:155], v[202:205], v[12:15]
	s_setprio 0
	s_setprio 1
	v_mfma_f32_16x16x32_bf16 v[56:59], v[156:159], v[172:175], 0
	v_mfma_f32_16x16x32_bf16 v[52:55], v[164:167], v[172:175], 0
	v_mfma_f32_16x16x32_bf16 v[40:43], v[156:159], v[180:183], 0
	v_mfma_f32_16x16x32_bf16 v[36:39], v[164:167], v[180:183], 0
	v_mfma_f32_16x16x32_bf16 v[24:27], v[156:159], v[188:191], 0
	v_mfma_f32_16x16x32_bf16 v[20:23], v[164:167], v[188:191], 0
	v_mfma_f32_16x16x32_bf16 v[8:11], v[156:159], v[196:199], 0
	v_mfma_f32_16x16x32_bf16 v[4:7], v[164:167], v[196:199], 0
	v_mfma_f32_16x16x32_bf16 v[56:59], v[160:163], v[176:179], v[56:59]
	v_mfma_f32_16x16x32_bf16 v[52:55], v[168:171], v[176:179], v[52:55]
	v_mfma_f32_16x16x32_bf16 v[40:43], v[160:163], v[184:187], v[40:43]
	v_mfma_f32_16x16x32_bf16 v[36:39], v[168:171], v[184:187], v[36:39]
	v_mfma_f32_16x16x32_bf16 v[24:27], v[160:163], v[192:195], v[24:27]
	v_mfma_f32_16x16x32_bf16 v[20:23], v[168:171], v[192:195], v[20:23]
	v_mfma_f32_16x16x32_bf16 v[8:11], v[160:163], v[202:205], v[8:11]
	v_mfma_f32_16x16x32_bf16 v[4:7], v[168:171], v[202:205], v[4:7]
	s_setprio 0
	s_barrier
	v_add_u32_e32 v132, 0x18000, v138
	ds_read_b128 v[140:143], v132
	ds_read_b128 v[144:147], v132 offset:1024
	ds_read_b128 v[148:151], v132 offset:2048
	ds_read_b128 v[152:155], v132 offset:3072
	v_add_u32_e32 v132, 0x1c000, v138
	ds_read_b128 v[156:159], v132
	ds_read_b128 v[160:163], v132 offset:1024
	ds_read_b128 v[164:167], v132 offset:2048
	ds_read_b128 v[168:171], v132 offset:3072
	ds_read_b128 v[172:175], v139 offset:32768
	ds_read_b128 v[176:179], v139 offset:33792
	ds_read_b128 v[180:183], v139 offset:34816
	ds_read_b128 v[184:187], v139 offset:35840
	ds_read_b128 v[188:191], v139 offset:36864
	ds_read_b128 v[192:195], v139 offset:37888
	ds_read_b128 v[196:199], v139 offset:38912
	ds_read_b128 v[202:205], v139 offset:39936
	s_add_u32 s38, s38, 0x80000
	s_addc_u32 s39, s39, 0
	s_mov_b32 m0, s49
	s_nop 0
	global_load_lds_dwordx4 v1, s[38:39]
	s_mov_b32 m0, s50
	s_nop 0
	global_load_lds_dwordx4 v134, s[38:39]
	s_waitcnt vmcnt(8)
	s_waitcnt lgkmcnt(0)
	s_barrier
	s_setprio 1
	s_waitcnt lgkmcnt(7)
	v_mfma_f32_16x16x32_bf16 v[124:127], v[140:143], v[172:175], v[124:127]
	v_mfma_f32_16x16x32_bf16 v[128:131], v[148:151], v[172:175], v[128:131]
	s_waitcnt lgkmcnt(5)
	v_mfma_f32_16x16x32_bf16 v[112:115], v[140:143], v[180:183], v[112:115]
	v_mfma_f32_16x16x32_bf16 v[108:111], v[148:151], v[180:183], v[108:111]
	s_waitcnt lgkmcnt(3)
	v_mfma_f32_16x16x32_bf16 v[96:99], v[140:143], v[188:191], v[96:99]
	v_mfma_f32_16x16x32_bf16 v[92:95], v[148:151], v[188:191], v[92:95]
	s_waitcnt lgkmcnt(1)
	v_mfma_f32_16x16x32_bf16 v[80:83], v[140:143], v[196:199], v[80:83]
	v_mfma_f32_16x16x32_bf16 v[76:79], v[148:151], v[196:199], v[76:79]
	v_mfma_f32_16x16x32_bf16 v[124:127], v[144:147], v[176:179], v[124:127]
	v_mfma_f32_16x16x32_bf16 v[128:131], v[152:155], v[176:179], v[128:131]
	v_mfma_f32_16x16x32_bf16 v[112:115], v[144:147], v[184:187], v[112:115]
	v_mfma_f32_16x16x32_bf16 v[108:111], v[152:155], v[184:187], v[108:111]
	v_mfma_f32_16x16x32_bf16 v[96:99], v[144:147], v[192:195], v[96:99]
	v_mfma_f32_16x16x32_bf16 v[92:95], v[152:155], v[192:195], v[92:95]
	s_waitcnt lgkmcnt(0)
	v_mfma_f32_16x16x32_bf16 v[80:83], v[144:147], v[202:205], v[80:83]
	v_mfma_f32_16x16x32_bf16 v[76:79], v[152:155], v[202:205], v[76:79]
	s_setprio 0
	s_setprio 1
	v_mfma_f32_16x16x32_bf16 v[120:123], v[156:159], v[172:175], v[120:123]
	v_mfma_f32_16x16x32_bf16 v[116:119], v[164:167], v[172:175], v[116:119]
	v_mfma_f32_16x16x32_bf16 v[104:107], v[156:159], v[180:183], v[104:107]
	v_mfma_f32_16x16x32_bf16 v[100:103], v[164:167], v[180:183], v[100:103]
	v_mfma_f32_16x16x32_bf16 v[88:91], v[156:159], v[188:191], v[88:91]
	v_mfma_f32_16x16x32_bf16 v[84:87], v[164:167], v[188:191], v[84:87]
	v_mfma_f32_16x16x32_bf16 v[72:75], v[156:159], v[196:199], v[72:75]
	v_mfma_f32_16x16x32_bf16 v[68:71], v[164:167], v[196:199], v[68:71]
	v_mfma_f32_16x16x32_bf16 v[120:123], v[160:163], v[176:179], v[120:123]
	v_mfma_f32_16x16x32_bf16 v[116:119], v[168:171], v[176:179], v[116:119]
	v_mfma_f32_16x16x32_bf16 v[104:107], v[160:163], v[184:187], v[104:107]
	v_mfma_f32_16x16x32_bf16 v[100:103], v[168:171], v[184:187], v[100:103]
	v_mfma_f32_16x16x32_bf16 v[88:91], v[160:163], v[192:195], v[88:91]
	v_mfma_f32_16x16x32_bf16 v[84:87], v[168:171], v[192:195], v[84:87]
	v_mfma_f32_16x16x32_bf16 v[72:75], v[160:163], v[202:205], v[72:75]
	v_mfma_f32_16x16x32_bf16 v[68:71], v[168:171], v[202:205], v[68:71]
	s_setprio 0
	s_barrier
	ds_read_b128 v[172:175], v139 offset:49152
	ds_read_b128 v[176:179], v139 offset:50176
	ds_read_b128 v[180:183], v139 offset:51200
	ds_read_b128 v[184:187], v139 offset:52224
	ds_read_b128 v[188:191], v139 offset:53248
	ds_read_b128 v[192:195], v139 offset:54272
	ds_read_b128 v[196:199], v139 offset:55296
	ds_read_b128 v[202:205], v139 offset:56320
	s_add_u32 s38, s30, 0x80
	s_addc_u32 s39, s31, 0
	s_mov_b32 m0, s53
	s_nop 0
	global_load_lds_dwordx4 v2, s[38:39]
	s_add_u32 s30, s30, 0x20080
	s_mov_b32 m0, s54
	s_nop 0
	global_load_lds_dwordx4 v135, s[38:39]
	s_addc_u32 s31, s31, 0
	s_mov_b32 m0, s57
	s_nop 0
	global_load_lds_dwordx4 v2, s[30:31]
	s_mov_b32 m0, s58
	s_nop 0
	global_load_lds_dwordx4 v135, s[30:31]
	s_mov_b32 m0, s55
	s_nop 0
	global_load_lds_dwordx4 v1, s[28:29]
	s_mov_b32 m0, s56
	s_nop 0
	global_load_lds_dwordx4 v134, s[28:29]
	s_waitcnt vmcnt(8)
	s_waitcnt lgkmcnt(0)
	s_barrier
	s_setprio 1
	s_waitcnt lgkmcnt(7)
	v_mfma_f32_16x16x32_bf16 v[64:67], v[140:143], v[172:175], v[64:67]
	v_mfma_f32_16x16x32_bf16 v[60:63], v[148:151], v[172:175], v[60:63]
	s_add_u32 s65, s65, 0x100
	s_waitcnt lgkmcnt(5)
	v_mfma_f32_16x16x32_bf16 v[48:51], v[140:143], v[180:183], v[48:51]
	s_addc_u32 s66, s66, 0
	v_mfma_f32_16x16x32_bf16 v[44:47], v[148:151], v[180:183], v[44:47]
	s_add_u32 s67, s67, 0x100
	s_waitcnt lgkmcnt(3)
	v_mfma_f32_16x16x32_bf16 v[32:35], v[140:143], v[188:191], v[32:35]
	s_addc_u32 s68, s68, 0
	v_mfma_f32_16x16x32_bf16 v[28:31], v[148:151], v[188:191], v[28:31]
	s_mov_b32 s28, s69
	s_waitcnt lgkmcnt(1)
	v_mfma_f32_16x16x32_bf16 v[16:19], v[140:143], v[196:199], v[16:19]
	s_cmp_ge_i32 s69, s52
	v_mfma_f32_16x16x32_bf16 v[12:15], v[148:151], v[196:199], v[12:15]
	v_mfma_f32_16x16x32_bf16 v[64:67], v[144:147], v[176:179], v[64:67]
	v_mfma_f32_16x16x32_bf16 v[60:63], v[152:155], v[176:179], v[60:63]
	v_mfma_f32_16x16x32_bf16 v[48:51], v[144:147], v[184:187], v[48:51]
	v_mfma_f32_16x16x32_bf16 v[44:47], v[152:155], v[184:187], v[44:47]
	v_mfma_f32_16x16x32_bf16 v[32:35], v[144:147], v[192:195], v[32:35]
	v_mfma_f32_16x16x32_bf16 v[28:31], v[152:155], v[192:195], v[28:31]
	s_waitcnt lgkmcnt(0)
	v_mfma_f32_16x16x32_bf16 v[16:19], v[144:147], v[202:205], v[16:19]
	v_mfma_f32_16x16x32_bf16 v[12:15], v[152:155], v[202:205], v[12:15]
	s_setprio 0
	s_setprio 1
	v_mfma_f32_16x16x32_bf16 v[56:59], v[156:159], v[172:175], v[56:59]
	v_mfma_f32_16x16x32_bf16 v[52:55], v[164:167], v[172:175], v[52:55]
	v_mfma_f32_16x16x32_bf16 v[40:43], v[156:159], v[180:183], v[40:43]
	v_mfma_f32_16x16x32_bf16 v[36:39], v[164:167], v[180:183], v[36:39]
	v_mfma_f32_16x16x32_bf16 v[24:27], v[156:159], v[188:191], v[24:27]
	v_mfma_f32_16x16x32_bf16 v[20:23], v[164:167], v[188:191], v[20:23]
	v_mfma_f32_16x16x32_bf16 v[8:11], v[156:159], v[196:199], v[8:11]
	v_mfma_f32_16x16x32_bf16 v[4:7], v[164:167], v[196:199], v[4:7]
	v_mfma_f32_16x16x32_bf16 v[56:59], v[160:163], v[176:179], v[56:59]
	v_mfma_f32_16x16x32_bf16 v[52:55], v[168:171], v[176:179], v[52:55]
	v_mfma_f32_16x16x32_bf16 v[40:43], v[160:163], v[184:187], v[40:43]
	v_mfma_f32_16x16x32_bf16 v[36:39], v[168:171], v[184:187], v[36:39]
	v_mfma_f32_16x16x32_bf16 v[24:27], v[160:163], v[192:195], v[24:27]
	v_mfma_f32_16x16x32_bf16 v[20:23], v[168:171], v[192:195], v[20:23]
	v_mfma_f32_16x16x32_bf16 v[8:11], v[160:163], v[202:205], v[8:11]
	v_mfma_f32_16x16x32_bf16 v[4:7], v[168:171], v[202:205], v[4:7]
	s_setprio 0
	s_barrier
	s_cbranch_scc0 .LBB0_1237
	s_branch .LBB0_1238
.LBB0_1237:
	v_add_u32_e32 v132, 0x10000, v138
	ds_read_b128 v[140:143], v132
	ds_read_b128 v[144:147], v132 offset:1024
	ds_read_b128 v[148:151], v132 offset:2048
	ds_read_b128 v[152:155], v132 offset:3072
	v_add_u32_e32 v132, 0x14000, v138
	ds_read_b128 v[156:159], v132
	ds_read_b128 v[160:163], v132 offset:1024
	ds_read_b128 v[164:167], v132 offset:2048
	ds_read_b128 v[168:171], v132 offset:3072
	s_add_i32 s69, s28, 2
	s_cmp_eq_u32 s59, s28
	s_cselect_b32 s38, s23, s65
	s_cselect_b32 s39, s21, s66
	s_cselect_b32 s30, s64, s67
	s_cselect_b32 s31, s63, s68
	s_add_u32 s28, s38, 0x80
	s_addc_u32 s29, s39, 0
	ds_read_b128 v[172:175], v139
	ds_read_b128 v[176:179], v139 offset:1024
	ds_read_b128 v[180:183], v139 offset:2048
	ds_read_b128 v[184:187], v139 offset:3072
	ds_read_b128 v[188:191], v139 offset:4096
	ds_read_b128 v[192:195], v139 offset:5120
	ds_read_b128 v[196:199], v139 offset:6144
	ds_read_b128 v[202:205], v139 offset:7168
	s_add_u32 s70, s65, 0x7ff80
	s_addc_u32 s71, s66, 0
	s_mov_b32 m0, s60
	s_nop 0
	global_load_lds_dwordx4 v1, s[70:71]
	s_mov_b32 m0, s61
	s_nop 0
	global_load_lds_dwordx4 v134, s[70:71]
	s_waitcnt vmcnt(8)
	s_waitcnt lgkmcnt(0)
	s_barrier
	s_setprio 1
	s_waitcnt lgkmcnt(7)
	v_mfma_f32_16x16x32_bf16 v[124:127], v[140:143], v[172:175], v[124:127]
	v_mfma_f32_16x16x32_bf16 v[128:131], v[148:151], v[172:175], v[128:131]
	s_waitcnt lgkmcnt(5)
	v_mfma_f32_16x16x32_bf16 v[112:115], v[140:143], v[180:183], v[112:115]
	v_mfma_f32_16x16x32_bf16 v[108:111], v[148:151], v[180:183], v[108:111]
	s_waitcnt lgkmcnt(3)
	v_mfma_f32_16x16x32_bf16 v[96:99], v[140:143], v[188:191], v[96:99]
	v_mfma_f32_16x16x32_bf16 v[92:95], v[148:151], v[188:191], v[92:95]
	s_waitcnt lgkmcnt(1)
	v_mfma_f32_16x16x32_bf16 v[80:83], v[140:143], v[196:199], v[80:83]
	v_mfma_f32_16x16x32_bf16 v[76:79], v[148:151], v[196:199], v[76:79]
	v_mfma_f32_16x16x32_bf16 v[124:127], v[144:147], v[176:179], v[124:127]
	v_mfma_f32_16x16x32_bf16 v[128:131], v[152:155], v[176:179], v[128:131]
	v_mfma_f32_16x16x32_bf16 v[112:115], v[144:147], v[184:187], v[112:115]
	v_mfma_f32_16x16x32_bf16 v[108:111], v[152:155], v[184:187], v[108:111]
	v_mfma_f32_16x16x32_bf16 v[96:99], v[144:147], v[192:195], v[96:99]
	v_mfma_f32_16x16x32_bf16 v[92:95], v[152:155], v[192:195], v[92:95]
	s_waitcnt lgkmcnt(0)
	v_mfma_f32_16x16x32_bf16 v[80:83], v[144:147], v[202:205], v[80:83]
	v_mfma_f32_16x16x32_bf16 v[76:79], v[152:155], v[202:205], v[76:79]
	s_setprio 0
	s_setprio 1
	v_mfma_f32_16x16x32_bf16 v[120:123], v[156:159], v[172:175], v[120:123]
	v_mfma_f32_16x16x32_bf16 v[116:119], v[164:167], v[172:175], v[116:119]
	v_mfma_f32_16x16x32_bf16 v[104:107], v[156:159], v[180:183], v[104:107]
	v_mfma_f32_16x16x32_bf16 v[100:103], v[164:167], v[180:183], v[100:103]
	v_mfma_f32_16x16x32_bf16 v[88:91], v[156:159], v[188:191], v[88:91]
	v_mfma_f32_16x16x32_bf16 v[84:87], v[164:167], v[188:191], v[84:87]
	v_mfma_f32_16x16x32_bf16 v[72:75], v[156:159], v[196:199], v[72:75]
	v_mfma_f32_16x16x32_bf16 v[68:71], v[164:167], v[196:199], v[68:71]
	v_mfma_f32_16x16x32_bf16 v[120:123], v[160:163], v[176:179], v[120:123]
	v_mfma_f32_16x16x32_bf16 v[116:119], v[168:171], v[176:179], v[116:119]
	v_mfma_f32_16x16x32_bf16 v[104:107], v[160:163], v[184:187], v[104:107]
	v_mfma_f32_16x16x32_bf16 v[100:103], v[168:171], v[184:187], v[100:103]
	v_mfma_f32_16x16x32_bf16 v[88:91], v[160:163], v[192:195], v[88:91]
	v_mfma_f32_16x16x32_bf16 v[84:87], v[168:171], v[192:195], v[84:87]
	v_mfma_f32_16x16x32_bf16 v[72:75], v[160:163], v[202:205], v[72:75]
	v_mfma_f32_16x16x32_bf16 v[68:71], v[168:171], v[202:205], v[68:71]
	s_setprio 0
	s_barrier
	ds_read_b128 v[172:175], v139 offset:16384
	ds_read_b128 v[176:179], v139 offset:17408
	ds_read_b128 v[180:183], v139 offset:18432
	ds_read_b128 v[184:187], v139 offset:19456
	ds_read_b128 v[188:191], v139 offset:20480
	ds_read_b128 v[192:195], v139 offset:21504
	ds_read_b128 v[196:199], v139 offset:22528
	ds_read_b128 v[202:205], v139 offset:23552
	s_mov_b32 m0, s40
	s_nop 0
	global_load_lds_dwordx4 v2, s[30:31]
	s_mov_b32 m0, s41
	s_nop 0
	global_load_lds_dwordx4 v135, s[30:31]
	s_add_u32 s70, s30, 0x20000
	s_addc_u32 s71, s31, 0
	s_mov_b32 m0, s42
	s_nop 0
	global_load_lds_dwordx4 v2, s[70:71]
	s_mov_b32 m0, s43
	s_nop 0
	global_load_lds_dwordx4 v135, s[70:71]
	s_mov_b32 m0, s0
	s_nop 0
	global_load_lds_dwordx4 v1, s[38:39]
	s_mov_b32 m0, s48
	s_nop 0
	global_load_lds_dwordx4 v134, s[38:39]
	s_waitcnt vmcnt(8)
	s_waitcnt lgkmcnt(0)
	s_barrier
	s_setprio 1
	s_waitcnt lgkmcnt(7)
	v_mfma_f32_16x16x32_bf16 v[64:67], v[140:143], v[172:175], v[64:67]
	v_mfma_f32_16x16x32_bf16 v[60:63], v[148:151], v[172:175], v[60:63]
	s_waitcnt lgkmcnt(5)
	v_mfma_f32_16x16x32_bf16 v[48:51], v[140:143], v[180:183], v[48:51]
	v_mfma_f32_16x16x32_bf16 v[44:47], v[148:151], v[180:183], v[44:47]
	s_waitcnt lgkmcnt(3)
	v_mfma_f32_16x16x32_bf16 v[32:35], v[140:143], v[188:191], v[32:35]
	v_mfma_f32_16x16x32_bf16 v[28:31], v[148:151], v[188:191], v[28:31]
	s_waitcnt lgkmcnt(1)
	v_mfma_f32_16x16x32_bf16 v[16:19], v[140:143], v[196:199], v[16:19]
	v_mfma_f32_16x16x32_bf16 v[12:15], v[148:151], v[196:199], v[12:15]
	v_mfma_f32_16x16x32_bf16 v[64:67], v[144:147], v[176:179], v[64:67]
	v_mfma_f32_16x16x32_bf16 v[60:63], v[152:155], v[176:179], v[60:63]
	v_mfma_f32_16x16x32_bf16 v[48:51], v[144:147], v[184:187], v[48:51]
	v_mfma_f32_16x16x32_bf16 v[44:47], v[152:155], v[184:187], v[44:47]
	v_mfma_f32_16x16x32_bf16 v[32:35], v[144:147], v[192:195], v[32:35]
	v_mfma_f32_16x16x32_bf16 v[28:31], v[152:155], v[192:195], v[28:31]
	s_waitcnt lgkmcnt(0)
	v_mfma_f32_16x16x32_bf16 v[16:19], v[144:147], v[202:205], v[16:19]
	v_mfma_f32_16x16x32_bf16 v[12:15], v[152:155], v[202:205], v[12:15]
	s_setprio 0
	s_setprio 1
	v_mfma_f32_16x16x32_bf16 v[56:59], v[156:159], v[172:175], v[56:59]
	v_mfma_f32_16x16x32_bf16 v[52:55], v[164:167], v[172:175], v[52:55]
	v_mfma_f32_16x16x32_bf16 v[40:43], v[156:159], v[180:183], v[40:43]
	v_mfma_f32_16x16x32_bf16 v[36:39], v[164:167], v[180:183], v[36:39]
	v_mfma_f32_16x16x32_bf16 v[24:27], v[156:159], v[188:191], v[24:27]
	v_mfma_f32_16x16x32_bf16 v[20:23], v[164:167], v[188:191], v[20:23]
	v_mfma_f32_16x16x32_bf16 v[8:11], v[156:159], v[196:199], v[8:11]
	v_mfma_f32_16x16x32_bf16 v[4:7], v[164:167], v[196:199], v[4:7]
	v_mfma_f32_16x16x32_bf16 v[56:59], v[160:163], v[176:179], v[56:59]
	v_mfma_f32_16x16x32_bf16 v[52:55], v[168:171], v[176:179], v[52:55]
	v_mfma_f32_16x16x32_bf16 v[40:43], v[160:163], v[184:187], v[40:43]
	v_mfma_f32_16x16x32_bf16 v[36:39], v[168:171], v[184:187], v[36:39]
	v_mfma_f32_16x16x32_bf16 v[24:27], v[160:163], v[192:195], v[24:27]
	v_mfma_f32_16x16x32_bf16 v[20:23], v[168:171], v[192:195], v[20:23]
	v_mfma_f32_16x16x32_bf16 v[8:11], v[160:163], v[202:205], v[8:11]
	v_mfma_f32_16x16x32_bf16 v[4:7], v[168:171], v[202:205], v[4:7]
	s_setprio 0
	s_barrier
	v_add_u32_e32 v132, 0x18000, v138
	ds_read_b128 v[140:143], v132
	ds_read_b128 v[144:147], v132 offset:1024
	ds_read_b128 v[148:151], v132 offset:2048
	ds_read_b128 v[152:155], v132 offset:3072
	v_add_u32_e32 v132, 0x1c000, v138
	ds_read_b128 v[156:159], v132
	ds_read_b128 v[160:163], v132 offset:1024
	ds_read_b128 v[164:167], v132 offset:2048
	ds_read_b128 v[168:171], v132 offset:3072
	ds_read_b128 v[172:175], v139 offset:32768
	ds_read_b128 v[176:179], v139 offset:33792
	ds_read_b128 v[180:183], v139 offset:34816
	ds_read_b128 v[184:187], v139 offset:35840
	ds_read_b128 v[188:191], v139 offset:36864
	ds_read_b128 v[192:195], v139 offset:37888
	ds_read_b128 v[196:199], v139 offset:38912
	ds_read_b128 v[202:205], v139 offset:39936
	s_add_u32 s38, s38, 0x80000
	s_addc_u32 s39, s39, 0
	s_mov_b32 m0, s49
	s_nop 0
	global_load_lds_dwordx4 v1, s[38:39]
	s_mov_b32 m0, s50
	s_nop 0
	global_load_lds_dwordx4 v134, s[38:39]
	s_waitcnt vmcnt(8)
	s_waitcnt lgkmcnt(0)
	s_barrier
	s_setprio 1
	s_waitcnt lgkmcnt(7)
	v_mfma_f32_16x16x32_bf16 v[124:127], v[140:143], v[172:175], v[124:127]
	v_mfma_f32_16x16x32_bf16 v[128:131], v[148:151], v[172:175], v[128:131]
	s_waitcnt lgkmcnt(5)
	v_mfma_f32_16x16x32_bf16 v[112:115], v[140:143], v[180:183], v[112:115]
	v_mfma_f32_16x16x32_bf16 v[108:111], v[148:151], v[180:183], v[108:111]
	s_waitcnt lgkmcnt(3)
	v_mfma_f32_16x16x32_bf16 v[96:99], v[140:143], v[188:191], v[96:99]
	v_mfma_f32_16x16x32_bf16 v[92:95], v[148:151], v[188:191], v[92:95]
	s_waitcnt lgkmcnt(1)
	v_mfma_f32_16x16x32_bf16 v[80:83], v[140:143], v[196:199], v[80:83]
	v_mfma_f32_16x16x32_bf16 v[76:79], v[148:151], v[196:199], v[76:79]
	v_mfma_f32_16x16x32_bf16 v[124:127], v[144:147], v[176:179], v[124:127]
	v_mfma_f32_16x16x32_bf16 v[128:131], v[152:155], v[176:179], v[128:131]
	v_mfma_f32_16x16x32_bf16 v[112:115], v[144:147], v[184:187], v[112:115]
	v_mfma_f32_16x16x32_bf16 v[108:111], v[152:155], v[184:187], v[108:111]
	v_mfma_f32_16x16x32_bf16 v[96:99], v[144:147], v[192:195], v[96:99]
	v_mfma_f32_16x16x32_bf16 v[92:95], v[152:155], v[192:195], v[92:95]
	s_waitcnt lgkmcnt(0)
	v_mfma_f32_16x16x32_bf16 v[80:83], v[144:147], v[202:205], v[80:83]
	v_mfma_f32_16x16x32_bf16 v[76:79], v[152:155], v[202:205], v[76:79]
	s_setprio 0
	s_setprio 1
	v_mfma_f32_16x16x32_bf16 v[120:123], v[156:159], v[172:175], v[120:123]
	v_mfma_f32_16x16x32_bf16 v[116:119], v[164:167], v[172:175], v[116:119]
	v_mfma_f32_16x16x32_bf16 v[104:107], v[156:159], v[180:183], v[104:107]
	v_mfma_f32_16x16x32_bf16 v[100:103], v[164:167], v[180:183], v[100:103]
	v_mfma_f32_16x16x32_bf16 v[88:91], v[156:159], v[188:191], v[88:91]
	v_mfma_f32_16x16x32_bf16 v[84:87], v[164:167], v[188:191], v[84:87]
	v_mfma_f32_16x16x32_bf16 v[72:75], v[156:159], v[196:199], v[72:75]
	v_mfma_f32_16x16x32_bf16 v[68:71], v[164:167], v[196:199], v[68:71]
	v_mfma_f32_16x16x32_bf16 v[120:123], v[160:163], v[176:179], v[120:123]
	v_mfma_f32_16x16x32_bf16 v[116:119], v[168:171], v[176:179], v[116:119]
	v_mfma_f32_16x16x32_bf16 v[104:107], v[160:163], v[184:187], v[104:107]
	v_mfma_f32_16x16x32_bf16 v[100:103], v[168:171], v[184:187], v[100:103]
	v_mfma_f32_16x16x32_bf16 v[88:91], v[160:163], v[192:195], v[88:91]
	v_mfma_f32_16x16x32_bf16 v[84:87], v[168:171], v[192:195], v[84:87]
	v_mfma_f32_16x16x32_bf16 v[72:75], v[160:163], v[202:205], v[72:75]
	v_mfma_f32_16x16x32_bf16 v[68:71], v[168:171], v[202:205], v[68:71]
	s_setprio 0
	s_barrier
	ds_read_b128 v[172:175], v139 offset:49152
	ds_read_b128 v[176:179], v139 offset:50176
	ds_read_b128 v[180:183], v139 offset:51200
	ds_read_b128 v[184:187], v139 offset:52224
	ds_read_b128 v[188:191], v139 offset:53248
	ds_read_b128 v[192:195], v139 offset:54272
	ds_read_b128 v[196:199], v139 offset:55296
	ds_read_b128 v[202:205], v139 offset:56320
	s_add_u32 s38, s30, 0x80
	s_addc_u32 s39, s31, 0
	s_mov_b32 m0, s53
	s_nop 0
	global_load_lds_dwordx4 v2, s[38:39]
	s_add_u32 s30, s30, 0x20080
	s_mov_b32 m0, s54
	s_nop 0
	global_load_lds_dwordx4 v135, s[38:39]
	s_addc_u32 s31, s31, 0
	s_mov_b32 m0, s57
	s_nop 0
	global_load_lds_dwordx4 v2, s[30:31]
	s_mov_b32 m0, s58
	s_nop 0
	global_load_lds_dwordx4 v135, s[30:31]
	s_mov_b32 m0, s55
	s_nop 0
	global_load_lds_dwordx4 v1, s[28:29]
	s_mov_b32 m0, s56
	s_nop 0
	global_load_lds_dwordx4 v134, s[28:29]
	s_waitcnt vmcnt(8)
	s_waitcnt lgkmcnt(0)
	s_barrier
	s_setprio 1
	s_waitcnt lgkmcnt(7)
	v_mfma_f32_16x16x32_bf16 v[64:67], v[140:143], v[172:175], v[64:67]
	v_mfma_f32_16x16x32_bf16 v[60:63], v[148:151], v[172:175], v[60:63]
	s_add_u32 s65, s65, 0x100
	s_waitcnt lgkmcnt(5)
	v_mfma_f32_16x16x32_bf16 v[48:51], v[140:143], v[180:183], v[48:51]
	s_addc_u32 s66, s66, 0
	v_mfma_f32_16x16x32_bf16 v[44:47], v[148:151], v[180:183], v[44:47]
	s_add_u32 s67, s67, 0x100
	s_waitcnt lgkmcnt(3)
	v_mfma_f32_16x16x32_bf16 v[32:35], v[140:143], v[188:191], v[32:35]
	s_addc_u32 s68, s68, 0
	v_mfma_f32_16x16x32_bf16 v[28:31], v[148:151], v[188:191], v[28:31]
	s_mov_b32 s28, s69
	s_waitcnt lgkmcnt(1)
	v_mfma_f32_16x16x32_bf16 v[16:19], v[140:143], v[196:199], v[16:19]
	s_cmp_ge_i32 s69, s52
	v_mfma_f32_16x16x32_bf16 v[12:15], v[148:151], v[196:199], v[12:15]
	v_mfma_f32_16x16x32_bf16 v[64:67], v[144:147], v[176:179], v[64:67]
	v_mfma_f32_16x16x32_bf16 v[60:63], v[152:155], v[176:179], v[60:63]
	v_mfma_f32_16x16x32_bf16 v[48:51], v[144:147], v[184:187], v[48:51]
	v_mfma_f32_16x16x32_bf16 v[44:47], v[152:155], v[184:187], v[44:47]
	v_mfma_f32_16x16x32_bf16 v[32:35], v[144:147], v[192:195], v[32:35]
	v_mfma_f32_16x16x32_bf16 v[28:31], v[152:155], v[192:195], v[28:31]
	s_waitcnt lgkmcnt(0)
	v_mfma_f32_16x16x32_bf16 v[16:19], v[144:147], v[202:205], v[16:19]
	v_mfma_f32_16x16x32_bf16 v[12:15], v[152:155], v[202:205], v[12:15]
	s_setprio 0
	s_setprio 1
	v_mfma_f32_16x16x32_bf16 v[56:59], v[156:159], v[172:175], v[56:59]
	v_mfma_f32_16x16x32_bf16 v[52:55], v[164:167], v[172:175], v[52:55]
	v_mfma_f32_16x16x32_bf16 v[40:43], v[156:159], v[180:183], v[40:43]
	v_mfma_f32_16x16x32_bf16 v[36:39], v[164:167], v[180:183], v[36:39]
	v_mfma_f32_16x16x32_bf16 v[24:27], v[156:159], v[188:191], v[24:27]
	v_mfma_f32_16x16x32_bf16 v[20:23], v[164:167], v[188:191], v[20:23]
	v_mfma_f32_16x16x32_bf16 v[8:11], v[156:159], v[196:199], v[8:11]
	v_mfma_f32_16x16x32_bf16 v[4:7], v[164:167], v[196:199], v[4:7]
	v_mfma_f32_16x16x32_bf16 v[56:59], v[160:163], v[176:179], v[56:59]
	v_mfma_f32_16x16x32_bf16 v[52:55], v[168:171], v[176:179], v[52:55]
	v_mfma_f32_16x16x32_bf16 v[40:43], v[160:163], v[184:187], v[40:43]
	v_mfma_f32_16x16x32_bf16 v[36:39], v[168:171], v[184:187], v[36:39]
	v_mfma_f32_16x16x32_bf16 v[24:27], v[160:163], v[192:195], v[24:27]
	v_mfma_f32_16x16x32_bf16 v[20:23], v[168:171], v[192:195], v[20:23]
	v_mfma_f32_16x16x32_bf16 v[8:11], v[160:163], v[202:205], v[8:11]
	v_mfma_f32_16x16x32_bf16 v[4:7], v[168:171], v[202:205], v[4:7]
	s_setprio 0
	s_barrier
	s_cbranch_scc0 .LBB0_1237

.Lkz_7:
	s_and_b64 s[38:39], s[4:5], exec
	s_cselect_b32 s3, s25, s31
	s_cselect_b32 s21, s24, s30
	s_cselect_b32 s65, s27, s29
	s_cselect_b32 s66, s26, s28
	s_add_u32 s67, s30, 0x100
	s_addc_u32 s68, s31, 0
	s_add_u32 s69, s28, 0x100
	s_addc_u32 s70, s29, 0
	s_add_u32 s28, s30, 0x200080
	s_addc_u32 s29, s31, 0
	s_mov_b32 s30, 0
	v_add_u32_e32 v150, 0x10000, v136
	v_add_u32_e32 v166, 0x14000, v136
	ds_read_b128 v[138:141], v150
	ds_read_b128 v[142:145], v150 offset:1024
	ds_read_b128 v[146:149], v150 offset:2048
	ds_read_b128 v[150:153], v150 offset:3072
	ds_read_b128 v[154:157], v166
	ds_read_b128 v[158:161], v166 offset:1024
	ds_read_b128 v[162:165], v166 offset:2048
	ds_read_b128 v[166:169], v166 offset:3072
	s_add_i32 s71, s30, 2
	s_cmp_eq_u32 s60, s30
	s_cselect_b32 s40, s21, s67
	s_cselect_b32 s41, s3, s68
	s_cselect_b32 s38, s66, s69
	s_cselect_b32 s39, s65, s70
	s_add_u32 s30, s40, 0x80
	s_addc_u32 s31, s41, 0
	ds_read_b128 v[170:173], v137
	ds_read_b128 v[174:177], v137 offset:1024
	ds_read_b128 v[178:181], v137 offset:2048
	ds_read_b128 v[182:185], v137 offset:3072
	ds_read_b128 v[186:189], v137 offset:4096
	ds_read_b128 v[190:193], v137 offset:5120
	ds_read_b128 v[194:197], v137 offset:6144
	ds_read_b128 v[202:205], v137 offset:7168
	s_mov_b32 m0, s61
	s_nop 0
	global_load_lds_dwordx4 v1, s[28:29]
	s_mov_b32 m0, s62
	s_nop 0
	global_load_lds_dwordx4 v132, s[28:29]
	s_waitcnt vmcnt(8)
	s_waitcnt lgkmcnt(0)
	s_barrier
	s_setprio 1
	s_waitcnt lgkmcnt(7)
	v_mfma_f32_16x16x32_bf16 v[124:127], v[138:141], v[170:173], 0
	v_mfma_f32_16x16x32_bf16 v[128:131], v[146:149], v[170:173], 0
	s_waitcnt lgkmcnt(5)
	v_mfma_f32_16x16x32_bf16 v[112:115], v[138:141], v[178:181], 0
	v_mfma_f32_16x16x32_bf16 v[108:111], v[146:149], v[178:181], 0
	s_waitcnt lgkmcnt(3)
	v_mfma_f32_16x16x32_bf16 v[96:99], v[138:141], v[186:189], 0
	v_mfma_f32_16x16x32_bf16 v[92:95], v[146:149], v[186:189], 0
	s_waitcnt lgkmcnt(1)
	v_mfma_f32_16x16x32_bf16 v[80:83], v[138:141], v[194:197], 0
	v_mfma_f32_16x16x32_bf16 v[76:79], v[146:149], v[194:197], 0
	v_mfma_f32_16x16x32_bf16 v[124:127], v[142:145], v[174:177], v[124:127]
	v_mfma_f32_16x16x32_bf16 v[128:131], v[150:153], v[174:177], v[128:131]
	v_mfma_f32_16x16x32_bf16 v[112:115], v[142:145], v[182:185], v[112:115]
	v_mfma_f32_16x16x32_bf16 v[108:111], v[150:153], v[182:185], v[108:111]
	v_mfma_f32_16x16x32_bf16 v[96:99], v[142:145], v[190:193], v[96:99]
	v_mfma_f32_16x16x32_bf16 v[92:95], v[150:153], v[190:193], v[92:95]
	s_waitcnt lgkmcnt(0)
	v_mfma_f32_16x16x32_bf16 v[80:83], v[142:145], v[202:205], v[80:83]
	v_mfma_f32_16x16x32_bf16 v[76:79], v[150:153], v[202:205], v[76:79]
	s_setprio 0
	s_setprio 1
	v_mfma_f32_16x16x32_bf16 v[120:123], v[154:157], v[170:173], 0
	v_mfma_f32_16x16x32_bf16 v[116:119], v[162:165], v[170:173], 0
	v_mfma_f32_16x16x32_bf16 v[104:107], v[154:157], v[178:181], 0
	v_mfma_f32_16x16x32_bf16 v[100:103], v[162:165], v[178:181], 0
	v_mfma_f32_16x16x32_bf16 v[88:91], v[154:157], v[186:189], 0
	v_mfma_f32_16x16x32_bf16 v[84:87], v[162:165], v[186:189], 0
	v_mfma_f32_16x16x32_bf16 v[72:75], v[154:157], v[194:197], 0
	v_mfma_f32_16x16x32_bf16 v[68:71], v[162:165], v[194:197], 0
	v_mfma_f32_16x16x32_bf16 v[120:123], v[158:161], v[174:177], v[120:123]
	v_mfma_f32_16x16x32_bf16 v[116:119], v[166:169], v[174:177], v[116:119]
	v_mfma_f32_16x16x32_bf16 v[104:107], v[158:161], v[182:185], v[104:107]
	v_mfma_f32_16x16x32_bf16 v[100:103], v[166:169], v[182:185], v[100:103]
	v_mfma_f32_16x16x32_bf16 v[88:91], v[158:161], v[190:193], v[88:91]
	v_mfma_f32_16x16x32_bf16 v[84:87], v[166:169], v[190:193], v[84:87]
	v_mfma_f32_16x16x32_bf16 v[72:75], v[158:161], v[202:205], v[72:75]
	v_mfma_f32_16x16x32_bf16 v[68:71], v[166:169], v[202:205], v[68:71]
	s_setprio 0
	s_barrier
	ds_read_b128 v[170:173], v137 offset:16384
	ds_read_b128 v[174:177], v137 offset:17408
	ds_read_b128 v[178:181], v137 offset:18432
	ds_read_b128 v[182:185], v137 offset:19456
	ds_read_b128 v[186:189], v137 offset:20480
	ds_read_b128 v[190:193], v137 offset:21504
	ds_read_b128 v[194:197], v137 offset:22528
	ds_read_b128 v[202:205], v137 offset:23552
	s_mov_b32 m0, s23
	s_nop 0
	global_load_lds_dwordx4 v2, s[38:39]
	s_mov_b32 m0, s42
	s_nop 0
	global_load_lds_dwordx4 v133, s[38:39]
	s_add_u32 s72, s38, 0x80000
	s_addc_u32 s73, s39, 0
	s_mov_b32 m0, s43
	s_nop 0
	global_load_lds_dwordx4 v2, s[72:73]
	s_mov_b32 m0, s48
	s_nop 0
	global_load_lds_dwordx4 v133, s[72:73]
	s_mov_b32 m0, s35
	s_nop 0
	global_load_lds_dwordx4 v1, s[40:41]
	s_mov_b32 m0, s49
	s_nop 0
	global_load_lds_dwordx4 v132, s[40:41]
	s_waitcnt vmcnt(8)
	s_waitcnt lgkmcnt(0)
	s_barrier
	s_setprio 1
	s_waitcnt lgkmcnt(7)
	v_mfma_f32_16x16x32_bf16 v[64:67], v[138:141], v[170:173], 0
	v_mfma_f32_16x16x32_bf16 v[60:63], v[146:149], v[170:173], 0
	s_waitcnt lgkmcnt(5)
	v_mfma_f32_16x16x32_bf16 v[48:51], v[138:141], v[178:181], 0
	v_mfma_f32_16x16x32_bf16 v[44:47], v[146:149], v[178:181], 0
	s_waitcnt lgkmcnt(3)
	v_mfma_f32_16x16x32_bf16 v[32:35], v[138:141], v[186:189], 0
	v_mfma_f32_16x16x32_bf16 v[28:31], v[146:149], v[186:189], 0
	s_waitcnt lgkmcnt(1)
	v_mfma_f32_16x16x32_bf16 v[16:19], v[138:141], v[194:197], 0
	v_mfma_f32_16x16x32_bf16 v[12:15], v[146:149], v[194:197], 0
	v_mfma_f32_16x16x32_bf16 v[64:67], v[142:145], v[174:177], v[64:67]
	v_mfma_f32_16x16x32_bf16 v[60:63], v[150:153], v[174:177], v[60:63]
	v_mfma_f32_16x16x32_bf16 v[48:51], v[142:145], v[182:185], v[48:51]
	v_mfma_f32_16x16x32_bf16 v[44:47], v[150:153], v[182:185], v[44:47]
	v_mfma_f32_16x16x32_bf16 v[32:35], v[142:145], v[190:193], v[32:35]
	v_mfma_f32_16x16x32_bf16 v[28:31], v[150:153], v[190:193], v[28:31]
	s_waitcnt lgkmcnt(0)
	v_mfma_f32_16x16x32_bf16 v[16:19], v[142:145], v[202:205], v[16:19]
	v_mfma_f32_16x16x32_bf16 v[12:15], v[150:153], v[202:205], v[12:15]
	s_setprio 0
	s_setprio 1
	v_mfma_f32_16x16x32_bf16 v[56:59], v[154:157], v[170:173], 0
	v_mfma_f32_16x16x32_bf16 v[52:55], v[162:165], v[170:173], 0
	v_mfma_f32_16x16x32_bf16 v[40:43], v[154:157], v[178:181], 0
	v_mfma_f32_16x16x32_bf16 v[36:39], v[162:165], v[178:181], 0
	v_mfma_f32_16x16x32_bf16 v[24:27], v[154:157], v[186:189], 0
	v_mfma_f32_16x16x32_bf16 v[20:23], v[162:165], v[186:189], 0
	v_mfma_f32_16x16x32_bf16 v[8:11], v[154:157], v[194:197], 0
	v_mfma_f32_16x16x32_bf16 v[4:7], v[162:165], v[194:197], 0
	v_mfma_f32_16x16x32_bf16 v[56:59], v[158:161], v[174:177], v[56:59]
	v_mfma_f32_16x16x32_bf16 v[52:55], v[166:169], v[174:177], v[52:55]
	v_mfma_f32_16x16x32_bf16 v[40:43], v[158:161], v[182:185], v[40:43]
	v_mfma_f32_16x16x32_bf16 v[36:39], v[166:169], v[182:185], v[36:39]
	v_mfma_f32_16x16x32_bf16 v[24:27], v[158:161], v[190:193], v[24:27]
	v_mfma_f32_16x16x32_bf16 v[20:23], v[166:169], v[190:193], v[20:23]
	v_mfma_f32_16x16x32_bf16 v[8:11], v[158:161], v[202:205], v[8:11]
	v_mfma_f32_16x16x32_bf16 v[4:7], v[166:169], v[202:205], v[4:7]
	s_setprio 0
	s_barrier
	v_add_u32_e32 v150, 0x18000, v136
	v_add_u32_e32 v166, 0x1c000, v136
	ds_read_b128 v[138:141], v150
	ds_read_b128 v[142:145], v150 offset:1024
	ds_read_b128 v[146:149], v150 offset:2048
	ds_read_b128 v[150:153], v150 offset:3072
	ds_read_b128 v[154:157], v166
	ds_read_b128 v[158:161], v166 offset:1024
	ds_read_b128 v[162:165], v166 offset:2048
	ds_read_b128 v[166:169], v166 offset:3072
	ds_read_b128 v[170:173], v137 offset:32768
	ds_read_b128 v[174:177], v137 offset:33792
	ds_read_b128 v[178:181], v137 offset:34816
	ds_read_b128 v[182:185], v137 offset:35840
	ds_read_b128 v[186:189], v137 offset:36864
	ds_read_b128 v[190:193], v137 offset:37888
	ds_read_b128 v[194:197], v137 offset:38912
	ds_read_b128 v[202:205], v137 offset:39936
	s_add_u32 s40, s40, 0x200000
	s_addc_u32 s41, s41, 0
	s_mov_b32 m0, s50
	s_nop 0
	global_load_lds_dwordx4 v1, s[40:41]
	s_mov_b32 m0, s51
	s_nop 0
	global_load_lds_dwordx4 v132, s[40:41]
	s_waitcnt vmcnt(8)
	s_waitcnt lgkmcnt(0)
	s_barrier
	s_setprio 1
	s_waitcnt lgkmcnt(7)
	v_mfma_f32_16x16x32_bf16 v[124:127], v[138:141], v[170:173], v[124:127]
	v_mfma_f32_16x16x32_bf16 v[128:131], v[146:149], v[170:173], v[128:131]
	s_waitcnt lgkmcnt(5)
	v_mfma_f32_16x16x32_bf16 v[112:115], v[138:141], v[178:181], v[112:115]
	v_mfma_f32_16x16x32_bf16 v[108:111], v[146:149], v[178:181], v[108:111]
	s_waitcnt lgkmcnt(3)
	v_mfma_f32_16x16x32_bf16 v[96:99], v[138:141], v[186:189], v[96:99]
	v_mfma_f32_16x16x32_bf16 v[92:95], v[146:149], v[186:189], v[92:95]
	s_waitcnt lgkmcnt(1)
	v_mfma_f32_16x16x32_bf16 v[80:83], v[138:141], v[194:197], v[80:83]
	v_mfma_f32_16x16x32_bf16 v[76:79], v[146:149], v[194:197], v[76:79]
	v_mfma_f32_16x16x32_bf16 v[124:127], v[142:145], v[174:177], v[124:127]
	v_mfma_f32_16x16x32_bf16 v[128:131], v[150:153], v[174:177], v[128:131]
	v_mfma_f32_16x16x32_bf16 v[112:115], v[142:145], v[182:185], v[112:115]
	v_mfma_f32_16x16x32_bf16 v[108:111], v[150:153], v[182:185], v[108:111]
	v_mfma_f32_16x16x32_bf16 v[96:99], v[142:145], v[190:193], v[96:99]
	v_mfma_f32_16x16x32_bf16 v[92:95], v[150:153], v[190:193], v[92:95]
	s_waitcnt lgkmcnt(0)
	v_mfma_f32_16x16x32_bf16 v[80:83], v[142:145], v[202:205], v[80:83]
	v_mfma_f32_16x16x32_bf16 v[76:79], v[150:153], v[202:205], v[76:79]
	s_setprio 0
	s_setprio 1
	v_mfma_f32_16x16x32_bf16 v[120:123], v[154:157], v[170:173], v[120:123]
	v_mfma_f32_16x16x32_bf16 v[116:119], v[162:165], v[170:173], v[116:119]
	v_mfma_f32_16x16x32_bf16 v[104:107], v[154:157], v[178:181], v[104:107]
	v_mfma_f32_16x16x32_bf16 v[100:103], v[162:165], v[178:181], v[100:103]
	v_mfma_f32_16x16x32_bf16 v[88:91], v[154:157], v[186:189], v[88:91]
	v_mfma_f32_16x16x32_bf16 v[84:87], v[162:165], v[186:189], v[84:87]
	v_mfma_f32_16x16x32_bf16 v[72:75], v[154:157], v[194:197], v[72:75]
	v_mfma_f32_16x16x32_bf16 v[68:71], v[162:165], v[194:197], v[68:71]
	v_mfma_f32_16x16x32_bf16 v[120:123], v[158:161], v[174:177], v[120:123]
	v_mfma_f32_16x16x32_bf16 v[116:119], v[166:169], v[174:177], v[116:119]
	v_mfma_f32_16x16x32_bf16 v[104:107], v[158:161], v[182:185], v[104:107]
	v_mfma_f32_16x16x32_bf16 v[100:103], v[166:169], v[182:185], v[100:103]
	v_mfma_f32_16x16x32_bf16 v[88:91], v[158:161], v[190:193], v[88:91]
	v_mfma_f32_16x16x32_bf16 v[84:87], v[166:169], v[190:193], v[84:87]
	v_mfma_f32_16x16x32_bf16 v[72:75], v[158:161], v[202:205], v[72:75]
	v_mfma_f32_16x16x32_bf16 v[68:71], v[166:169], v[202:205], v[68:71]
	s_setprio 0
	s_barrier
	ds_read_b128 v[170:173], v137 offset:49152
	ds_read_b128 v[174:177], v137 offset:50176
	ds_read_b128 v[178:181], v137 offset:51200
	ds_read_b128 v[182:185], v137 offset:52224
	ds_read_b128 v[186:189], v137 offset:53248
	ds_read_b128 v[190:193], v137 offset:54272
	ds_read_b128 v[194:197], v137 offset:55296
	ds_read_b128 v[202:205], v137 offset:56320
	s_add_u32 s40, s38, 0x80
	s_addc_u32 s41, s39, 0
	s_mov_b32 m0, s54
	s_nop 0
	global_load_lds_dwordx4 v2, s[40:41]
	s_add_u32 s38, s38, 0x80080
	s_mov_b32 m0, s55
	s_nop 0
	global_load_lds_dwordx4 v133, s[40:41]
	s_addc_u32 s39, s39, 0
	s_mov_b32 m0, s58
	s_nop 0
	global_load_lds_dwordx4 v2, s[38:39]
	s_mov_b32 m0, s59
	s_nop 0
	global_load_lds_dwordx4 v133, s[38:39]
	s_mov_b32 m0, s56
	s_nop 0
	global_load_lds_dwordx4 v1, s[30:31]
	s_mov_b32 m0, s57
	s_nop 0
	global_load_lds_dwordx4 v132, s[30:31]
	s_waitcnt vmcnt(8)
	s_waitcnt lgkmcnt(0)
	s_barrier
	s_setprio 1
	s_waitcnt lgkmcnt(7)
	v_mfma_f32_16x16x32_bf16 v[64:67], v[138:141], v[170:173], v[64:67]
	v_mfma_f32_16x16x32_bf16 v[60:63], v[146:149], v[170:173], v[60:63]
	s_add_u32 s67, s67, 0x100
	s_waitcnt lgkmcnt(5)
	v_mfma_f32_16x16x32_bf16 v[48:51], v[138:141], v[178:181], v[48:51]
	s_addc_u32 s68, s68, 0
	v_mfma_f32_16x16x32_bf16 v[44:47], v[146:149], v[178:181], v[44:47]
	s_add_u32 s69, s69, 0x100
	s_waitcnt lgkmcnt(3)
	v_mfma_f32_16x16x32_bf16 v[32:35], v[138:141], v[186:189], v[32:35]
	s_addc_u32 s70, s70, 0
	v_mfma_f32_16x16x32_bf16 v[28:31], v[146:149], v[186:189], v[28:31]
	s_add_u32 s28, s28, 0x100
	s_waitcnt lgkmcnt(1)
	v_mfma_f32_16x16x32_bf16 v[16:19], v[138:141], v[194:197], v[16:19]
	s_addc_u32 s29, s29, 0
	v_mfma_f32_16x16x32_bf16 v[12:15], v[146:149], v[194:197], v[12:15]
	s_mov_b32 s30, s71
	v_mfma_f32_16x16x32_bf16 v[64:67], v[142:145], v[174:177], v[64:67]
	s_cmp_ge_i32 s71, s53
	v_mfma_f32_16x16x32_bf16 v[60:63], v[150:153], v[174:177], v[60:63]
	v_mfma_f32_16x16x32_bf16 v[48:51], v[142:145], v[182:185], v[48:51]
	v_mfma_f32_16x16x32_bf16 v[44:47], v[150:153], v[182:185], v[44:47]
	v_mfma_f32_16x16x32_bf16 v[32:35], v[142:145], v[190:193], v[32:35]
	v_mfma_f32_16x16x32_bf16 v[28:31], v[150:153], v[190:193], v[28:31]
	s_waitcnt lgkmcnt(0)
	v_mfma_f32_16x16x32_bf16 v[16:19], v[142:145], v[202:205], v[16:19]
	v_mfma_f32_16x16x32_bf16 v[12:15], v[150:153], v[202:205], v[12:15]
	s_setprio 0
	s_setprio 1
	v_mfma_f32_16x16x32_bf16 v[56:59], v[154:157], v[170:173], v[56:59]
	v_mfma_f32_16x16x32_bf16 v[52:55], v[162:165], v[170:173], v[52:55]
	v_mfma_f32_16x16x32_bf16 v[40:43], v[154:157], v[178:181], v[40:43]
	v_mfma_f32_16x16x32_bf16 v[36:39], v[162:165], v[178:181], v[36:39]
	v_mfma_f32_16x16x32_bf16 v[24:27], v[154:157], v[186:189], v[24:27]
	v_mfma_f32_16x16x32_bf16 v[20:23], v[162:165], v[186:189], v[20:23]
	v_mfma_f32_16x16x32_bf16 v[8:11], v[154:157], v[194:197], v[8:11]
	v_mfma_f32_16x16x32_bf16 v[4:7], v[162:165], v[194:197], v[4:7]
	v_mfma_f32_16x16x32_bf16 v[56:59], v[158:161], v[174:177], v[56:59]
	v_mfma_f32_16x16x32_bf16 v[52:55], v[166:169], v[174:177], v[52:55]
	v_mfma_f32_16x16x32_bf16 v[40:43], v[158:161], v[182:185], v[40:43]
	v_mfma_f32_16x16x32_bf16 v[36:39], v[166:169], v[182:185], v[36:39]
	v_mfma_f32_16x16x32_bf16 v[24:27], v[158:161], v[190:193], v[24:27]
	v_mfma_f32_16x16x32_bf16 v[20:23], v[166:169], v[190:193], v[20:23]
	v_mfma_f32_16x16x32_bf16 v[8:11], v[158:161], v[202:205], v[8:11]
	v_mfma_f32_16x16x32_bf16 v[4:7], v[166:169], v[202:205], v[4:7]
	s_setprio 0
	s_barrier
	s_cbranch_scc0 .LBB0_1309
	s_branch .LBB0_1310
.LBB0_1309:
	v_add_u32_e32 v150, 0x10000, v136
	v_add_u32_e32 v166, 0x14000, v136
	ds_read_b128 v[138:141], v150
	ds_read_b128 v[142:145], v150 offset:1024
	ds_read_b128 v[146:149], v150 offset:2048
	ds_read_b128 v[150:153], v150 offset:3072
	ds_read_b128 v[154:157], v166
	ds_read_b128 v[158:161], v166 offset:1024
	ds_read_b128 v[162:165], v166 offset:2048
	ds_read_b128 v[166:169], v166 offset:3072
	s_add_i32 s71, s30, 2
	s_cmp_eq_u32 s60, s30
	s_cselect_b32 s40, s21, s67
	s_cselect_b32 s41, s3, s68
	s_cselect_b32 s38, s66, s69
	s_cselect_b32 s39, s65, s70
	s_add_u32 s30, s40, 0x80
	s_addc_u32 s31, s41, 0
	ds_read_b128 v[170:173], v137
	ds_read_b128 v[174:177], v137 offset:1024
	ds_read_b128 v[178:181], v137 offset:2048
	ds_read_b128 v[182:185], v137 offset:3072
	ds_read_b128 v[186:189], v137 offset:4096
	ds_read_b128 v[190:193], v137 offset:5120
	ds_read_b128 v[194:197], v137 offset:6144
	ds_read_b128 v[202:205], v137 offset:7168
	s_mov_b32 m0, s61
	s_nop 0
	global_load_lds_dwordx4 v1, s[28:29]
	s_mov_b32 m0, s62
	s_nop 0
	global_load_lds_dwordx4 v132, s[28:29]
	s_waitcnt vmcnt(8)
	s_waitcnt lgkmcnt(0)
	s_barrier
	s_setprio 1
	s_waitcnt lgkmcnt(7)
	v_mfma_f32_16x16x32_bf16 v[124:127], v[138:141], v[170:173], v[124:127]
	v_mfma_f32_16x16x32_bf16 v[128:131], v[146:149], v[170:173], v[128:131]
	s_waitcnt lgkmcnt(5)
	v_mfma_f32_16x16x32_bf16 v[112:115], v[138:141], v[178:181], v[112:115]
	v_mfma_f32_16x16x32_bf16 v[108:111], v[146:149], v[178:181], v[108:111]
	s_waitcnt lgkmcnt(3)
	v_mfma_f32_16x16x32_bf16 v[96:99], v[138:141], v[186:189], v[96:99]
	v_mfma_f32_16x16x32_bf16 v[92:95], v[146:149], v[186:189], v[92:95]
	s_waitcnt lgkmcnt(1)
	v_mfma_f32_16x16x32_bf16 v[80:83], v[138:141], v[194:197], v[80:83]
	v_mfma_f32_16x16x32_bf16 v[76:79], v[146:149], v[194:197], v[76:79]
	v_mfma_f32_16x16x32_bf16 v[124:127], v[142:145], v[174:177], v[124:127]
	v_mfma_f32_16x16x32_bf16 v[128:131], v[150:153], v[174:177], v[128:131]
	v_mfma_f32_16x16x32_bf16 v[112:115], v[142:145], v[182:185], v[112:115]
	v_mfma_f32_16x16x32_bf16 v[108:111], v[150:153], v[182:185], v[108:111]
	v_mfma_f32_16x16x32_bf16 v[96:99], v[142:145], v[190:193], v[96:99]
	v_mfma_f32_16x16x32_bf16 v[92:95], v[150:153], v[190:193], v[92:95]
	s_waitcnt lgkmcnt(0)
	v_mfma_f32_16x16x32_bf16 v[80:83], v[142:145], v[202:205], v[80:83]
	v_mfma_f32_16x16x32_bf16 v[76:79], v[150:153], v[202:205], v[76:79]
	s_setprio 0
	s_setprio 1
	v_mfma_f32_16x16x32_bf16 v[120:123], v[154:157], v[170:173], v[120:123]
	v_mfma_f32_16x16x32_bf16 v[116:119], v[162:165], v[170:173], v[116:119]
	v_mfma_f32_16x16x32_bf16 v[104:107], v[154:157], v[178:181], v[104:107]
	v_mfma_f32_16x16x32_bf16 v[100:103], v[162:165], v[178:181], v[100:103]
	v_mfma_f32_16x16x32_bf16 v[88:91], v[154:157], v[186:189], v[88:91]
	v_mfma_f32_16x16x32_bf16 v[84:87], v[162:165], v[186:189], v[84:87]
	v_mfma_f32_16x16x32_bf16 v[72:75], v[154:157], v[194:197], v[72:75]
	v_mfma_f32_16x16x32_bf16 v[68:71], v[162:165], v[194:197], v[68:71]
	v_mfma_f32_16x16x32_bf16 v[120:123], v[158:161], v[174:177], v[120:123]
	v_mfma_f32_16x16x32_bf16 v[116:119], v[166:169], v[174:177], v[116:119]
	v_mfma_f32_16x16x32_bf16 v[104:107], v[158:161], v[182:185], v[104:107]
	v_mfma_f32_16x16x32_bf16 v[100:103], v[166:169], v[182:185], v[100:103]
	v_mfma_f32_16x16x32_bf16 v[88:91], v[158:161], v[190:193], v[88:91]
	v_mfma_f32_16x16x32_bf16 v[84:87], v[166:169], v[190:193], v[84:87]
	v_mfma_f32_16x16x32_bf16 v[72:75], v[158:161], v[202:205], v[72:75]
	v_mfma_f32_16x16x32_bf16 v[68:71], v[166:169], v[202:205], v[68:71]
	s_setprio 0
	s_barrier
	ds_read_b128 v[170:173], v137 offset:16384
	ds_read_b128 v[174:177], v137 offset:17408
	ds_read_b128 v[178:181], v137 offset:18432
	ds_read_b128 v[182:185], v137 offset:19456
	ds_read_b128 v[186:189], v137 offset:20480
	ds_read_b128 v[190:193], v137 offset:21504
	ds_read_b128 v[194:197], v137 offset:22528
	ds_read_b128 v[202:205], v137 offset:23552
	s_mov_b32 m0, s23
	s_nop 0
	global_load_lds_dwordx4 v2, s[38:39]
	s_mov_b32 m0, s42
	s_nop 0
	global_load_lds_dwordx4 v133, s[38:39]
	s_add_u32 s72, s38, 0x80000
	s_addc_u32 s73, s39, 0
	s_mov_b32 m0, s43
	s_nop 0
	global_load_lds_dwordx4 v2, s[72:73]
	s_mov_b32 m0, s48
	s_nop 0
	global_load_lds_dwordx4 v133, s[72:73]
	s_mov_b32 m0, s35
	s_nop 0
	global_load_lds_dwordx4 v1, s[40:41]
	s_mov_b32 m0, s49
	s_nop 0
	global_load_lds_dwordx4 v132, s[40:41]
	s_waitcnt vmcnt(8)
	s_waitcnt lgkmcnt(0)
	s_barrier
	s_setprio 1
	s_waitcnt lgkmcnt(7)
	v_mfma_f32_16x16x32_bf16 v[64:67], v[138:141], v[170:173], v[64:67]
	v_mfma_f32_16x16x32_bf16 v[60:63], v[146:149], v[170:173], v[60:63]
	s_waitcnt lgkmcnt(5)
	v_mfma_f32_16x16x32_bf16 v[48:51], v[138:141], v[178:181], v[48:51]
	v_mfma_f32_16x16x32_bf16 v[44:47], v[146:149], v[178:181], v[44:47]
	s_waitcnt lgkmcnt(3)
	v_mfma_f32_16x16x32_bf16 v[32:35], v[138:141], v[186:189], v[32:35]
	v_mfma_f32_16x16x32_bf16 v[28:31], v[146:149], v[186:189], v[28:31]
	s_waitcnt lgkmcnt(1)
	v_mfma_f32_16x16x32_bf16 v[16:19], v[138:141], v[194:197], v[16:19]
	v_mfma_f32_16x16x32_bf16 v[12:15], v[146:149], v[194:197], v[12:15]
	v_mfma_f32_16x16x32_bf16 v[64:67], v[142:145], v[174:177], v[64:67]
	v_mfma_f32_16x16x32_bf16 v[60:63], v[150:153], v[174:177], v[60:63]
	v_mfma_f32_16x16x32_bf16 v[48:51], v[142:145], v[182:185], v[48:51]
	v_mfma_f32_16x16x32_bf16 v[44:47], v[150:153], v[182:185], v[44:47]
	v_mfma_f32_16x16x32_bf16 v[32:35], v[142:145], v[190:193], v[32:35]
	v_mfma_f32_16x16x32_bf16 v[28:31], v[150:153], v[190:193], v[28:31]
	s_waitcnt lgkmcnt(0)
	v_mfma_f32_16x16x32_bf16 v[16:19], v[142:145], v[202:205], v[16:19]
	v_mfma_f32_16x16x32_bf16 v[12:15], v[150:153], v[202:205], v[12:15]
	s_setprio 0
	s_setprio 1
	v_mfma_f32_16x16x32_bf16 v[56:59], v[154:157], v[170:173], v[56:59]
	v_mfma_f32_16x16x32_bf16 v[52:55], v[162:165], v[170:173], v[52:55]
	v_mfma_f32_16x16x32_bf16 v[40:43], v[154:157], v[178:181], v[40:43]
	v_mfma_f32_16x16x32_bf16 v[36:39], v[162:165], v[178:181], v[36:39]
	v_mfma_f32_16x16x32_bf16 v[24:27], v[154:157], v[186:189], v[24:27]
	v_mfma_f32_16x16x32_bf16 v[20:23], v[162:165], v[186:189], v[20:23]
	v_mfma_f32_16x16x32_bf16 v[8:11], v[154:157], v[194:197], v[8:11]
	v_mfma_f32_16x16x32_bf16 v[4:7], v[162:165], v[194:197], v[4:7]
	v_mfma_f32_16x16x32_bf16 v[56:59], v[158:161], v[174:177], v[56:59]
	v_mfma_f32_16x16x32_bf16 v[52:55], v[166:169], v[174:177], v[52:55]
	v_mfma_f32_16x16x32_bf16 v[40:43], v[158:161], v[182:185], v[40:43]
	v_mfma_f32_16x16x32_bf16 v[36:39], v[166:169], v[182:185], v[36:39]
	v_mfma_f32_16x16x32_bf16 v[24:27], v[158:161], v[190:193], v[24:27]
	v_mfma_f32_16x16x32_bf16 v[20:23], v[166:169], v[190:193], v[20:23]
	v_mfma_f32_16x16x32_bf16 v[8:11], v[158:161], v[202:205], v[8:11]
	v_mfma_f32_16x16x32_bf16 v[4:7], v[166:169], v[202:205], v[4:7]
	s_setprio 0
	s_barrier
	v_add_u32_e32 v150, 0x18000, v136
	v_add_u32_e32 v166, 0x1c000, v136
	ds_read_b128 v[138:141], v150
	ds_read_b128 v[142:145], v150 offset:1024
	ds_read_b128 v[146:149], v150 offset:2048
	ds_read_b128 v[150:153], v150 offset:3072
	ds_read_b128 v[154:157], v166
	ds_read_b128 v[158:161], v166 offset:1024
	ds_read_b128 v[162:165], v166 offset:2048
	ds_read_b128 v[166:169], v166 offset:3072
	ds_read_b128 v[170:173], v137 offset:32768
	ds_read_b128 v[174:177], v137 offset:33792
	ds_read_b128 v[178:181], v137 offset:34816
	ds_read_b128 v[182:185], v137 offset:35840
	ds_read_b128 v[186:189], v137 offset:36864
	ds_read_b128 v[190:193], v137 offset:37888
	ds_read_b128 v[194:197], v137 offset:38912
	ds_read_b128 v[202:205], v137 offset:39936
	s_add_u32 s40, s40, 0x200000
	s_addc_u32 s41, s41, 0
	s_mov_b32 m0, s50
	s_nop 0
	global_load_lds_dwordx4 v1, s[40:41]
	s_mov_b32 m0, s51
	s_nop 0
	global_load_lds_dwordx4 v132, s[40:41]
	s_waitcnt vmcnt(8)
	s_waitcnt lgkmcnt(0)
	s_barrier
	s_setprio 1
	s_waitcnt lgkmcnt(7)
	v_mfma_f32_16x16x32_bf16 v[124:127], v[138:141], v[170:173], v[124:127]
	v_mfma_f32_16x16x32_bf16 v[128:131], v[146:149], v[170:173], v[128:131]
	s_waitcnt lgkmcnt(5)
	v_mfma_f32_16x16x32_bf16 v[112:115], v[138:141], v[178:181], v[112:115]
	v_mfma_f32_16x16x32_bf16 v[108:111], v[146:149], v[178:181], v[108:111]
	s_waitcnt lgkmcnt(3)
	v_mfma_f32_16x16x32_bf16 v[96:99], v[138:141], v[186:189], v[96:99]
	v_mfma_f32_16x16x32_bf16 v[92:95], v[146:149], v[186:189], v[92:95]
	s_waitcnt lgkmcnt(1)
	v_mfma_f32_16x16x32_bf16 v[80:83], v[138:141], v[194:197], v[80:83]
	v_mfma_f32_16x16x32_bf16 v[76:79], v[146:149], v[194:197], v[76:79]
	v_mfma_f32_16x16x32_bf16 v[124:127], v[142:145], v[174:177], v[124:127]
	v_mfma_f32_16x16x32_bf16 v[128:131], v[150:153], v[174:177], v[128:131]
	v_mfma_f32_16x16x32_bf16 v[112:115], v[142:145], v[182:185], v[112:115]
	v_mfma_f32_16x16x32_bf16 v[108:111], v[150:153], v[182:185], v[108:111]
	v_mfma_f32_16x16x32_bf16 v[96:99], v[142:145], v[190:193], v[96:99]
	v_mfma_f32_16x16x32_bf16 v[92:95], v[150:153], v[190:193], v[92:95]
	s_waitcnt lgkmcnt(0)
	v_mfma_f32_16x16x32_bf16 v[80:83], v[142:145], v[202:205], v[80:83]
	v_mfma_f32_16x16x32_bf16 v[76:79], v[150:153], v[202:205], v[76:79]
	s_setprio 0
	s_setprio 1
	v_mfma_f32_16x16x32_bf16 v[120:123], v[154:157], v[170:173], v[120:123]
	v_mfma_f32_16x16x32_bf16 v[116:119], v[162:165], v[170:173], v[116:119]
	v_mfma_f32_16x16x32_bf16 v[104:107], v[154:157], v[178:181], v[104:107]
	v_mfma_f32_16x16x32_bf16 v[100:103], v[162:165], v[178:181], v[100:103]
	v_mfma_f32_16x16x32_bf16 v[88:91], v[154:157], v[186:189], v[88:91]
	v_mfma_f32_16x16x32_bf16 v[84:87], v[162:165], v[186:189], v[84:87]
	v_mfma_f32_16x16x32_bf16 v[72:75], v[154:157], v[194:197], v[72:75]
	v_mfma_f32_16x16x32_bf16 v[68:71], v[162:165], v[194:197], v[68:71]
	v_mfma_f32_16x16x32_bf16 v[120:123], v[158:161], v[174:177], v[120:123]
	v_mfma_f32_16x16x32_bf16 v[116:119], v[166:169], v[174:177], v[116:119]
	v_mfma_f32_16x16x32_bf16 v[104:107], v[158:161], v[182:185], v[104:107]
	v_mfma_f32_16x16x32_bf16 v[100:103], v[166:169], v[182:185], v[100:103]
	v_mfma_f32_16x16x32_bf16 v[88:91], v[158:161], v[190:193], v[88:91]
	v_mfma_f32_16x16x32_bf16 v[84:87], v[166:169], v[190:193], v[84:87]
	v_mfma_f32_16x16x32_bf16 v[72:75], v[158:161], v[202:205], v[72:75]
	v_mfma_f32_16x16x32_bf16 v[68:71], v[166:169], v[202:205], v[68:71]
	s_setprio 0
	s_barrier
	ds_read_b128 v[170:173], v137 offset:49152
	ds_read_b128 v[174:177], v137 offset:50176
	ds_read_b128 v[178:181], v137 offset:51200
	ds_read_b128 v[182:185], v137 offset:52224
	ds_read_b128 v[186:189], v137 offset:53248
	ds_read_b128 v[190:193], v137 offset:54272
	ds_read_b128 v[194:197], v137 offset:55296
	ds_read_b128 v[202:205], v137 offset:56320
	s_add_u32 s40, s38, 0x80
	s_addc_u32 s41, s39, 0
	s_mov_b32 m0, s54
	s_nop 0
	global_load_lds_dwordx4 v2, s[40:41]
	s_add_u32 s38, s38, 0x80080
	s_mov_b32 m0, s55
	s_nop 0
	global_load_lds_dwordx4 v133, s[40:41]
	s_addc_u32 s39, s39, 0
	s_mov_b32 m0, s58
	s_nop 0
	global_load_lds_dwordx4 v2, s[38:39]
	s_mov_b32 m0, s59
	s_nop 0
	global_load_lds_dwordx4 v133, s[38:39]
	s_mov_b32 m0, s56
	s_nop 0
	global_load_lds_dwordx4 v1, s[30:31]
	s_mov_b32 m0, s57
	s_nop 0
	global_load_lds_dwordx4 v132, s[30:31]
	s_waitcnt vmcnt(8)
	s_waitcnt lgkmcnt(0)
	s_barrier
	s_setprio 1
	s_waitcnt lgkmcnt(7)
	v_mfma_f32_16x16x32_bf16 v[64:67], v[138:141], v[170:173], v[64:67]
	v_mfma_f32_16x16x32_bf16 v[60:63], v[146:149], v[170:173], v[60:63]
	s_add_u32 s67, s67, 0x100
	s_waitcnt lgkmcnt(5)
	v_mfma_f32_16x16x32_bf16 v[48:51], v[138:141], v[178:181], v[48:51]
	s_addc_u32 s68, s68, 0
	v_mfma_f32_16x16x32_bf16 v[44:47], v[146:149], v[178:181], v[44:47]
	s_add_u32 s69, s69, 0x100
	s_waitcnt lgkmcnt(3)
	v_mfma_f32_16x16x32_bf16 v[32:35], v[138:141], v[186:189], v[32:35]
	s_addc_u32 s70, s70, 0
	v_mfma_f32_16x16x32_bf16 v[28:31], v[146:149], v[186:189], v[28:31]
	s_add_u32 s28, s28, 0x100
	s_waitcnt lgkmcnt(1)
	v_mfma_f32_16x16x32_bf16 v[16:19], v[138:141], v[194:197], v[16:19]
	s_addc_u32 s29, s29, 0
	v_mfma_f32_16x16x32_bf16 v[12:15], v[146:149], v[194:197], v[12:15]
	s_mov_b32 s30, s71
	v_mfma_f32_16x16x32_bf16 v[64:67], v[142:145], v[174:177], v[64:67]
	s_cmp_ge_i32 s71, s53
	v_mfma_f32_16x16x32_bf16 v[60:63], v[150:153], v[174:177], v[60:63]
	v_mfma_f32_16x16x32_bf16 v[48:51], v[142:145], v[182:185], v[48:51]
	v_mfma_f32_16x16x32_bf16 v[44:47], v[150:153], v[182:185], v[44:47]
	v_mfma_f32_16x16x32_bf16 v[32:35], v[142:145], v[190:193], v[32:35]
	v_mfma_f32_16x16x32_bf16 v[28:31], v[150:153], v[190:193], v[28:31]
	s_waitcnt lgkmcnt(0)
	v_mfma_f32_16x16x32_bf16 v[16:19], v[142:145], v[202:205], v[16:19]
	v_mfma_f32_16x16x32_bf16 v[12:15], v[150:153], v[202:205], v[12:15]
	s_setprio 0
	s_setprio 1
	v_mfma_f32_16x16x32_bf16 v[56:59], v[154:157], v[170:173], v[56:59]
	v_mfma_f32_16x16x32_bf16 v[52:55], v[162:165], v[170:173], v[52:55]
	v_mfma_f32_16x16x32_bf16 v[40:43], v[154:157], v[178:181], v[40:43]
	v_mfma_f32_16x16x32_bf16 v[36:39], v[162:165], v[178:181], v[36:39]
	v_mfma_f32_16x16x32_bf16 v[24:27], v[154:157], v[186:189], v[24:27]
	v_mfma_f32_16x16x32_bf16 v[20:23], v[162:165], v[186:189], v[20:23]
	v_mfma_f32_16x16x32_bf16 v[8:11], v[154:157], v[194:197], v[8:11]
	v_mfma_f32_16x16x32_bf16 v[4:7], v[162:165], v[194:197], v[4:7]
	v_mfma_f32_16x16x32_bf16 v[56:59], v[158:161], v[174:177], v[56:59]
	v_mfma_f32_16x16x32_bf16 v[52:55], v[166:169], v[174:177], v[52:55]
	v_mfma_f32_16x16x32_bf16 v[40:43], v[158:161], v[182:185], v[40:43]
	v_mfma_f32_16x16x32_bf16 v[36:39], v[166:169], v[182:185], v[36:39]
	v_mfma_f32_16x16x32_bf16 v[24:27], v[158:161], v[190:193], v[24:27]
	v_mfma_f32_16x16x32_bf16 v[20:23], v[166:169], v[190:193], v[20:23]
	v_mfma_f32_16x16x32_bf16 v[8:11], v[158:161], v[202:205], v[8:11]
	v_mfma_f32_16x16x32_bf16 v[4:7], v[166:169], v[202:205], v[4:7]
	s_setprio 0
	s_barrier
	s_cbranch_scc0 .LBB0_1309
